# adds: P3 epilogue reuses rstd from mid-K, attention O stores as global_store, lane^1 exchanges via DPP instead of ds_swizzle
# speedup vs baseline: 1.0202x; 1.0062x over previous
; #define GAS __attribute__((address_space(1)))
; __device__ __forceinline__ unsigned pk2(float lo, float hi) { return f2bf(lo) | (f2bf(hi) << 16); }
; __device__ __forceinline__ float wave_sum(float v) { v += shx<1>(v); v += shx<2>(v); v += shx<4>(v); v += shx<8>(v); v += shx<16>(v); return sum32(v); }
; __device__ __forceinline__ void rms_row_to_bf16(const float* xrow, const float* g, bf16* orow, int lane) {
;     const GAS f32x4* xr = (const GAS f32x4*)xrow + lane; const GAS f32x4* gr = (const GAS f32x4*)g + lane;
;     f32x4 v[8]; float s = 0.f;
; #pragma unroll
;     for (int j = 0; j < 8; ++j) { v[j] = __builtin_nontemporal_load(xr + 64 * j); s += (v[j].x * v[j].x + v[j].y * v[j].y) + (v[j].z * v[j].z + v[j].w * v[j].w); }
;     const float rstd = 1.0f / sqrtf(wave_sum(s) * (1.f / DM) + EPS);
;     GAS unsigned long long* o8 = (GAS unsigned long long*)orow + lane;
; #pragma unroll
;     for (int j = 0; j < 8; ++j) { const f32x4 gg = gr[64 * j]; o8[64 * j] = (unsigned long long)pk2(v[j].x * rstd * gg.x, v[j].y * rstd * gg.y) | ((unsigned long long)pk2(v[j].z * rstd * gg.z, v[j].w * rstd * gg.w) << 32); }
.LBB0_108:
	s_cmpk_gt_i32 s6, 0x1fff
	s_mov_b64 s[0:1], -1
	s_cbranch_scc0 .LBB0_110
	s_add_i32 s20, s6, 0xffffe000
	s_lshl_b64 s[0:1], s[20:21], 12
	s_add_u32 s22, s81, s0
	s_addc_u32 s23, s88, s1
	s_lshl_b64 s[0:1], s[20:21], 13
	v_lshl_add_u64 v[2:3], v[56:57], 0, s[0:1]
	global_load_dwordx4 v[62:65], v[2:3], off nt
	global_load_dwordx4 v[66:69], v[2:3], off offset:1024 nt
	global_load_dwordx4 v[22:25], v[2:3], off offset:2048 nt
	global_load_dwordx4 v[18:21], v[2:3], off offset:3072 nt
	v_add_co_u32_e32 v2, vcc, s5, v2
	s_waitcnt vmcnt(3)
	v_mul_f32_e32 v26, v63, v63
	v_addc_co_u32_e32 v3, vcc, 0, v3, vcc
	global_load_dwordx4 v[14:17], v[2:3], off nt
	global_load_dwordx4 v[10:13], v[2:3], off offset:1024 nt
	global_load_dwordx4 v[6:9], v[2:3], off offset:2048 nt
	s_nop 0
	global_load_dwordx4 v[2:5], v[2:3], off offset:3072 nt
	s_nop 0
	global_load_dwordx4 v[70:73], v[30:31], off
	v_mul_f32_e32 v27, v65, v65
	s_waitcnt vmcnt(7)
	v_mul_f32_e32 v28, v67, v67
	v_mul_f32_e32 v29, v69, v69
	s_waitcnt vmcnt(6)
	v_mul_f32_e32 v40, v23, v23
	v_mul_f32_e32 v41, v25, v25
	v_fmac_f32_e32 v26, v62, v62
	v_fmac_f32_e32 v27, v64, v64
	v_fmac_f32_e32 v28, v66, v66
	v_fmac_f32_e32 v29, v68, v68
	s_waitcnt vmcnt(5)
	v_mul_f32_e32 v74, v19, v19
	v_mul_f32_e32 v75, v21, v21
	v_fmac_f32_e32 v40, v22, v22
	v_fmac_f32_e32 v41, v24, v24
	v_add_f32_e32 v26, v26, v27
	v_add_f32_e32 v27, v28, v29
	v_fmac_f32_e32 v74, v18, v18
	v_fmac_f32_e32 v75, v20, v20
	v_add_f32_e32 v28, v40, v41
	v_add_f32_e32 v26, v26, v27
	v_add_f32_e32 v29, v74, v75
	v_add_f32_e32 v26, v26, v28
	v_add_f32_e32 v26, v26, v29
	s_waitcnt vmcnt(4)
	v_mul_f32_e32 v76, v15, v15
	v_mul_f32_e32 v77, v17, v17
	s_waitcnt vmcnt(3)
	v_mul_f32_e32 v78, v11, v11
	v_mul_f32_e32 v79, v13, v13
	v_fmac_f32_e32 v76, v14, v14
	v_fmac_f32_e32 v77, v16, v16
	s_waitcnt vmcnt(2)
	v_mul_f32_e32 v80, v7, v7
	v_mul_f32_e32 v81, v9, v9
	v_fmac_f32_e32 v78, v10, v10
	v_fmac_f32_e32 v79, v12, v12
	v_add_f32_e32 v27, v76, v77
	s_waitcnt vmcnt(1)
	v_mul_f32_e32 v82, v3, v3
	v_mul_f32_e32 v83, v5, v5
	v_fmac_f32_e32 v80, v6, v6
	v_fmac_f32_e32 v81, v8, v8
	v_add_f32_e32 v40, v78, v79
	v_add_f32_e32 v26, v26, v27
	v_fmac_f32_e32 v82, v2, v2
	v_fmac_f32_e32 v83, v4, v4
	v_add_f32_e32 v41, v80, v81
	v_add_f32_e32 v26, v26, v40
	v_add_f32_e32 v74, v82, v83
	v_add_f32_e32 v26, v26, v41
	v_add_f32_e32 v26, v26, v74
	s_nop 1
	v_mov_b32_dpp v27, v26 quad_perm:[1,0,3,2] row_mask:0xf bank_mask:0xf
	s_waitcnt lgkmcnt(0)
	v_add_f32_e32 v26, v26, v27
	ds_swizzle_b32 v27, v26 offset:swizzle(SWAP,2)
	s_waitcnt lgkmcnt(0)
	v_add_f32_e32 v26, v26, v27
	ds_swizzle_b32 v27, v26 offset:swizzle(SWAP,4)
	s_waitcnt lgkmcnt(0)
	v_add_f32_e32 v26, v26, v27
	ds_swizzle_b32 v27, v26 offset:swizzle(SWAP,8)
	s_waitcnt lgkmcnt(0)
	v_add_f32_e32 v26, v26, v27
	ds_swizzle_b32 v27, v26 offset:swizzle(SWAP,16)
	s_waitcnt lgkmcnt(0)
	v_add_f32_e32 v26, v26, v27
	v_mov_b32_e32 v27, v26
	s_nop 1
	v_permlane32_swap_b32_e32 v26, v27
	v_add_f32_e32 v26, v26, v27
	v_fmamk_f32 v26, v26, 0x3a000000, v44
	v_mul_f32_e32 v27, 0x4f800000, v26
	v_cmp_gt_f32_e32 vcc, s7, v26
	s_nop 1
	v_cndmask_b32_e32 v26, v26, v27, vcc
	v_sqrt_f32_e32 v27, v26
	s_nop 0
	v_add_u32_e32 v28, -1, v27
	v_add_u32_e32 v29, 1, v27
	v_fma_f32 v40, -v28, v27, v26
	v_fma_f32 v41, -v29, v27, v26
	v_cmp_ge_f32_e64 s[0:1], 0, v40
	s_nop 1
	v_cndmask_b32_e64 v27, v27, v28, s[0:1]
	v_cmp_lt_f32_e64 s[0:1], 0, v41
	s_nop 1
	v_cndmask_b32_e64 v27, v27, v29, s[0:1]
	v_mul_f32_e32 v28, 0x37800000, v27
	v_cndmask_b32_e32 v27, v27, v28, vcc
	v_cmp_class_f32_e32 vcc, v26, v45
	s_nop 1
	v_cndmask_b32_e32 v26, v27, v26, vcc
	v_div_scale_f32 v27, s[0:1], v26, v26, 1.0
	v_rcp_f32_e32 v28, v27
	v_div_scale_f32 v29, vcc, 1.0, v26, 1.0
	s_mov_b64 s[0:1], 0
	v_fma_f32 v40, -v27, v28, 1.0
	v_fmac_f32_e32 v28, v40, v28
	v_mul_f32_e32 v40, v29, v28
	v_fma_f32 v41, -v27, v40, v29
	v_fmac_f32_e32 v40, v41, v28
	v_fma_f32 v27, -v27, v40, v29
	v_div_fmas_f32 v27, v27, v28, v40
	v_div_fixup_f32 v26, v27, v26, 1.0
	v_mul_f32_e32 v27, v62, v26
	v_mul_f32_e32 v29, v64, v26
	v_mul_f32_e32 v28, v63, v26
	v_mul_f32_e32 v40, v65, v26
	s_waitcnt vmcnt(0)
	v_mul_f32_e32 v27, v70, v27
	v_mul_f32_e32 v29, v72, v29
	v_mul_f32_e32 v28, v71, v28
	v_mul_f32_e32 v40, v73, v40
	v_bfe_u32 v41, v27, 16, 1
	v_bfe_u32 v63, v29, 16, 1
	v_bfe_u32 v62, v28, 16, 1
	v_bfe_u32 v64, v40, 16, 1
	v_add3_u32 v27, v27, v41, s26
	v_add3_u32 v29, v29, v63, s26
	v_add3_u32 v28, v28, v62, s26
	v_add3_u32 v40, v40, v64, s26
	v_lshrrev_b32_e32 v27, 16, v27
	v_lshrrev_b32_e32 v29, 16, v29
	v_and_or_b32 v28, v28, s27, v27
	v_and_or_b32 v29, v40, s27, v29
	global_store_dwordx2 v60, v[28:29], s[22:23]
	global_load_dwordx4 v[62:65], v[30:31], off offset:1024
	v_mul_f32_e32 v27, v66, v26
	v_mul_f32_e32 v29, v68, v26
	v_mul_f32_e32 v28, v67, v26
	v_mul_f32_e32 v40, v69, v26
	v_mul_f32_e32 v22, v22, v26
	v_mul_f32_e32 v24, v24, v26
	v_mul_f32_e32 v23, v23, v26
	v_mul_f32_e32 v25, v25, v26
	v_mul_f32_e32 v18, v18, v26
	v_mul_f32_e32 v20, v20, v26
	v_mul_f32_e32 v19, v19, v26
	v_mul_f32_e32 v21, v21, v26
	v_mul_f32_e32 v14, v14, v26
	v_mul_f32_e32 v16, v16, v26
	v_mul_f32_e32 v15, v15, v26
	v_mul_f32_e32 v17, v17, v26
	v_mul_f32_e32 v10, v10, v26
	v_mul_f32_e32 v12, v12, v26
	v_mul_f32_e32 v11, v11, v26
	v_mul_f32_e32 v13, v13, v26
	v_mul_f32_e32 v6, v6, v26
	v_mul_f32_e32 v8, v8, v26
	v_mul_f32_e32 v7, v7, v26
	v_mul_f32_e32 v9, v9, v26
	s_waitcnt vmcnt(0)
; #define GAS __attribute__((address_space(1)))
; __device__ __forceinline__ unsigned pk2(float lo, float hi) { return f2bf(lo) | (f2bf(hi) << 16); }
; __device__ __forceinline__ float wave_sum(float v) { v += shx<1>(v); v += shx<2>(v); v += shx<4>(v); v += shx<8>(v); v += shx<16>(v); return sum32(v); }
; __device__ __forceinline__ void rms_row_to_bf16(const float* xrow, const float* g, bf16* orow, int lane) {
;     const GAS f32x4* xr = (const GAS f32x4*)xrow + lane; const GAS f32x4* gr = (const GAS f32x4*)g + lane;
;     f32x4 v[8]; float s = 0.f;
; #pragma unroll
;     for (int j = 0; j < 8; ++j) { v[j] = __builtin_nontemporal_load(xr + 64 * j); s += (v[j].x * v[j].x + v[j].y * v[j].y) + (v[j].z * v[j].z + v[j].w * v[j].w); }
;     const float rstd = 1.0f / sqrtf(wave_sum(s) * (1.f / DM) + EPS);
;     GAS unsigned long long* o8 = (GAS unsigned long long*)orow + lane;
; #pragma unroll
;     for (int j = 0; j < 8; ++j) { const f32x4 gg = gr[64 * j]; o8[64 * j] = (unsigned long long)pk2(v[j].x * rstd * gg.x, v[j].y * rstd * gg.y) | ((unsigned long long)pk2(v[j].z * rstd * gg.z, v[j].w * rstd * gg.w) << 32); }
	v_mul_f32_e32 v27, v62, v27
	v_mul_f32_e32 v29, v64, v29
	v_mul_f32_e32 v28, v63, v28
	v_mul_f32_e32 v40, v65, v40
	v_bfe_u32 v41, v27, 16, 1
	v_bfe_u32 v63, v29, 16, 1
	v_bfe_u32 v62, v28, 16, 1
	v_bfe_u32 v64, v40, 16, 1
	v_add3_u32 v27, v27, v41, s26
	v_add3_u32 v29, v29, v63, s26
	v_add3_u32 v28, v28, v62, s26
	v_add3_u32 v40, v40, v64, s26
	v_lshrrev_b32_e32 v27, 16, v27
	v_lshrrev_b32_e32 v29, 16, v29
	v_and_or_b32 v28, v28, s27, v27
	v_and_or_b32 v29, v40, s27, v29
	global_store_dwordx2 v60, v[28:29], s[22:23] offset:512
	global_load_dwordx4 v[62:65], v[30:31], off offset:2048
	s_waitcnt vmcnt(0)
	v_mul_f32_e32 v22, v62, v22
	v_mul_f32_e32 v24, v64, v24
	v_mul_f32_e32 v23, v63, v23
	v_mul_f32_e32 v25, v65, v25
	v_bfe_u32 v27, v22, 16, 1
	v_bfe_u32 v29, v24, 16, 1
	v_bfe_u32 v28, v23, 16, 1
	v_bfe_u32 v40, v25, 16, 1
	v_add3_u32 v22, v22, v27, s26
	v_add3_u32 v24, v24, v29, s26
	v_add3_u32 v23, v23, v28, s26
	v_add3_u32 v25, v25, v40, s26
	v_lshrrev_b32_e32 v22, 16, v22
	v_lshrrev_b32_e32 v24, 16, v24
	v_and_or_b32 v22, v23, s27, v22
	v_and_or_b32 v23, v25, s27, v24
	global_store_dwordx2 v60, v[22:23], s[22:23] offset:1024
	global_load_dwordx4 v[22:25], v[30:31], off offset:3072
	v_pk_mul_f32 v[2:3], v[2:3], v[26:27] op_sel_hi:[1,0]
	v_mul_f32_e32 v27, v4, v26
	s_waitcnt vmcnt(0)
	v_mul_f32_e32 v18, v18, v22
	v_mul_f32_e32 v20, v20, v24
	v_mul_f32_e32 v19, v19, v23
	v_mul_f32_e32 v21, v21, v25
	v_bfe_u32 v22, v18, 16, 1
	v_bfe_u32 v24, v20, 16, 1
	v_bfe_u32 v23, v19, 16, 1
	v_bfe_u32 v25, v21, 16, 1
	v_add3_u32 v18, v18, v22, s26
	v_add3_u32 v20, v20, v24, s26
	v_add3_u32 v19, v19, v23, s26
	v_add3_u32 v21, v21, v25, s26
	v_lshrrev_b32_e32 v18, 16, v18
	v_lshrrev_b32_e32 v20, 16, v20
	v_and_or_b32 v18, v19, s27, v18
	v_and_or_b32 v19, v21, s27, v20
	global_store_dwordx2 v60, v[18:19], s[22:23] offset:1536
	global_load_dwordx4 v[18:21], v[32:33], off
	s_waitcnt vmcnt(0)
	v_mul_f32_e32 v14, v14, v18
	v_mul_f32_e32 v16, v16, v20
	v_mul_f32_e32 v15, v15, v19
	v_mul_f32_e32 v17, v17, v21
	v_bfe_u32 v18, v14, 16, 1
	v_bfe_u32 v20, v16, 16, 1
	v_bfe_u32 v19, v15, 16, 1
	v_bfe_u32 v21, v17, 16, 1
	v_add3_u32 v14, v14, v18, s26
	v_add3_u32 v16, v16, v20, s26
	v_add3_u32 v15, v15, v19, s26
	v_add3_u32 v17, v17, v21, s26
	v_lshrrev_b32_e32 v14, 16, v14
	v_lshrrev_b32_e32 v16, 16, v16
	v_and_or_b32 v14, v15, s27, v14
	v_and_or_b32 v15, v17, s27, v16
	global_store_dwordx2 v60, v[14:15], s[22:23] offset:2048
	global_load_dwordx4 v[14:17], v[34:35], off
	s_waitcnt vmcnt(0)
	v_mul_f32_e32 v10, v10, v14
	v_mul_f32_e32 v12, v12, v16
	v_mul_f32_e32 v11, v11, v15
	v_mul_f32_e32 v13, v13, v17
	v_bfe_u32 v14, v10, 16, 1
	v_bfe_u32 v16, v12, 16, 1
	v_bfe_u32 v15, v11, 16, 1
	v_bfe_u32 v17, v13, 16, 1
	v_add3_u32 v10, v10, v14, s26
	v_add3_u32 v12, v12, v16, s26
	v_add3_u32 v11, v11, v15, s26
	v_add3_u32 v13, v13, v17, s26
	v_lshrrev_b32_e32 v10, 16, v10
	v_lshrrev_b32_e32 v12, 16, v12
	v_and_or_b32 v10, v11, s27, v10
	v_and_or_b32 v11, v13, s27, v12
	global_store_dwordx2 v60, v[10:11], s[22:23] offset:2560
	global_load_dwordx4 v[10:13], v[36:37], off
	s_waitcnt vmcnt(0)
	v_mul_f32_e32 v6, v6, v10
	v_mul_f32_e32 v8, v8, v12
	v_mul_f32_e32 v7, v7, v11
	v_mul_f32_e32 v9, v9, v13
	v_bfe_u32 v10, v6, 16, 1
	v_bfe_u32 v12, v8, 16, 1
	v_bfe_u32 v11, v7, 16, 1
	v_bfe_u32 v13, v9, 16, 1
	v_add3_u32 v6, v6, v10, s26
	v_add3_u32 v8, v8, v12, s26
	v_add3_u32 v7, v7, v11, s26
	v_add3_u32 v9, v9, v13, s26
	v_lshrrev_b32_e32 v6, 16, v6
	v_lshrrev_b32_e32 v8, 16, v8
	v_and_or_b32 v6, v7, s27, v6
	v_and_or_b32 v7, v9, s27, v8
	global_store_dwordx2 v60, v[6:7], s[22:23] offset:3072
	global_load_dwordx4 v[6:9], v[42:43], off
	s_waitcnt vmcnt(0)
	v_pk_mul_f32 v[2:3], v[2:3], v[6:7]
	s_nop 0
	v_and_b32_sdwa v7, v2, v61 dst_sel:DWORD dst_unused:UNUSED_PAD src0_sel:WORD_1 src1_sel:DWORD
	v_and_b32_sdwa v6, v3, v61 dst_sel:DWORD dst_unused:UNUSED_PAD src0_sel:WORD_1 src1_sel:DWORD
	v_add3_u32 v2, v2, v7, s26
	v_pk_mov_b32 v[4:5], v[4:5], v[8:9] op_sel:[1,0]
	v_add3_u32 v3, v3, v6, s26
	v_lshrrev_b32_e32 v2, 16, v2
	v_pk_mul_f32 v[4:5], v[4:5], v[26:27]
	v_and_or_b32 v2, v3, s27, v2
.LBB0_110:
	s_andn2_b64 vcc, exec, s[0:1]
	s_cbranch_vccnz .LBB0_107
	global_load_dwordx4 v[62:65], v[58:59], off offset:-4096 nt
	global_load_dwordx4 v[26:29], v[58:59], off offset:-3072 nt
	global_load_dwordx4 v[22:25], v[58:59], off offset:-2048 nt
	global_load_dwordx4 v[18:21], v[58:59], off offset:-1024 nt
	global_load_dwordx4 v[14:17], v[58:59], off nt
	global_load_dwordx4 v[10:13], v[58:59], off offset:1024 nt
	global_load_dwordx4 v[6:9], v[58:59], off offset:2048 nt
	global_load_dwordx4 v[2:5], v[58:59], off offset:3072 nt
	global_load_dwordx4 v[66:69], v[46:47], off
	s_add_u32 s22, s16, 0x6900000
	s_addc_u32 s23, s17, 0
	s_waitcnt vmcnt(8)
	v_mul_f32_e32 v40, v63, v63
	v_mul_f32_e32 v41, v65, v65
	s_waitcnt vmcnt(7)
	v_mul_f32_e32 v70, v27, v27
	v_mul_f32_e32 v71, v29, v29
	s_waitcnt vmcnt(6)
	v_mul_f32_e32 v72, v23, v23
	v_mul_f32_e32 v73, v25, v25
	v_fmac_f32_e32 v40, v62, v62
	v_fmac_f32_e32 v41, v64, v64
	v_fmac_f32_e32 v70, v26, v26
	v_fmac_f32_e32 v71, v28, v28
	s_waitcnt vmcnt(5)
	v_mul_f32_e32 v74, v19, v19
	v_mul_f32_e32 v75, v21, v21
	v_fmac_f32_e32 v72, v22, v22
	v_fmac_f32_e32 v73, v24, v24
	v_add_f32_e32 v40, v40, v41
	v_add_f32_e32 v41, v70, v71
	s_waitcnt vmcnt(4)
	v_mul_f32_e32 v76, v15, v15
	v_mul_f32_e32 v77, v17, v17
	v_fmac_f32_e32 v74, v18, v18
	v_fmac_f32_e32 v75, v20, v20
	v_add_f32_e32 v70, v72, v73
	v_add_f32_e32 v40, v40, v41
	s_waitcnt vmcnt(3)
	v_mul_f32_e32 v78, v11, v11
	v_mul_f32_e32 v79, v13, v13
	v_fmac_f32_e32 v76, v14, v14
	v_fmac_f32_e32 v77, v16, v16
	v_add_f32_e32 v71, v74, v75
	v_add_f32_e32 v40, v40, v70
	s_waitcnt vmcnt(2)
; #define GAS __attribute__((address_space(1)))
; __device__ __forceinline__ unsigned pk2(float lo, float hi) { return f2bf(lo) | (f2bf(hi) << 16); }
; __device__ __forceinline__ float wave_sum(float v) { v += shx<1>(v); v += shx<2>(v); v += shx<4>(v); v += shx<8>(v); v += shx<16>(v); return sum32(v); }
; __device__ __forceinline__ void rms_row_to_bf16(const float* xrow, const float* g, bf16* orow, int lane) {
;     const GAS f32x4* xr = (const GAS f32x4*)xrow + lane; const GAS f32x4* gr = (const GAS f32x4*)g + lane;
;     f32x4 v[8]; float s = 0.f;
; #pragma unroll
;     for (int j = 0; j < 8; ++j) { v[j] = __builtin_nontemporal_load(xr + 64 * j); s += (v[j].x * v[j].x + v[j].y * v[j].y) + (v[j].z * v[j].z + v[j].w * v[j].w); }
;     const float rstd = 1.0f / sqrtf(wave_sum(s) * (1.f / DM) + EPS);
;     GAS unsigned long long* o8 = (GAS unsigned long long*)orow + lane;
; #pragma unroll
;     for (int j = 0; j < 8; ++j) { const f32x4 gg = gr[64 * j]; o8[64 * j] = (unsigned long long)pk2(v[j].x * rstd * gg.x, v[j].y * rstd * gg.y) | ((unsigned long long)pk2(v[j].z * rstd * gg.z, v[j].w * rstd * gg.w) << 32); }
	v_mul_f32_e32 v80, v7, v7
	v_mul_f32_e32 v81, v9, v9
	v_fmac_f32_e32 v78, v10, v10
	v_fmac_f32_e32 v79, v12, v12
	v_add_f32_e32 v72, v76, v77
	v_add_f32_e32 v40, v40, v71
	s_waitcnt vmcnt(1)
	v_mul_f32_e32 v82, v3, v3
	v_mul_f32_e32 v83, v5, v5
	v_fmac_f32_e32 v80, v6, v6
	v_fmac_f32_e32 v81, v8, v8
	v_add_f32_e32 v73, v78, v79
	v_add_f32_e32 v40, v40, v72
	v_fmac_f32_e32 v82, v2, v2
	v_fmac_f32_e32 v83, v4, v4
	v_add_f32_e32 v74, v80, v81
	v_add_f32_e32 v40, v40, v73
	v_add_f32_e32 v75, v82, v83
	v_add_f32_e32 v40, v40, v74
	v_add_f32_e32 v40, v40, v75
	s_nop 1
	v_mov_b32_dpp v41, v40 quad_perm:[1,0,3,2] row_mask:0xf bank_mask:0xf
	s_waitcnt lgkmcnt(0)
	v_add_f32_e32 v40, v40, v41
	ds_swizzle_b32 v41, v40 offset:swizzle(SWAP,2)
	s_waitcnt lgkmcnt(0)
	v_add_f32_e32 v40, v40, v41
	ds_swizzle_b32 v41, v40 offset:swizzle(SWAP,4)
	s_waitcnt lgkmcnt(0)
	v_add_f32_e32 v40, v40, v41
	ds_swizzle_b32 v41, v40 offset:swizzle(SWAP,8)
	s_waitcnt lgkmcnt(0)
	v_add_f32_e32 v40, v40, v41
	ds_swizzle_b32 v41, v40 offset:swizzle(SWAP,16)
	s_waitcnt lgkmcnt(0)
	v_add_f32_e32 v40, v40, v41
	v_mov_b32_e32 v41, v40
	s_nop 1
	v_permlane32_swap_b32_e32 v40, v41
	v_add_f32_e32 v40, v40, v41
	v_fmamk_f32 v40, v40, 0x3a000000, v44
	v_mul_f32_e32 v41, 0x4f800000, v40
	v_cmp_gt_f32_e32 vcc, s7, v40
	s_nop 1
	v_cndmask_b32_e32 v70, v40, v41, vcc
	v_sqrt_f32_e32 v71, v70
	v_lshl_add_u64 v[40:41], s[16:17], 0, v[38:39]
	v_add_u32_e32 v72, -1, v71
	v_add_u32_e32 v73, 1, v71
	v_fma_f32 v74, -v72, v71, v70
	v_fma_f32 v75, -v73, v71, v70
	v_cmp_ge_f32_e64 s[0:1], 0, v74
	s_nop 1
	v_cndmask_b32_e64 v71, v71, v72, s[0:1]
	v_cmp_lt_f32_e64 s[0:1], 0, v75
	s_nop 1
	v_cndmask_b32_e64 v71, v71, v73, s[0:1]
	v_mul_f32_e32 v72, 0x37800000, v71
	v_cndmask_b32_e32 v71, v71, v72, vcc
	v_cmp_class_f32_e32 vcc, v70, v45
	s_nop 1
	v_cndmask_b32_e32 v72, v71, v70, vcc
	v_div_scale_f32 v73, s[0:1], v72, v72, 1.0
	v_rcp_f32_e32 v74, v73
	v_add_co_u32_e32 v70, vcc, s28, v40
	s_nop 1
	v_addc_co_u32_e32 v71, vcc, 0, v41, vcc
	v_fma_f32 v41, -v73, v74, 1.0
	v_div_scale_f32 v40, vcc, 1.0, v72, 1.0
	v_fmac_f32_e32 v74, v41, v74
	v_mul_f32_e32 v41, v40, v74
	v_fma_f32 v75, -v73, v41, v40
	v_fmac_f32_e32 v41, v75, v74
	v_fma_f32 v40, -v73, v41, v40
	v_div_fmas_f32 v40, v40, v74, v41
	v_div_fixup_f32 v40, v40, v72, 1.0
	v_mul_f32_e32 v41, v62, v40
	v_mul_f32_e32 v62, v63, v40
	v_mul_f32_e32 v63, v64, v40
	v_mul_f32_e32 v64, v65, v40
	s_waitcnt vmcnt(0)
	v_mul_f32_e32 v41, v66, v41
	v_mul_f32_e32 v63, v68, v63
	v_mul_f32_e32 v62, v67, v62
	v_mul_f32_e32 v64, v69, v64
	v_bfe_u32 v65, v41, 16, 1
	v_bfe_u32 v67, v63, 16, 1
	v_bfe_u32 v66, v62, 16, 1
	v_bfe_u32 v68, v64, 16, 1
	v_add3_u32 v41, v41, v65, s26
	v_add3_u32 v63, v63, v67, s26
	v_add3_u32 v62, v62, v66, s26
	v_add3_u32 v64, v64, v68, s26
	v_lshrrev_b32_e32 v41, 16, v41
	v_lshrrev_b32_e32 v63, 16, v63
	v_and_or_b32 v62, v62, s27, v41
	v_and_or_b32 v63, v64, s27, v63
	global_store_dwordx2 v[70:71], v[62:63], off
	global_load_dwordx4 v[62:65], v[46:47], off offset:1024
	v_mul_f32_e32 v26, v26, v40
	v_mul_f32_e32 v28, v28, v40
	v_mul_f32_e32 v27, v27, v40
	v_mul_f32_e32 v29, v29, v40
	v_mul_f32_e32 v22, v22, v40
	v_mul_f32_e32 v24, v24, v40
	v_mul_f32_e32 v23, v23, v40
	v_mul_f32_e32 v25, v25, v40
	v_mul_f32_e32 v18, v18, v40
	v_mul_f32_e32 v20, v20, v40
	v_mul_f32_e32 v19, v19, v40
	v_mul_f32_e32 v21, v21, v40
	v_mul_f32_e32 v14, v14, v40
	v_mul_f32_e32 v16, v16, v40
	v_mul_f32_e32 v15, v15, v40
	v_mul_f32_e32 v17, v17, v40
	v_mul_f32_e32 v10, v10, v40
	v_mul_f32_e32 v12, v12, v40
	v_mul_f32_e32 v11, v11, v40
	v_mul_f32_e32 v13, v13, v40
	v_mul_f32_e32 v6, v6, v40
	v_mul_f32_e32 v8, v8, v40
	v_mul_f32_e32 v7, v7, v40
	v_mul_f32_e32 v9, v9, v40
	s_waitcnt vmcnt(0)
; #define GAS __attribute__((address_space(1)))
; __device__ __forceinline__ unsigned pk2(float lo, float hi) { return f2bf(lo) | (f2bf(hi) << 16); }
; __device__ __forceinline__ float wave_sum(float v) { v += shx<1>(v); v += shx<2>(v); v += shx<4>(v); v += shx<8>(v); v += shx<16>(v); return sum32(v); }
; __device__ __forceinline__ void rms_row_to_bf16(const float* xrow, const float* g, bf16* orow, int lane) {
;     const GAS f32x4* xr = (const GAS f32x4*)xrow + lane; const GAS f32x4* gr = (const GAS f32x4*)g + lane;
;     f32x4 v[8]; float s = 0.f;
; #pragma unroll
;     for (int j = 0; j < 8; ++j) { v[j] = __builtin_nontemporal_load(xr + 64 * j); s += (v[j].x * v[j].x + v[j].y * v[j].y) + (v[j].z * v[j].z + v[j].w * v[j].w); }
;     const float rstd = 1.0f / sqrtf(wave_sum(s) * (1.f / DM) + EPS);
;     GAS unsigned long long* o8 = (GAS unsigned long long*)orow + lane;
; #pragma unroll
;     for (int j = 0; j < 8; ++j) { const f32x4 gg = gr[64 * j]; o8[64 * j] = (unsigned long long)pk2(v[j].x * rstd * gg.x, v[j].y * rstd * gg.y) | ((unsigned long long)pk2(v[j].z * rstd * gg.z, v[j].w * rstd * gg.w) << 32); }
	v_mul_f32_e32 v26, v62, v26
	v_mul_f32_e32 v28, v64, v28
	v_mul_f32_e32 v27, v63, v27
	v_mul_f32_e32 v29, v65, v29
	v_bfe_u32 v41, v26, 16, 1
	v_bfe_u32 v63, v28, 16, 1
	v_bfe_u32 v62, v27, 16, 1
	v_bfe_u32 v64, v29, 16, 1
	v_add3_u32 v26, v26, v41, s26
	v_add3_u32 v28, v28, v63, s26
	v_add3_u32 v27, v27, v62, s26
	v_add3_u32 v29, v29, v64, s26
	v_lshrrev_b32_e32 v26, 16, v26
	v_lshrrev_b32_e32 v28, 16, v28
	v_and_or_b32 v26, v27, s27, v26
	v_and_or_b32 v27, v29, s27, v28
	global_store_dwordx2 v[70:71], v[26:27], off offset:512
	global_load_dwordx4 v[26:29], v[46:47], off offset:2048
	v_pk_mul_f32 v[2:3], v[2:3], v[40:41] op_sel_hi:[1,0]
	v_mul_f32_e32 v41, v4, v40
	s_waitcnt vmcnt(0)
	v_mul_f32_e32 v22, v26, v22
	v_mul_f32_e32 v24, v28, v24
	v_mul_f32_e32 v23, v27, v23
	v_mul_f32_e32 v25, v29, v25
	v_bfe_u32 v26, v22, 16, 1
	v_bfe_u32 v28, v24, 16, 1
	v_bfe_u32 v27, v23, 16, 1
	v_bfe_u32 v29, v25, 16, 1
	v_add3_u32 v22, v22, v26, s26
	v_add3_u32 v24, v24, v28, s26
	v_add3_u32 v23, v23, v27, s26
	v_add3_u32 v25, v25, v29, s26
	v_lshrrev_b32_e32 v22, 16, v22
	v_lshrrev_b32_e32 v24, 16, v24
	v_and_or_b32 v22, v23, s27, v22
	v_and_or_b32 v23, v25, s27, v24
	global_store_dwordx2 v[70:71], v[22:23], off offset:1024
	global_load_dwordx4 v[22:25], v[46:47], off offset:3072
	s_waitcnt vmcnt(0)
	v_mul_f32_e32 v18, v18, v22
	v_mul_f32_e32 v20, v20, v24
	v_mul_f32_e32 v19, v19, v23
	v_mul_f32_e32 v21, v21, v25
	v_bfe_u32 v22, v18, 16, 1
	v_bfe_u32 v24, v20, 16, 1
	v_bfe_u32 v23, v19, 16, 1
	v_bfe_u32 v25, v21, 16, 1
	v_add3_u32 v18, v18, v22, s26
	v_add3_u32 v20, v20, v24, s26
	v_add3_u32 v19, v19, v23, s26
	v_add3_u32 v21, v21, v25, s26
	v_lshrrev_b32_e32 v18, 16, v18
	v_lshrrev_b32_e32 v20, 16, v20
	v_and_or_b32 v18, v19, s27, v18
	v_and_or_b32 v19, v21, s27, v20
	global_store_dwordx2 v[70:71], v[18:19], off offset:1536
	global_load_dwordx4 v[18:21], v[48:49], off
	s_waitcnt vmcnt(0)
	v_mul_f32_e32 v14, v14, v18
	v_mul_f32_e32 v16, v16, v20
	v_mul_f32_e32 v15, v15, v19
	v_mul_f32_e32 v17, v17, v21
	v_bfe_u32 v18, v14, 16, 1
	v_bfe_u32 v20, v16, 16, 1
	v_bfe_u32 v19, v15, 16, 1
	v_bfe_u32 v21, v17, 16, 1
	v_add3_u32 v14, v14, v18, s26
	v_add3_u32 v16, v16, v20, s26
	v_add3_u32 v15, v15, v19, s26
	v_add3_u32 v17, v17, v21, s26
	v_lshrrev_b32_e32 v14, 16, v14
	v_lshrrev_b32_e32 v16, 16, v16
	v_and_or_b32 v14, v15, s27, v14
	v_and_or_b32 v15, v17, s27, v16
	global_store_dwordx2 v[70:71], v[14:15], off offset:2048
	global_load_dwordx4 v[14:17], v[50:51], off
	s_waitcnt vmcnt(0)
	v_mul_f32_e32 v10, v10, v14
	v_mul_f32_e32 v12, v12, v16
	v_mul_f32_e32 v11, v11, v15
	v_mul_f32_e32 v13, v13, v17
	v_bfe_u32 v14, v10, 16, 1
	v_bfe_u32 v16, v12, 16, 1
	v_bfe_u32 v15, v11, 16, 1
	v_bfe_u32 v17, v13, 16, 1
	v_add3_u32 v10, v10, v14, s26
	v_add3_u32 v12, v12, v16, s26
	v_add3_u32 v11, v11, v15, s26
	v_add3_u32 v13, v13, v17, s26
	v_lshrrev_b32_e32 v10, 16, v10
	v_lshrrev_b32_e32 v12, 16, v12
	v_and_or_b32 v10, v11, s27, v10
	v_and_or_b32 v11, v13, s27, v12
	global_store_dwordx2 v[70:71], v[10:11], off offset:2560
	global_load_dwordx4 v[10:13], v[52:53], off
	s_waitcnt vmcnt(0)
	v_mul_f32_e32 v6, v6, v10
	v_mul_f32_e32 v8, v8, v12
	v_mul_f32_e32 v7, v7, v11
	v_mul_f32_e32 v9, v9, v13
	v_bfe_u32 v10, v6, 16, 1
	v_bfe_u32 v12, v8, 16, 1
	v_bfe_u32 v11, v7, 16, 1
	v_bfe_u32 v13, v9, 16, 1
	v_add3_u32 v6, v6, v10, s26
	v_add3_u32 v8, v8, v12, s26
	v_add3_u32 v7, v7, v11, s26
	v_add3_u32 v9, v9, v13, s26
	v_lshrrev_b32_e32 v6, 16, v6
	v_lshrrev_b32_e32 v8, 16, v8
	v_and_or_b32 v6, v7, s27, v6
	v_and_or_b32 v7, v9, s27, v8
	global_store_dwordx2 v[70:71], v[6:7], off offset:3072
	global_load_dwordx4 v[6:9], v[54:55], off
	s_waitcnt vmcnt(0)
	v_pk_mul_f32 v[2:3], v[2:3], v[6:7]
	s_nop 0
	v_and_b32_sdwa v7, v2, v61 dst_sel:DWORD dst_unused:UNUSED_PAD src0_sel:WORD_1 src1_sel:DWORD
	v_and_b32_sdwa v6, v3, v61 dst_sel:DWORD dst_unused:UNUSED_PAD src0_sel:WORD_1 src1_sel:DWORD
	v_add3_u32 v2, v2, v7, s26
	v_pk_mov_b32 v[4:5], v[4:5], v[8:9] op_sel:[1,0]
	v_add3_u32 v3, v3, v6, s26
	v_lshrrev_b32_e32 v2, 16, v2
	v_and_or_b32 v2, v3, s27, v2
	v_pk_mul_f32 v[4:5], v[4:5], v[40:41]
	s_branch .LBB0_107

; template <int K> __device__ __forceinline__ float shx(float v) { static_assert(K < 32, "use sum32"); return __int_as_float(__builtin_amdgcn_ds_swizzle(__float_as_int(v), (K << 10) | 0x1f)); }
; __device__ __forceinline__ unsigned pk2(float lo, float hi) { return f2bf(lo) | (f2bf(hi) << 16); }
; __device__ __forceinline__ float bflo(unsigned w) { return __uint_as_float(w << 16); }
; __device__ __forceinline__ float bfhi(unsigned w) { return __uint_as_float(w & 0xffff0000u); }
; __global__ void __launch_bounds__(NTHR, LB2) hymba_fwd(Args a) {
;     ...
;         for (int p = 0; p < 8; ++p) { const unsigned row = (unsigned)(pm * 256 + p * 32 + (tid >> 4)), o = (row * 1024u + c8) * 2u;
;             const v4u hw = __builtin_nontemporal_load((const v4u*)((const char*)HL + o)), aw = __builtin_nontemporal_load((const v4u*)((const char*)AC + o)), gw = __builtin_nontemporal_load((const v4u*)((const char*)GG + o));
;             const f32x4 y0 = ((f32x4){bflo(hw.x), bfhi(hw.x), bflo(hw.y), bfhi(hw.y)} + (f32x4){bflo(aw.x), bfhi(aw.x), bflo(aw.y), bfhi(aw.y)} * hi0) * (f32x4){bflo(gw.x), bfhi(gw.x), bflo(gw.y), bfhi(gw.y)};
;             const f32x4 y1 = ((f32x4){bflo(hw.z), bfhi(hw.z), bflo(hw.w), bfhi(hw.w)} + (f32x4){bflo(aw.z), bfhi(aw.z), bflo(aw.w), bfhi(aw.w)} * hi1) * (f32x4){bflo(gw.z), bfhi(gw.z), bflo(gw.w), bfhi(gw.w)};
;             float ss = (y0.x * y0.x + y0.y * y0.y) + (y0.z * y0.z + y0.w * y0.w) + (y1.x * y1.x + y1.y * y1.y) + (y1.z * y1.z + y1.w * y1.w);
;             v4u ow; ow.x = pk2(y0.x, y0.y); ow.y = pk2(y0.z, y0.w); ow.z = pk2(y1.x, y1.y); ow.w = pk2(y1.z, y1.w);
;             *(v4u*)((char*)MIX + ((size_t)row * 2048 + 1024 + c8) * 2) = ow;
;             ss += shx<1>(ss); ss += shx<2>(ss); ss += shx<4>(ss); ss += shx<8>(ss);
;             if ((tid & 15) == 0) SSQL[row * 8 + nblk] = ss; } } }
.LBB0_796:
	s_waitcnt lgkmcnt(0)
	global_load_dwordx4 v[0:3], v26, s[26:27] nt
	global_load_dwordx4 v[28:31], v26, s[28:29] nt
	global_load_dwordx4 v[32:35], v26, s[20:21] nt
	v_subrev_u32_e32 v4, 32, v18
	s_mov_b32 s12, 0xf000000
	s_waitcnt vmcnt(2)
	v_lshlrev_b32_e32 v20, 16, v0
	v_and_b32_e32 v21, 0xffff0000, v0
	v_lshlrev_b32_e32 v0, 16, v1
	v_and_b32_e32 v1, 0xffff0000, v1
	s_waitcnt vmcnt(1)
	v_lshlrev_b32_e32 v36, 16, v28
	v_and_b32_e32 v37, 0xffff0000, v28
	v_lshlrev_b32_e32 v28, 16, v29
	v_and_b32_e32 v29, 0xffff0000, v29
	v_pk_fma_f32 v[20:21], v[10:11], v[36:37], v[20:21]
	v_pk_fma_f32 v[0:1], v[12:13], v[28:29], v[0:1]
	s_waitcnt vmcnt(0)
	v_lshlrev_b32_e32 v28, 16, v32
	v_and_b32_e32 v29, 0xffff0000, v32
	v_lshlrev_b32_e32 v32, 16, v33
	v_and_b32_e32 v33, 0xffff0000, v33
	v_pk_mul_f32 v[0:1], v[0:1], v[32:33]
	v_pk_mul_f32 v[20:21], v[20:21], v[28:29]
	v_lshlrev_b32_e32 v28, 16, v2
	v_and_b32_e32 v29, 0xffff0000, v2
	v_lshlrev_b32_e32 v2, 16, v3
	v_and_b32_e32 v3, 0xffff0000, v3
	v_lshlrev_b32_e32 v32, 16, v30
	v_and_b32_e32 v33, 0xffff0000, v30
	v_lshlrev_b32_e32 v30, 16, v31
	v_and_b32_e32 v31, 0xffff0000, v31
	v_pk_fma_f32 v[28:29], v[14:15], v[32:33], v[28:29]
	v_pk_fma_f32 v[2:3], v[16:17], v[30:31], v[2:3]
	v_lshlrev_b32_e32 v30, 16, v34
	v_and_b32_e32 v31, 0xffff0000, v34
	v_mul_f32_e32 v19, v21, v21
	v_mul_f32_e32 v27, v1, v1
	v_pk_mul_f32 v[28:29], v[28:29], v[30:31]
	v_fmac_f32_e32 v19, v20, v20
	v_fmac_f32_e32 v27, v0, v0
	v_lshlrev_b32_e32 v32, 16, v35
	v_and_b32_e32 v33, 0xffff0000, v35
	v_add_f32_e32 v19, v19, v27
	v_mul_f32_e32 v27, v29, v29
	v_pk_mul_f32 v[2:3], v[2:3], v[32:33]
	v_fmac_f32_e32 v27, v28, v28
	v_add_f32_e32 v19, v27, v19
	v_mul_f32_e32 v27, v3, v3
	v_fmac_f32_e32 v27, v2, v2
	v_add_f32_e32 v19, v27, v19
	v_and_b32_sdwa v27, v0, v25 dst_sel:DWORD dst_unused:UNUSED_PAD src0_sel:WORD_1 src1_sel:DWORD
	v_and_b32_sdwa v30, v20, v25 dst_sel:DWORD dst_unused:UNUSED_PAD src0_sel:WORD_1 src1_sel:DWORD
	v_add3_u32 v20, v20, v30, s7
	v_add3_u32 v0, v0, v27, s7
	v_and_b32_sdwa v27, v1, v25 dst_sel:DWORD dst_unused:UNUSED_PAD src0_sel:WORD_1 src1_sel:DWORD
	v_and_b32_sdwa v30, v21, v25 dst_sel:DWORD dst_unused:UNUSED_PAD src0_sel:WORD_1 src1_sel:DWORD
	v_add3_u32 v1, v1, v27, s7
	v_add3_u32 v21, v21, v30, s7
	v_and_b32_e32 v1, 0xffff0000, v1
	v_and_b32_e32 v21, 0xffff0000, v21
	v_or_b32_sdwa v1, v1, v0 dst_sel:DWORD dst_unused:UNUSED_PAD src0_sel:DWORD src1_sel:WORD_1
	v_or_b32_sdwa v0, v21, v20 dst_sel:DWORD dst_unused:UNUSED_PAD src0_sel:DWORD src1_sel:WORD_1
	v_and_b32_sdwa v20, v2, v25 dst_sel:DWORD dst_unused:UNUSED_PAD src0_sel:WORD_1 src1_sel:DWORD
	v_add3_u32 v2, v2, v20, s7
	v_and_b32_sdwa v20, v3, v25 dst_sel:DWORD dst_unused:UNUSED_PAD src0_sel:WORD_1 src1_sel:DWORD
	v_and_b32_sdwa v27, v29, v25 dst_sel:DWORD dst_unused:UNUSED_PAD src0_sel:WORD_1 src1_sel:DWORD
	v_and_b32_sdwa v21, v28, v25 dst_sel:DWORD dst_unused:UNUSED_PAD src0_sel:WORD_1 src1_sel:DWORD
	v_add3_u32 v3, v3, v20, s7
	v_add3_u32 v20, v29, v27, s7
	v_add3_u32 v21, v28, v21, s7
	v_and_b32_e32 v3, 0xffff0000, v3
	v_and_b32_e32 v20, 0xffff0000, v20
	v_or_b32_sdwa v3, v3, v2 dst_sel:DWORD dst_unused:UNUSED_PAD src0_sel:DWORD src1_sel:WORD_1
	v_or_b32_sdwa v2, v20, v21 dst_sel:DWORD dst_unused:UNUSED_PAD src0_sel:DWORD src1_sel:WORD_1
	v_lshlrev_b64 v[20:21], 12, v[4:5]
	v_lshl_add_u64 v[20:21], v[6:7], 0, v[20:21]
	v_add_co_u32_e32 v20, vcc, s12, v20
	v_add_u32_e32 v4, s0, v22
	s_nop 0
	v_addc_co_u32_e32 v21, vcc, 0, v21, vcc
	global_store_dwordx4 v[20:21], v[0:3], off offset:2048
	s_nop 1
	v_mov_b32_dpp v0, v19 quad_perm:[1,0,3,2] row_mask:0xf bank_mask:0xf
	s_waitcnt lgkmcnt(0)
	v_add_f32_e32 v0, v19, v0
	ds_swizzle_b32 v1, v0 offset:swizzle(SWAP,2)
	s_waitcnt lgkmcnt(0)
	v_add_f32_e32 v0, v0, v1
	ds_swizzle_b32 v1, v0 offset:swizzle(SWAP,4)
	s_waitcnt lgkmcnt(0)
	v_add_f32_e32 v0, v0, v1
	ds_swizzle_b32 v1, v0 offset:swizzle(SWAP,8)
	s_and_saveexec_b64 s[12:13], s[34:35]
	s_cbranch_execz .LBB0_798
	v_lshl_add_u64 v[2:3], v[4:5], 2, s[24:25]
	s_waitcnt lgkmcnt(0)
	v_add_f32_e32 v0, v0, v1
	global_store_dword v[2:3], v0, off
; template <int K> __device__ __forceinline__ float shx(float v) { static_assert(K < 32, "use sum32"); return __int_as_float(__builtin_amdgcn_ds_swizzle(__float_as_int(v), (K << 10) | 0x1f)); }
; __device__ __forceinline__ unsigned pk2(float lo, float hi) { return f2bf(lo) | (f2bf(hi) << 16); }
; __device__ __forceinline__ float bflo(unsigned w) { return __uint_as_float(w << 16); }
; __device__ __forceinline__ float bfhi(unsigned w) { return __uint_as_float(w & 0xffff0000u); }
; __global__ void __launch_bounds__(NTHR, LB2) hymba_fwd(Args a) {
;     ...
;         for (int p = 0; p < 8; ++p) { const unsigned row = (unsigned)(pm * 256 + p * 32 + (tid >> 4)), o = (row * 1024u + c8) * 2u;
;             const v4u hw = __builtin_nontemporal_load((const v4u*)((const char*)HL + o)), aw = __builtin_nontemporal_load((const v4u*)((const char*)AC + o)), gw = __builtin_nontemporal_load((const v4u*)((const char*)GG + o));
;             const f32x4 y0 = ((f32x4){bflo(hw.x), bfhi(hw.x), bflo(hw.y), bfhi(hw.y)} + (f32x4){bflo(aw.x), bfhi(aw.x), bflo(aw.y), bfhi(aw.y)} * hi0) * (f32x4){bflo(gw.x), bfhi(gw.x), bflo(gw.y), bfhi(gw.y)};
;             const f32x4 y1 = ((f32x4){bflo(hw.z), bfhi(hw.z), bflo(hw.w), bfhi(hw.w)} + (f32x4){bflo(aw.z), bfhi(aw.z), bflo(aw.w), bfhi(aw.w)} * hi1) * (f32x4){bflo(gw.z), bfhi(gw.z), bflo(gw.w), bfhi(gw.w)};
;             float ss = (y0.x * y0.x + y0.y * y0.y) + (y0.z * y0.z + y0.w * y0.w) + (y1.x * y1.x + y1.y * y1.y) + (y1.z * y1.z + y1.w * y1.w);
;             v4u ow; ow.x = pk2(y0.x, y0.y); ow.y = pk2(y0.z, y0.w); ow.z = pk2(y1.x, y1.y); ow.w = pk2(y1.z, y1.w);
;             *(v4u*)((char*)MIX + ((size_t)row * 2048 + 1024 + c8) * 2) = ow;
;             ss += shx<1>(ss); ss += shx<2>(ss); ss += shx<4>(ss); ss += shx<8>(ss);
;             if ((tid & 15) == 0) SSQL[row * 8 + nblk] = ss; } } }
.LBB0_798:
	s_or_b64 exec, exec, s[12:13]
	v_add_u32_e32 v19, 0x10000, v26
	s_waitcnt lgkmcnt(0)
	global_load_dwordx4 v[0:3], v19, s[26:27] nt
	global_load_dwordx4 v[28:31], v19, s[28:29] nt
	global_load_dwordx4 v[32:35], v19, s[20:21] nt
	s_waitcnt vmcnt(2)
	v_lshlrev_b32_e32 v20, 16, v0
	v_and_b32_e32 v21, 0xffff0000, v0
	v_lshlrev_b32_e32 v0, 16, v1
	v_and_b32_e32 v1, 0xffff0000, v1
	s_waitcnt vmcnt(1)
	v_lshlrev_b32_e32 v36, 16, v28
	v_and_b32_e32 v37, 0xffff0000, v28
	v_lshlrev_b32_e32 v28, 16, v29
	v_and_b32_e32 v29, 0xffff0000, v29
	v_pk_fma_f32 v[20:21], v[10:11], v[36:37], v[20:21]
	v_pk_fma_f32 v[0:1], v[12:13], v[28:29], v[0:1]
	s_waitcnt vmcnt(0)
	v_lshlrev_b32_e32 v28, 16, v32
	v_and_b32_e32 v29, 0xffff0000, v32
	v_lshlrev_b32_e32 v32, 16, v33
	v_and_b32_e32 v33, 0xffff0000, v33
	v_pk_mul_f32 v[0:1], v[0:1], v[32:33]
	v_pk_mul_f32 v[20:21], v[20:21], v[28:29]
	v_lshlrev_b32_e32 v28, 16, v2
	v_and_b32_e32 v29, 0xffff0000, v2
	v_lshlrev_b32_e32 v2, 16, v3
	v_and_b32_e32 v3, 0xffff0000, v3
	v_lshlrev_b32_e32 v32, 16, v30
	v_and_b32_e32 v33, 0xffff0000, v30
	v_lshlrev_b32_e32 v30, 16, v31
	v_and_b32_e32 v31, 0xffff0000, v31
	v_pk_fma_f32 v[28:29], v[14:15], v[32:33], v[28:29]
	v_pk_fma_f32 v[2:3], v[16:17], v[30:31], v[2:3]
	v_lshlrev_b32_e32 v30, 16, v34
	v_and_b32_e32 v31, 0xffff0000, v34
	v_mul_f32_e32 v19, v21, v21
	v_mul_f32_e32 v27, v1, v1
	v_pk_mul_f32 v[28:29], v[28:29], v[30:31]
	v_fmac_f32_e32 v19, v20, v20
	v_fmac_f32_e32 v27, v0, v0
	v_lshlrev_b32_e32 v32, 16, v35
	v_and_b32_e32 v33, 0xffff0000, v35
	v_add_f32_e32 v19, v19, v27
	v_mul_f32_e32 v27, v29, v29
	v_pk_mul_f32 v[2:3], v[2:3], v[32:33]
	v_fmac_f32_e32 v27, v28, v28
	v_add_f32_e32 v19, v27, v19
	v_mul_f32_e32 v27, v3, v3
	v_fmac_f32_e32 v27, v2, v2
	v_add_f32_e32 v27, v27, v19
	v_and_b32_sdwa v19, v0, v25 dst_sel:DWORD dst_unused:UNUSED_PAD src0_sel:WORD_1 src1_sel:DWORD
	v_and_b32_sdwa v30, v20, v25 dst_sel:DWORD dst_unused:UNUSED_PAD src0_sel:WORD_1 src1_sel:DWORD
	v_add3_u32 v20, v20, v30, s7
	v_add3_u32 v0, v0, v19, s7
	v_and_b32_sdwa v19, v1, v25 dst_sel:DWORD dst_unused:UNUSED_PAD src0_sel:WORD_1 src1_sel:DWORD
	v_and_b32_sdwa v30, v21, v25 dst_sel:DWORD dst_unused:UNUSED_PAD src0_sel:WORD_1 src1_sel:DWORD
	v_add3_u32 v1, v1, v19, s7
	v_add3_u32 v19, v21, v30, s7
	v_and_b32_e32 v1, 0xffff0000, v1
	v_and_b32_e32 v19, 0xffff0000, v19
	v_or_b32_sdwa v1, v1, v0 dst_sel:DWORD dst_unused:UNUSED_PAD src0_sel:DWORD src1_sel:WORD_1
	v_or_b32_sdwa v0, v19, v20 dst_sel:DWORD dst_unused:UNUSED_PAD src0_sel:DWORD src1_sel:WORD_1
	v_and_b32_sdwa v19, v2, v25 dst_sel:DWORD dst_unused:UNUSED_PAD src0_sel:WORD_1 src1_sel:DWORD
	v_add3_u32 v2, v2, v19, s7
	v_and_b32_sdwa v19, v3, v25 dst_sel:DWORD dst_unused:UNUSED_PAD src0_sel:WORD_1 src1_sel:DWORD
	v_and_b32_sdwa v21, v29, v25 dst_sel:DWORD dst_unused:UNUSED_PAD src0_sel:WORD_1 src1_sel:DWORD
	v_and_b32_sdwa v20, v28, v25 dst_sel:DWORD dst_unused:UNUSED_PAD src0_sel:WORD_1 src1_sel:DWORD
	v_add3_u32 v3, v3, v19, s7
	v_add3_u32 v19, v29, v21, s7
	v_add3_u32 v20, v28, v20, s7
	v_and_b32_e32 v3, 0xffff0000, v3
	v_and_b32_e32 v19, 0xffff0000, v19
	v_or_b32_sdwa v3, v3, v2 dst_sel:DWORD dst_unused:UNUSED_PAD src0_sel:DWORD src1_sel:WORD_1
	v_or_b32_sdwa v2, v19, v20 dst_sel:DWORD dst_unused:UNUSED_PAD src0_sel:DWORD src1_sel:WORD_1
	v_mov_b32_e32 v19, v5
	v_lshlrev_b64 v[20:21], 12, v[18:19]
	v_lshl_add_u64 v[20:21], v[6:7], 0, v[20:21]
	v_add_co_u32_e32 v20, vcc, 0xf000000, v20
	s_nop 1
	v_addc_co_u32_e32 v21, vcc, 0, v21, vcc
	global_store_dwordx4 v[20:21], v[0:3], off offset:2048
	s_nop 1
	v_mov_b32_dpp v0, v27 quad_perm:[1,0,3,2] row_mask:0xf bank_mask:0xf
	s_waitcnt lgkmcnt(0)
	v_add_f32_e32 v0, v27, v0
	ds_swizzle_b32 v1, v0 offset:swizzle(SWAP,2)
	s_waitcnt lgkmcnt(0)
	v_add_f32_e32 v0, v0, v1
	ds_swizzle_b32 v1, v0 offset:swizzle(SWAP,4)
	s_waitcnt lgkmcnt(0)
	v_add_f32_e32 v0, v0, v1
	ds_swizzle_b32 v1, v0 offset:swizzle(SWAP,8)
	s_and_saveexec_b64 s[12:13], s[34:35]
	s_cbranch_execz .LBB0_795
	v_add_u32_e32 v4, 0x100, v4
	v_lshl_add_u64 v[2:3], v[4:5], 2, s[24:25]
	s_waitcnt lgkmcnt(0)
	v_add_f32_e32 v0, v0, v1
	global_store_dword v[2:3], v0, off
	s_branch .LBB0_795

; template <int K> __device__ __forceinline__ float shx(float v) { static_assert(K < 32, "use sum32"); return __int_as_float(__builtin_amdgcn_ds_swizzle(__float_as_int(v), (K << 10) | 0x1f)); }
; #define SBAR() __builtin_amdgcn_sched_barrier(0)
; __device__ __forceinline__ int crow(int r, int hi) { return (r & 3) + 8 * (r >> 2) + 4 * hi; }
; template <class TIn, class TOut, int ost, bool HAS_SS>
; __device__ __forceinline__ void causal_swa_block(const BlockRef<TIn, TOut>& cur_, const BlockRef<TIn, TOut>& nxt_, int skv, int W, char* lds, Seam<TIn>& S, int cbl  ) {
;     ...
;     if (hi == 0) li_l[r32] = l_reg; asm volatile("s_waitcnt lgkmcnt(0)" ::: "memory");
;     float rli[16];
; #pragma unroll
;     for (int r = 0; r < 16; ++r) rli[r] = __builtin_amdgcn_rcpf(li_l[crow(r, hi)]);
;     int r32e = r32, hie = hi; asm volatile("" : "+v"(r32e), "+v"(hie));
;     char* Ob = (char*)cur.O; const unsigned ob0 = (unsigned)((wid * QBLK + 4 * hie) * ost + r32e) * 2u;
; #pragma unroll
;     for (int r = 0; r < 16; ++r) { const unsigned rowoff = ob0 + (unsigned)(((r & 3) + 8 * (r >> 2)) * ost * 2); float ss_ = 0.f;
; #pragma unroll
;         for (int d0 = 0; d0 < 4; ++d0) { const float v = o[d0][r] * rli[r]; ss_ += v * v;
;             const float vn = shx<1>(v);
;             if ((r32e & 1) == 0) *(unsigned*)(Ob + rowoff + d0 * 64) = cvtpk(v, vn); }
;         if (HAS_SS) { ss_ += shx<1>(ss_); ss_ += shx<2>(ss_); ss_ += shx<4>(ss_); ss_ += shx<8>(ss_); ss_ += shx<16>(ss_);
;             if (r32e == 0) *(float*)((char*)cur.SS + (unsigned)(wid * QBLK + 4 * hie + (r & 3) + 8 * (r >> 2)) * 32u) = ss_; }
;         SBAR(); }
.LBB0_922:
	s_waitcnt vmcnt(8)
	s_waitcnt vmcnt(0) lgkmcnt(0)
	ds_write_b128 v200, v[120:123] offset:32768
	ds_write_b128 v200, v[124:127] offset:40960
	v_cmp_gt_u32_e32 vcc, 32, v201
	s_and_saveexec_b64 s[12:13], vcc
	ds_write_b32 v203, v0
	s_or_b64 exec, exec, s[12:13]
	s_waitcnt lgkmcnt(0)
	ds_read_b128 v[80:83], v202
	ds_read_b128 v[10:13], v202 offset:32
	ds_read_b128 v[6:9], v202 offset:64
	ds_read_b128 v[2:5], v202 offset:96
	s_waitcnt lgkmcnt(3)
	v_rcp_f32_e32 v85, v80
	v_lshl_add_u32 v80, v199, 2, s16
	v_lshlrev_b32_e32 v84, 1, v198
	v_and_b32_e32 v0, 1, v198
	v_cmp_eq_u32_e32 vcc, 0, v0
	v_lshl_add_u32 v0, v80, 12, v84
	v_lshl_add_u64 v[14:15], s[96:97], 0, v[0:1]
	v_mul_f32_e32 v0, v64, v85
	s_nop 1
	v_mov_b32_dpp v64, v0 quad_perm:[1,0,3,2] row_mask:0xf bank_mask:0xf
	s_and_saveexec_b64 s[12:13], vcc
	s_cbranch_execz .LBB0_926
	s_waitcnt lgkmcnt(0)
	v_cvt_pk_bf16_f32 v64, v0, v64
	global_store_dword v[14:15], v64, off
.LBB0_926:
	s_or_b64 exec, exec, s[12:13]
	v_mul_f32_e32 v48, v48, v85
	s_waitcnt lgkmcnt(0)
	s_nop 1
	v_mov_b32_dpp v64, v48 quad_perm:[1,0,3,2] row_mask:0xf bank_mask:0xf
	s_and_saveexec_b64 s[12:13], vcc
	s_cbranch_execz .LBB0_928
	s_waitcnt lgkmcnt(0)
	v_cvt_pk_bf16_f32 v64, v48, v64
	global_store_dword v[14:15], v64, off offset:64
.LBB0_928:
	s_or_b64 exec, exec, s[12:13]
	v_mul_f32_e32 v32, v32, v85
	s_waitcnt lgkmcnt(0)
	s_nop 1
	v_mov_b32_dpp v64, v32 quad_perm:[1,0,3,2] row_mask:0xf bank_mask:0xf
	s_and_saveexec_b64 s[12:13], vcc
	s_cbranch_execz .LBB0_930
	s_waitcnt lgkmcnt(0)
	v_cvt_pk_bf16_f32 v64, v32, v64
	global_store_dword v[14:15], v64, off offset:128
.LBB0_930:
	s_or_b64 exec, exec, s[12:13]
	v_mul_f32_e32 v16, v16, v85
	s_waitcnt lgkmcnt(0)
	s_nop 1
	v_mov_b32_dpp v64, v16 quad_perm:[1,0,3,2] row_mask:0xf bank_mask:0xf
	s_and_saveexec_b64 s[12:13], vcc
	s_cbranch_execz .LBB0_932
	s_waitcnt lgkmcnt(0)
	v_cvt_pk_bf16_f32 v64, v16, v64
	global_store_dword v[14:15], v64, off offset:192
.LBB0_932:
	s_or_b64 exec, exec, s[12:13]
	v_mul_f32_e32 v14, v48, v48
	v_fmac_f32_e32 v14, v0, v0
	v_fmac_f32_e32 v14, v32, v32
	v_fmac_f32_e32 v14, v16, v16
	s_nop 1
	v_mov_b32_dpp v0, v14 quad_perm:[1,0,3,2] row_mask:0xf bank_mask:0xf
	v_cmp_eq_u32_e64 s[34:35], 0, v198
	s_waitcnt lgkmcnt(0)
	v_add_f32_e32 v0, v14, v0
	ds_swizzle_b32 v14, v0 offset:swizzle(SWAP,2)
	s_waitcnt lgkmcnt(0)
	v_add_f32_e32 v0, v0, v14
	ds_swizzle_b32 v14, v0 offset:swizzle(SWAP,4)
	s_waitcnt lgkmcnt(0)
	v_add_f32_e32 v0, v0, v14
	ds_swizzle_b32 v14, v0 offset:swizzle(SWAP,8)
	s_waitcnt lgkmcnt(0)
	v_add_f32_e32 v0, v0, v14
	ds_swizzle_b32 v14, v0 offset:swizzle(SWAP,16)
	s_and_saveexec_b64 s[12:13], s[34:35]
	s_cbranch_execz .LBB0_934
	s_waitcnt lgkmcnt(0)
	v_add_f32_e32 v16, v0, v14
	v_lshlrev_b32_e32 v0, 5, v80
	v_lshl_add_u64 v[14:15], s[86:87], 0, v[0:1]
	global_store_dword v[14:15], v16, off
.LBB0_934:
	s_or_b64 exec, exec, s[12:13]
	v_rcp_f32_e32 v32, v81
	v_or_b32_e32 v16, 1, v80
	v_lshl_add_u32 v0, v16, 12, v84
	s_waitcnt lgkmcnt(0)
	v_lshl_add_u64 v[14:15], s[96:97], 0, v[0:1]
	v_mul_f32_e32 v0, v65, v32
	s_nop 1
	v_mov_b32_dpp v48, v0 quad_perm:[1,0,3,2] row_mask:0xf bank_mask:0xf
	s_and_saveexec_b64 s[12:13], vcc
	s_cbranch_execz .LBB0_936
	s_waitcnt lgkmcnt(0)
	v_cvt_pk_bf16_f32 v48, v0, v48
	global_store_dword v[14:15], v48, off
.LBB0_936:
	s_or_b64 exec, exec, s[12:13]
	s_waitcnt lgkmcnt(0)
	v_mul_f32_e32 v48, v49, v32
	s_nop 1
	v_mov_b32_dpp v49, v48 quad_perm:[1,0,3,2] row_mask:0xf bank_mask:0xf
	s_and_saveexec_b64 s[12:13], vcc
	s_cbranch_execz .LBB0_938
	s_waitcnt lgkmcnt(0)
	v_cvt_pk_bf16_f32 v49, v48, v49
	global_store_dword v[14:15], v49, off offset:64
.LBB0_938:
	s_or_b64 exec, exec, s[12:13]
	v_mul_f32_e32 v33, v33, v32
	s_waitcnt lgkmcnt(0)
	s_nop 1
	v_mov_b32_dpp v49, v33 quad_perm:[1,0,3,2] row_mask:0xf bank_mask:0xf
	s_and_saveexec_b64 s[12:13], vcc
	s_cbranch_execz .LBB0_940
	s_waitcnt lgkmcnt(0)
	v_cvt_pk_bf16_f32 v49, v33, v49
	global_store_dword v[14:15], v49, off offset:128
.LBB0_940:
	s_or_b64 exec, exec, s[12:13]
	v_mul_f32_e32 v17, v17, v32
	s_nop 1
	v_mov_b32_dpp v32, v17 quad_perm:[1,0,3,2] row_mask:0xf bank_mask:0xf
	s_and_saveexec_b64 s[12:13], vcc
	s_cbranch_execz .LBB0_942
	s_waitcnt lgkmcnt(0)
	v_cvt_pk_bf16_f32 v32, v17, v32
	global_store_dword v[14:15], v32, off offset:192
.LBB0_942:
	s_or_b64 exec, exec, s[12:13]
	v_mul_f32_e32 v14, v48, v48
	v_fmac_f32_e32 v14, v0, v0
	v_fmac_f32_e32 v14, v33, v33
	v_fmac_f32_e32 v14, v17, v17
	s_nop 1
	v_mov_b32_dpp v0, v14 quad_perm:[1,0,3,2] row_mask:0xf bank_mask:0xf
	s_waitcnt lgkmcnt(0)
	v_add_f32_e32 v0, v14, v0
	ds_swizzle_b32 v14, v0 offset:swizzle(SWAP,2)
	s_waitcnt lgkmcnt(0)
	v_add_f32_e32 v0, v0, v14
	ds_swizzle_b32 v14, v0 offset:swizzle(SWAP,4)
	s_waitcnt lgkmcnt(0)
	v_add_f32_e32 v0, v0, v14
	ds_swizzle_b32 v14, v0 offset:swizzle(SWAP,8)
	s_waitcnt lgkmcnt(0)
	v_add_f32_e32 v0, v0, v14
	ds_swizzle_b32 v14, v0 offset:swizzle(SWAP,16)
	s_and_saveexec_b64 s[12:13], s[34:35]
	s_cbranch_execz .LBB0_944
	s_waitcnt lgkmcnt(0)
	v_add_f32_e32 v17, v0, v14
	v_lshlrev_b32_e32 v0, 5, v16
	v_lshl_add_u64 v[14:15], s[86:87], 0, v[0:1]
	global_store_dword v[14:15], v17, off
.LBB0_944:
	s_or_b64 exec, exec, s[12:13]
	v_rcp_f32_e32 v17, v82
	v_or_b32_e32 v16, 2, v80
	v_lshl_add_u32 v0, v16, 12, v84
	s_waitcnt lgkmcnt(0)
	v_lshl_add_u64 v[14:15], s[96:97], 0, v[0:1]
	v_mul_f32_e32 v0, v66, v17
	s_nop 1
	v_mov_b32_dpp v32, v0 quad_perm:[1,0,3,2] row_mask:0xf bank_mask:0xf
	s_and_saveexec_b64 s[12:13], vcc
	s_cbranch_execz .LBB0_946
	s_waitcnt lgkmcnt(0)
	v_cvt_pk_bf16_f32 v32, v0, v32
	global_store_dword v[14:15], v32, off
; template <int K> __device__ __forceinline__ float shx(float v) { static_assert(K < 32, "use sum32"); return __int_as_float(__builtin_amdgcn_ds_swizzle(__float_as_int(v), (K << 10) | 0x1f)); }
; #define SBAR() __builtin_amdgcn_sched_barrier(0)
; __device__ __forceinline__ int crow(int r, int hi) { return (r & 3) + 8 * (r >> 2) + 4 * hi; }
; template <class TIn, class TOut, int ost, bool HAS_SS>
; __device__ __forceinline__ void causal_swa_block(const BlockRef<TIn, TOut>& cur_, const BlockRef<TIn, TOut>& nxt_, int skv, int W, char* lds, Seam<TIn>& S, int cbl  ) {
;     ...
;     if (hi == 0) li_l[r32] = l_reg; asm volatile("s_waitcnt lgkmcnt(0)" ::: "memory");
;     float rli[16];
; #pragma unroll
;     for (int r = 0; r < 16; ++r) rli[r] = __builtin_amdgcn_rcpf(li_l[crow(r, hi)]);
;     int r32e = r32, hie = hi; asm volatile("" : "+v"(r32e), "+v"(hie));
;     char* Ob = (char*)cur.O; const unsigned ob0 = (unsigned)((wid * QBLK + 4 * hie) * ost + r32e) * 2u;
; #pragma unroll
;     for (int r = 0; r < 16; ++r) { const unsigned rowoff = ob0 + (unsigned)(((r & 3) + 8 * (r >> 2)) * ost * 2); float ss_ = 0.f;
; #pragma unroll
;         for (int d0 = 0; d0 < 4; ++d0) { const float v = o[d0][r] * rli[r]; ss_ += v * v;
;             const float vn = shx<1>(v);
;             if ((r32e & 1) == 0) *(unsigned*)(Ob + rowoff + d0 * 64) = cvtpk(v, vn); }
;         if (HAS_SS) { ss_ += shx<1>(ss_); ss_ += shx<2>(ss_); ss_ += shx<4>(ss_); ss_ += shx<8>(ss_); ss_ += shx<16>(ss_);
;             if (r32e == 0) *(float*)((char*)cur.SS + (unsigned)(wid * QBLK + 4 * hie + (r & 3) + 8 * (r >> 2)) * 32u) = ss_; }
;         SBAR(); }
.LBB0_946:
	s_or_b64 exec, exec, s[12:13]
	s_waitcnt lgkmcnt(0)
	v_mul_f32_e32 v32, v50, v17
	s_nop 1
	v_mov_b32_dpp v33, v32 quad_perm:[1,0,3,2] row_mask:0xf bank_mask:0xf
	s_and_saveexec_b64 s[12:13], vcc
	s_cbranch_execz .LBB0_948
	s_waitcnt lgkmcnt(0)
	v_cvt_pk_bf16_f32 v33, v32, v33
	global_store_dword v[14:15], v33, off offset:64
.LBB0_948:
	s_or_b64 exec, exec, s[12:13]
	s_waitcnt lgkmcnt(0)
	v_mul_f32_e32 v33, v34, v17
	s_nop 1
	v_mov_b32_dpp v34, v33 quad_perm:[1,0,3,2] row_mask:0xf bank_mask:0xf
	s_and_saveexec_b64 s[12:13], vcc
	s_cbranch_execz .LBB0_950
	s_waitcnt lgkmcnt(0)
	v_cvt_pk_bf16_f32 v34, v33, v34
	global_store_dword v[14:15], v34, off offset:128
.LBB0_950:
	s_or_b64 exec, exec, s[12:13]
	v_mul_f32_e32 v17, v18, v17
	s_nop 1
	v_mov_b32_dpp v18, v17 quad_perm:[1,0,3,2] row_mask:0xf bank_mask:0xf
	s_and_saveexec_b64 s[12:13], vcc
	s_cbranch_execz .LBB0_952
	s_waitcnt lgkmcnt(0)
	v_cvt_pk_bf16_f32 v18, v17, v18
	global_store_dword v[14:15], v18, off offset:192
.LBB0_952:
	s_or_b64 exec, exec, s[12:13]
	v_mul_f32_e32 v14, v32, v32
	v_fmac_f32_e32 v14, v0, v0
	v_fmac_f32_e32 v14, v33, v33
	v_fmac_f32_e32 v14, v17, v17
	s_nop 1
	v_mov_b32_dpp v0, v14 quad_perm:[1,0,3,2] row_mask:0xf bank_mask:0xf
	s_waitcnt lgkmcnt(0)
	v_add_f32_e32 v0, v14, v0
	ds_swizzle_b32 v14, v0 offset:swizzle(SWAP,2)
	s_waitcnt lgkmcnt(0)
	v_add_f32_e32 v0, v0, v14
	ds_swizzle_b32 v14, v0 offset:swizzle(SWAP,4)
	s_waitcnt lgkmcnt(0)
	v_add_f32_e32 v0, v0, v14
	ds_swizzle_b32 v14, v0 offset:swizzle(SWAP,8)
	s_waitcnt lgkmcnt(0)
	v_add_f32_e32 v0, v0, v14
	ds_swizzle_b32 v14, v0 offset:swizzle(SWAP,16)
	s_and_saveexec_b64 s[12:13], s[34:35]
	s_cbranch_execz .LBB0_954
	s_waitcnt lgkmcnt(0)
	v_add_f32_e32 v17, v0, v14
	v_lshlrev_b32_e32 v0, 5, v16
	v_lshl_add_u64 v[14:15], s[86:87], 0, v[0:1]
	global_store_dword v[14:15], v17, off
.LBB0_954:
	s_or_b64 exec, exec, s[12:13]
	v_rcp_f32_e32 v17, v83
	v_or_b32_e32 v16, 3, v80
	v_lshl_add_u32 v0, v16, 12, v84
	s_waitcnt lgkmcnt(0)
	v_lshl_add_u64 v[14:15], s[96:97], 0, v[0:1]
	v_mul_f32_e32 v0, v67, v17
	s_nop 1
	v_mov_b32_dpp v18, v0 quad_perm:[1,0,3,2] row_mask:0xf bank_mask:0xf
	s_and_saveexec_b64 s[12:13], vcc
	s_cbranch_execz .LBB0_956
	s_waitcnt lgkmcnt(0)
	v_cvt_pk_bf16_f32 v18, v0, v18
	global_store_dword v[14:15], v18, off
.LBB0_956:
	s_or_b64 exec, exec, s[12:13]
	s_waitcnt lgkmcnt(0)
	v_mul_f32_e32 v18, v51, v17
	s_nop 1
	v_mov_b32_dpp v32, v18 quad_perm:[1,0,3,2] row_mask:0xf bank_mask:0xf
	s_and_saveexec_b64 s[12:13], vcc
	s_cbranch_execz .LBB0_958
	s_waitcnt lgkmcnt(0)
	v_cvt_pk_bf16_f32 v32, v18, v32
	global_store_dword v[14:15], v32, off offset:64
.LBB0_958:
	s_or_b64 exec, exec, s[12:13]
	s_waitcnt lgkmcnt(0)
	v_mul_f32_e32 v32, v35, v17
	s_nop 1
	v_mov_b32_dpp v33, v32 quad_perm:[1,0,3,2] row_mask:0xf bank_mask:0xf
	s_and_saveexec_b64 s[12:13], vcc
	s_cbranch_execz .LBB0_960
	s_waitcnt lgkmcnt(0)
	v_cvt_pk_bf16_f32 v33, v32, v33
	global_store_dword v[14:15], v33, off offset:128
.LBB0_960:
	s_or_b64 exec, exec, s[12:13]
	v_mul_f32_e32 v17, v19, v17
	s_nop 1
	v_mov_b32_dpp v19, v17 quad_perm:[1,0,3,2] row_mask:0xf bank_mask:0xf
	s_and_saveexec_b64 s[12:13], vcc
	s_cbranch_execz .LBB0_962
	s_waitcnt lgkmcnt(0)
	v_cvt_pk_bf16_f32 v19, v17, v19
	global_store_dword v[14:15], v19, off offset:192
.LBB0_962:
	s_or_b64 exec, exec, s[12:13]
	v_mul_f32_e32 v14, v18, v18
	v_fmac_f32_e32 v14, v0, v0
	v_fmac_f32_e32 v14, v32, v32
	v_fmac_f32_e32 v14, v17, v17
	s_nop 1
	v_mov_b32_dpp v0, v14 quad_perm:[1,0,3,2] row_mask:0xf bank_mask:0xf
	s_waitcnt lgkmcnt(0)
	v_add_f32_e32 v0, v14, v0
	ds_swizzle_b32 v14, v0 offset:swizzle(SWAP,2)
	s_waitcnt lgkmcnt(0)
	v_add_f32_e32 v0, v0, v14
	ds_swizzle_b32 v14, v0 offset:swizzle(SWAP,4)
	s_waitcnt lgkmcnt(0)
	v_add_f32_e32 v0, v0, v14
	ds_swizzle_b32 v14, v0 offset:swizzle(SWAP,8)
	s_waitcnt lgkmcnt(0)
	v_add_f32_e32 v0, v0, v14
	ds_swizzle_b32 v14, v0 offset:swizzle(SWAP,16)
	s_and_saveexec_b64 s[12:13], s[34:35]
	s_cbranch_execz .LBB0_964
	s_waitcnt lgkmcnt(0)
	v_add_f32_e32 v17, v0, v14
	v_lshlrev_b32_e32 v0, 5, v16
	v_lshl_add_u64 v[14:15], s[86:87], 0, v[0:1]
	global_store_dword v[14:15], v17, off
.LBB0_964:
	s_or_b64 exec, exec, s[12:13]
	v_rcp_f32_e32 v16, v10
	v_add_u32_e32 v10, 8, v80
	v_lshl_add_u32 v0, v10, 12, v84
	s_waitcnt lgkmcnt(0)
	v_lshl_add_u64 v[14:15], s[96:97], 0, v[0:1]
	v_mul_f32_e32 v0, v68, v16
	s_nop 1
	v_mov_b32_dpp v17, v0 quad_perm:[1,0,3,2] row_mask:0xf bank_mask:0xf
	s_and_saveexec_b64 s[12:13], vcc
	s_cbranch_execz .LBB0_966
	s_waitcnt lgkmcnt(0)
	v_cvt_pk_bf16_f32 v17, v0, v17
	global_store_dword v[14:15], v17, off
.LBB0_966:
	s_or_b64 exec, exec, s[12:13]
	s_waitcnt lgkmcnt(0)
	v_mul_f32_e32 v17, v52, v16
	s_nop 1
	v_mov_b32_dpp v18, v17 quad_perm:[1,0,3,2] row_mask:0xf bank_mask:0xf
	s_and_saveexec_b64 s[12:13], vcc
	s_cbranch_execz .LBB0_968
	s_waitcnt lgkmcnt(0)
	v_cvt_pk_bf16_f32 v18, v17, v18
	global_store_dword v[14:15], v18, off offset:64
.LBB0_968:
	s_or_b64 exec, exec, s[12:13]
	s_waitcnt lgkmcnt(0)
	v_mul_f32_e32 v18, v36, v16
	s_nop 1
	v_mov_b32_dpp v19, v18 quad_perm:[1,0,3,2] row_mask:0xf bank_mask:0xf
	s_and_saveexec_b64 s[12:13], vcc
	s_cbranch_execz .LBB0_970
	s_waitcnt lgkmcnt(0)
	v_cvt_pk_bf16_f32 v19, v18, v19
	global_store_dword v[14:15], v19, off offset:128
.LBB0_970:
	s_or_b64 exec, exec, s[12:13]
	v_mul_f32_e32 v16, v20, v16
	s_waitcnt lgkmcnt(0)
	s_nop 1
	v_mov_b32_dpp v19, v16 quad_perm:[1,0,3,2] row_mask:0xf bank_mask:0xf
	s_and_saveexec_b64 s[12:13], vcc
	s_cbranch_execz .LBB0_972
	s_waitcnt lgkmcnt(0)
	v_cvt_pk_bf16_f32 v19, v16, v19
	global_store_dword v[14:15], v19, off offset:192
; template <int K> __device__ __forceinline__ float shx(float v) { static_assert(K < 32, "use sum32"); return __int_as_float(__builtin_amdgcn_ds_swizzle(__float_as_int(v), (K << 10) | 0x1f)); }
; #define SBAR() __builtin_amdgcn_sched_barrier(0)
; __device__ __forceinline__ int crow(int r, int hi) { return (r & 3) + 8 * (r >> 2) + 4 * hi; }
; template <class TIn, class TOut, int ost, bool HAS_SS>
; __device__ __forceinline__ void causal_swa_block(const BlockRef<TIn, TOut>& cur_, const BlockRef<TIn, TOut>& nxt_, int skv, int W, char* lds, Seam<TIn>& S, int cbl  ) {
;     ...
;     if (hi == 0) li_l[r32] = l_reg; asm volatile("s_waitcnt lgkmcnt(0)" ::: "memory");
;     float rli[16];
; #pragma unroll
;     for (int r = 0; r < 16; ++r) rli[r] = __builtin_amdgcn_rcpf(li_l[crow(r, hi)]);
;     int r32e = r32, hie = hi; asm volatile("" : "+v"(r32e), "+v"(hie));
;     char* Ob = (char*)cur.O; const unsigned ob0 = (unsigned)((wid * QBLK + 4 * hie) * ost + r32e) * 2u;
; #pragma unroll
;     for (int r = 0; r < 16; ++r) { const unsigned rowoff = ob0 + (unsigned)(((r & 3) + 8 * (r >> 2)) * ost * 2); float ss_ = 0.f;
; #pragma unroll
;         for (int d0 = 0; d0 < 4; ++d0) { const float v = o[d0][r] * rli[r]; ss_ += v * v;
;             const float vn = shx<1>(v);
;             if ((r32e & 1) == 0) *(unsigned*)(Ob + rowoff + d0 * 64) = cvtpk(v, vn); }
;         if (HAS_SS) { ss_ += shx<1>(ss_); ss_ += shx<2>(ss_); ss_ += shx<4>(ss_); ss_ += shx<8>(ss_); ss_ += shx<16>(ss_);
;             if (r32e == 0) *(float*)((char*)cur.SS + (unsigned)(wid * QBLK + 4 * hie + (r & 3) + 8 * (r >> 2)) * 32u) = ss_; }
;         SBAR(); }
.LBB0_972:
	s_or_b64 exec, exec, s[12:13]
	v_mul_f32_e32 v14, v17, v17
	v_fmac_f32_e32 v14, v0, v0
	v_fmac_f32_e32 v14, v18, v18
	v_fmac_f32_e32 v14, v16, v16
	s_nop 1
	v_mov_b32_dpp v0, v14 quad_perm:[1,0,3,2] row_mask:0xf bank_mask:0xf
	s_waitcnt lgkmcnt(0)
	v_add_f32_e32 v0, v14, v0
	ds_swizzle_b32 v14, v0 offset:swizzle(SWAP,2)
	s_waitcnt lgkmcnt(0)
	v_add_f32_e32 v0, v0, v14
	ds_swizzle_b32 v14, v0 offset:swizzle(SWAP,4)
	s_waitcnt lgkmcnt(0)
	v_add_f32_e32 v0, v0, v14
	ds_swizzle_b32 v14, v0 offset:swizzle(SWAP,8)
	s_waitcnt lgkmcnt(0)
	v_add_f32_e32 v0, v0, v14
	ds_swizzle_b32 v14, v0 offset:swizzle(SWAP,16)
	s_and_saveexec_b64 s[12:13], s[34:35]
	s_cbranch_execz .LBB0_974
	s_waitcnt lgkmcnt(0)
	v_add_f32_e32 v16, v0, v14
	v_lshlrev_b32_e32 v0, 5, v10
	v_lshl_add_u64 v[14:15], s[86:87], 0, v[0:1]
	global_store_dword v[14:15], v16, off
.LBB0_974:
	s_or_b64 exec, exec, s[12:13]
	v_rcp_f32_e32 v15, v11
	s_waitcnt lgkmcnt(0)
	v_add_u32_e32 v14, 9, v80
	v_lshl_add_u32 v0, v14, 12, v84
	v_lshl_add_u64 v[10:11], s[96:97], 0, v[0:1]
	v_mul_f32_e32 v0, v69, v15
	s_nop 1
	v_mov_b32_dpp v16, v0 quad_perm:[1,0,3,2] row_mask:0xf bank_mask:0xf
	s_and_saveexec_b64 s[12:13], vcc
	s_cbranch_execz .LBB0_976
	s_waitcnt lgkmcnt(0)
	v_cvt_pk_bf16_f32 v16, v0, v16
	global_store_dword v[10:11], v16, off
.LBB0_976:
	s_or_b64 exec, exec, s[12:13]
	s_waitcnt lgkmcnt(0)
	v_mul_f32_e32 v16, v53, v15
	s_nop 1
	v_mov_b32_dpp v17, v16 quad_perm:[1,0,3,2] row_mask:0xf bank_mask:0xf
	s_and_saveexec_b64 s[12:13], vcc
	s_cbranch_execz .LBB0_978
	s_waitcnt lgkmcnt(0)
	v_cvt_pk_bf16_f32 v17, v16, v17
	global_store_dword v[10:11], v17, off offset:64
.LBB0_978:
	s_or_b64 exec, exec, s[12:13]
	s_waitcnt lgkmcnt(0)
	v_mul_f32_e32 v17, v37, v15
	s_nop 1
	v_mov_b32_dpp v18, v17 quad_perm:[1,0,3,2] row_mask:0xf bank_mask:0xf
	s_and_saveexec_b64 s[12:13], vcc
	s_cbranch_execz .LBB0_980
	s_waitcnt lgkmcnt(0)
	v_cvt_pk_bf16_f32 v18, v17, v18
	global_store_dword v[10:11], v18, off offset:128
.LBB0_980:
	s_or_b64 exec, exec, s[12:13]
	v_mul_f32_e32 v15, v21, v15
	s_waitcnt lgkmcnt(0)
	s_nop 1
	v_mov_b32_dpp v18, v15 quad_perm:[1,0,3,2] row_mask:0xf bank_mask:0xf
	s_and_saveexec_b64 s[12:13], vcc
	s_cbranch_execz .LBB0_982
	s_waitcnt lgkmcnt(0)
	v_cvt_pk_bf16_f32 v18, v15, v18
	global_store_dword v[10:11], v18, off offset:192
.LBB0_982:
	s_or_b64 exec, exec, s[12:13]
	v_mul_f32_e32 v10, v16, v16
	v_fmac_f32_e32 v10, v0, v0
	v_fmac_f32_e32 v10, v17, v17
	v_fmac_f32_e32 v10, v15, v15
	s_nop 1
	v_mov_b32_dpp v0, v10 quad_perm:[1,0,3,2] row_mask:0xf bank_mask:0xf
	s_waitcnt lgkmcnt(0)
	v_add_f32_e32 v0, v10, v0
	ds_swizzle_b32 v10, v0 offset:swizzle(SWAP,2)
	s_waitcnt lgkmcnt(0)
	v_add_f32_e32 v0, v0, v10
	ds_swizzle_b32 v10, v0 offset:swizzle(SWAP,4)
	s_waitcnt lgkmcnt(0)
	v_add_f32_e32 v0, v0, v10
	ds_swizzle_b32 v10, v0 offset:swizzle(SWAP,8)
	s_waitcnt lgkmcnt(0)
	v_add_f32_e32 v0, v0, v10
	ds_swizzle_b32 v10, v0 offset:swizzle(SWAP,16)
	s_and_saveexec_b64 s[12:13], s[34:35]
	s_cbranch_execz .LBB0_984
	s_waitcnt lgkmcnt(0)
	v_add_f32_e32 v15, v0, v10
	v_lshlrev_b32_e32 v0, 5, v14
	v_lshl_add_u64 v[10:11], s[86:87], 0, v[0:1]
	global_store_dword v[10:11], v15, off
.LBB0_984:
	s_or_b64 exec, exec, s[12:13]
	v_rcp_f32_e32 v14, v12
	v_add_u32_e32 v12, 10, v80
	v_lshl_add_u32 v0, v12, 12, v84
	s_waitcnt lgkmcnt(0)
	v_lshl_add_u64 v[10:11], s[96:97], 0, v[0:1]
	v_mul_f32_e32 v0, v70, v14
	s_nop 1
	v_mov_b32_dpp v15, v0 quad_perm:[1,0,3,2] row_mask:0xf bank_mask:0xf
	s_and_saveexec_b64 s[12:13], vcc
	s_cbranch_execz .LBB0_986
	s_waitcnt lgkmcnt(0)
	v_cvt_pk_bf16_f32 v15, v0, v15
	global_store_dword v[10:11], v15, off
.LBB0_986:
	s_or_b64 exec, exec, s[12:13]
	s_waitcnt lgkmcnt(0)
	v_mul_f32_e32 v15, v54, v14
	s_nop 1
	v_mov_b32_dpp v16, v15 quad_perm:[1,0,3,2] row_mask:0xf bank_mask:0xf
	s_and_saveexec_b64 s[12:13], vcc
	s_cbranch_execz .LBB0_988
	s_waitcnt lgkmcnt(0)
	v_cvt_pk_bf16_f32 v16, v15, v16
	global_store_dword v[10:11], v16, off offset:64
.LBB0_988:
	s_or_b64 exec, exec, s[12:13]
	s_waitcnt lgkmcnt(0)
	v_mul_f32_e32 v16, v38, v14
	s_nop 1
	v_mov_b32_dpp v17, v16 quad_perm:[1,0,3,2] row_mask:0xf bank_mask:0xf
	s_and_saveexec_b64 s[12:13], vcc
	s_cbranch_execz .LBB0_990
	s_waitcnt lgkmcnt(0)
	v_cvt_pk_bf16_f32 v17, v16, v17
	global_store_dword v[10:11], v17, off offset:128
.LBB0_990:
	s_or_b64 exec, exec, s[12:13]
	v_mul_f32_e32 v14, v22, v14
	s_waitcnt lgkmcnt(0)
	s_nop 1
	v_mov_b32_dpp v17, v14 quad_perm:[1,0,3,2] row_mask:0xf bank_mask:0xf
	s_and_saveexec_b64 s[12:13], vcc
	s_cbranch_execz .LBB0_992
	s_waitcnt lgkmcnt(0)
	v_cvt_pk_bf16_f32 v17, v14, v17
	global_store_dword v[10:11], v17, off offset:192
.LBB0_992:
	s_or_b64 exec, exec, s[12:13]
	v_mul_f32_e32 v10, v15, v15
	v_fmac_f32_e32 v10, v0, v0
	v_fmac_f32_e32 v10, v16, v16
	v_fmac_f32_e32 v10, v14, v14
	s_nop 1
	v_mov_b32_dpp v0, v10 quad_perm:[1,0,3,2] row_mask:0xf bank_mask:0xf
	s_waitcnt lgkmcnt(0)
	v_add_f32_e32 v0, v10, v0
	ds_swizzle_b32 v10, v0 offset:swizzle(SWAP,2)
	s_waitcnt lgkmcnt(0)
	v_add_f32_e32 v0, v0, v10
	ds_swizzle_b32 v10, v0 offset:swizzle(SWAP,4)
	s_waitcnt lgkmcnt(0)
	v_add_f32_e32 v0, v0, v10
	ds_swizzle_b32 v10, v0 offset:swizzle(SWAP,8)
	s_waitcnt lgkmcnt(0)
	v_add_f32_e32 v0, v0, v10
	ds_swizzle_b32 v10, v0 offset:swizzle(SWAP,16)
	s_and_saveexec_b64 s[12:13], s[34:35]
	s_cbranch_execz .LBB0_994
	s_waitcnt lgkmcnt(0)
	v_add_f32_e32 v14, v0, v10
	v_lshlrev_b32_e32 v0, 5, v12
	v_lshl_add_u64 v[10:11], s[86:87], 0, v[0:1]
	global_store_dword v[10:11], v14, off
; template <int K> __device__ __forceinline__ float shx(float v) { static_assert(K < 32, "use sum32"); return __int_as_float(__builtin_amdgcn_ds_swizzle(__float_as_int(v), (K << 10) | 0x1f)); }
; #define SBAR() __builtin_amdgcn_sched_barrier(0)
; __device__ __forceinline__ int crow(int r, int hi) { return (r & 3) + 8 * (r >> 2) + 4 * hi; }
; template <class TIn, class TOut, int ost, bool HAS_SS>
; __device__ __forceinline__ void causal_swa_block(const BlockRef<TIn, TOut>& cur_, const BlockRef<TIn, TOut>& nxt_, int skv, int W, char* lds, Seam<TIn>& S, int cbl  ) {
;     ...
;     if (hi == 0) li_l[r32] = l_reg; asm volatile("s_waitcnt lgkmcnt(0)" ::: "memory");
;     float rli[16];
; #pragma unroll
;     for (int r = 0; r < 16; ++r) rli[r] = __builtin_amdgcn_rcpf(li_l[crow(r, hi)]);
;     int r32e = r32, hie = hi; asm volatile("" : "+v"(r32e), "+v"(hie));
;     char* Ob = (char*)cur.O; const unsigned ob0 = (unsigned)((wid * QBLK + 4 * hie) * ost + r32e) * 2u;
; #pragma unroll
;     for (int r = 0; r < 16; ++r) { const unsigned rowoff = ob0 + (unsigned)(((r & 3) + 8 * (r >> 2)) * ost * 2); float ss_ = 0.f;
; #pragma unroll
;         for (int d0 = 0; d0 < 4; ++d0) { const float v = o[d0][r] * rli[r]; ss_ += v * v;
;             const float vn = shx<1>(v);
;             if ((r32e & 1) == 0) *(unsigned*)(Ob + rowoff + d0 * 64) = cvtpk(v, vn); }
;         if (HAS_SS) { ss_ += shx<1>(ss_); ss_ += shx<2>(ss_); ss_ += shx<4>(ss_); ss_ += shx<8>(ss_); ss_ += shx<16>(ss_);
;             if (r32e == 0) *(float*)((char*)cur.SS + (unsigned)(wid * QBLK + 4 * hie + (r & 3) + 8 * (r >> 2)) * 32u) = ss_; }
;         SBAR(); }
.LBB0_994:
	s_or_b64 exec, exec, s[12:13]
	v_rcp_f32_e32 v13, v13
	v_add_u32_e32 v12, 11, v80
	v_lshl_add_u32 v0, v12, 12, v84
	s_waitcnt lgkmcnt(0)
	v_lshl_add_u64 v[10:11], s[96:97], 0, v[0:1]
	v_mul_f32_e32 v0, v71, v13
	s_nop 1
	v_mov_b32_dpp v14, v0 quad_perm:[1,0,3,2] row_mask:0xf bank_mask:0xf
	s_and_saveexec_b64 s[12:13], vcc
	s_cbranch_execz .LBB0_996
	s_waitcnt lgkmcnt(0)
	v_cvt_pk_bf16_f32 v14, v0, v14
	global_store_dword v[10:11], v14, off
.LBB0_996:
	s_or_b64 exec, exec, s[12:13]
	s_waitcnt lgkmcnt(0)
	v_mul_f32_e32 v14, v55, v13
	s_nop 1
	v_mov_b32_dpp v15, v14 quad_perm:[1,0,3,2] row_mask:0xf bank_mask:0xf
	s_and_saveexec_b64 s[12:13], vcc
	s_cbranch_execz .LBB0_998
	s_waitcnt lgkmcnt(0)
	v_cvt_pk_bf16_f32 v15, v14, v15
	global_store_dword v[10:11], v15, off offset:64
.LBB0_998:
	s_or_b64 exec, exec, s[12:13]
	s_waitcnt lgkmcnt(0)
	v_mul_f32_e32 v15, v39, v13
	s_nop 1
	v_mov_b32_dpp v16, v15 quad_perm:[1,0,3,2] row_mask:0xf bank_mask:0xf
	s_and_saveexec_b64 s[12:13], vcc
	s_cbranch_execz .LBB0_1000
	s_waitcnt lgkmcnt(0)
	v_cvt_pk_bf16_f32 v16, v15, v16
	global_store_dword v[10:11], v16, off offset:128
.LBB0_1000:
	s_or_b64 exec, exec, s[12:13]
	v_mul_f32_e32 v13, v23, v13
	s_waitcnt lgkmcnt(0)
	s_nop 1
	v_mov_b32_dpp v16, v13 quad_perm:[1,0,3,2] row_mask:0xf bank_mask:0xf
	s_and_saveexec_b64 s[12:13], vcc
	s_cbranch_execz .LBB0_1002
	s_waitcnt lgkmcnt(0)
	v_cvt_pk_bf16_f32 v16, v13, v16
	global_store_dword v[10:11], v16, off offset:192
.LBB0_1002:
	s_or_b64 exec, exec, s[12:13]
	v_mul_f32_e32 v10, v14, v14
	v_fmac_f32_e32 v10, v0, v0
	v_fmac_f32_e32 v10, v15, v15
	v_fmac_f32_e32 v10, v13, v13
	s_nop 1
	v_mov_b32_dpp v0, v10 quad_perm:[1,0,3,2] row_mask:0xf bank_mask:0xf
	s_waitcnt lgkmcnt(0)
	v_add_f32_e32 v0, v10, v0
	ds_swizzle_b32 v10, v0 offset:swizzle(SWAP,2)
	s_waitcnt lgkmcnt(0)
	v_add_f32_e32 v0, v0, v10
	ds_swizzle_b32 v10, v0 offset:swizzle(SWAP,4)
	s_waitcnt lgkmcnt(0)
	v_add_f32_e32 v0, v0, v10
	ds_swizzle_b32 v10, v0 offset:swizzle(SWAP,8)
	s_waitcnt lgkmcnt(0)
	v_add_f32_e32 v0, v0, v10
	ds_swizzle_b32 v10, v0 offset:swizzle(SWAP,16)
	s_and_saveexec_b64 s[12:13], s[34:35]
	s_cbranch_execz .LBB0_1004
	s_waitcnt lgkmcnt(0)
	v_add_f32_e32 v13, v0, v10
	v_lshlrev_b32_e32 v0, 5, v12
	v_lshl_add_u64 v[10:11], s[86:87], 0, v[0:1]
	global_store_dword v[10:11], v13, off
.LBB0_1004:
	s_or_b64 exec, exec, s[12:13]
	v_rcp_f32_e32 v12, v6
	v_add_u32_e32 v6, 16, v80
	v_lshl_add_u32 v0, v6, 12, v84
	s_waitcnt lgkmcnt(0)
	v_lshl_add_u64 v[10:11], s[96:97], 0, v[0:1]
	v_mul_f32_e32 v0, v72, v12
	s_nop 1
	v_mov_b32_dpp v13, v0 quad_perm:[1,0,3,2] row_mask:0xf bank_mask:0xf
	s_and_saveexec_b64 s[12:13], vcc
	s_cbranch_execz .LBB0_1006
	s_waitcnt lgkmcnt(0)
	v_cvt_pk_bf16_f32 v13, v0, v13
	global_store_dword v[10:11], v13, off
.LBB0_1006:
	s_or_b64 exec, exec, s[12:13]
	s_waitcnt lgkmcnt(0)
	v_mul_f32_e32 v13, v56, v12
	s_nop 1
	v_mov_b32_dpp v14, v13 quad_perm:[1,0,3,2] row_mask:0xf bank_mask:0xf
	s_and_saveexec_b64 s[12:13], vcc
	s_cbranch_execz .LBB0_1008
	s_waitcnt lgkmcnt(0)
	v_cvt_pk_bf16_f32 v14, v13, v14
	global_store_dword v[10:11], v14, off offset:64
.LBB0_1008:
	s_or_b64 exec, exec, s[12:13]
	s_waitcnt lgkmcnt(0)
	v_mul_f32_e32 v14, v40, v12
	s_nop 1
	v_mov_b32_dpp v15, v14 quad_perm:[1,0,3,2] row_mask:0xf bank_mask:0xf
	s_and_saveexec_b64 s[12:13], vcc
	s_cbranch_execz .LBB0_1010
	s_waitcnt lgkmcnt(0)
	v_cvt_pk_bf16_f32 v15, v14, v15
	global_store_dword v[10:11], v15, off offset:128
.LBB0_1010:
	s_or_b64 exec, exec, s[12:13]
	v_mul_f32_e32 v12, v24, v12
	s_waitcnt lgkmcnt(0)
	s_nop 1
	v_mov_b32_dpp v15, v12 quad_perm:[1,0,3,2] row_mask:0xf bank_mask:0xf
	s_and_saveexec_b64 s[12:13], vcc
	s_cbranch_execz .LBB0_1012
	s_waitcnt lgkmcnt(0)
	v_cvt_pk_bf16_f32 v15, v12, v15
	global_store_dword v[10:11], v15, off offset:192
.LBB0_1012:
	s_or_b64 exec, exec, s[12:13]
	v_mul_f32_e32 v10, v13, v13
	v_fmac_f32_e32 v10, v0, v0
	v_fmac_f32_e32 v10, v14, v14
	v_fmac_f32_e32 v10, v12, v12
	s_nop 1
	v_mov_b32_dpp v0, v10 quad_perm:[1,0,3,2] row_mask:0xf bank_mask:0xf
	s_waitcnt lgkmcnt(0)
	v_add_f32_e32 v0, v10, v0
	ds_swizzle_b32 v10, v0 offset:swizzle(SWAP,2)
	s_waitcnt lgkmcnt(0)
	v_add_f32_e32 v0, v0, v10
	ds_swizzle_b32 v10, v0 offset:swizzle(SWAP,4)
	s_waitcnt lgkmcnt(0)
	v_add_f32_e32 v0, v0, v10
	ds_swizzle_b32 v10, v0 offset:swizzle(SWAP,8)
	s_waitcnt lgkmcnt(0)
	v_add_f32_e32 v0, v0, v10
	ds_swizzle_b32 v10, v0 offset:swizzle(SWAP,16)
	s_and_saveexec_b64 s[12:13], s[34:35]
	s_cbranch_execz .LBB0_1014
	s_waitcnt lgkmcnt(0)
	v_add_f32_e32 v12, v0, v10
	v_lshlrev_b32_e32 v0, 5, v6
	v_lshl_add_u64 v[10:11], s[86:87], 0, v[0:1]
	global_store_dword v[10:11], v12, off
.LBB0_1014:
	s_or_b64 exec, exec, s[12:13]
	v_rcp_f32_e32 v11, v7
	s_waitcnt lgkmcnt(0)
	v_add_u32_e32 v10, 17, v80
	v_lshl_add_u32 v0, v10, 12, v84
	v_lshl_add_u64 v[6:7], s[96:97], 0, v[0:1]
	v_mul_f32_e32 v0, v73, v11
	s_nop 1
	v_mov_b32_dpp v12, v0 quad_perm:[1,0,3,2] row_mask:0xf bank_mask:0xf
	s_and_saveexec_b64 s[12:13], vcc
	s_cbranch_execz .LBB0_1016
	s_waitcnt lgkmcnt(0)
	v_cvt_pk_bf16_f32 v12, v0, v12
	global_store_dword v[6:7], v12, off
.LBB0_1016:
	s_or_b64 exec, exec, s[12:13]
	s_waitcnt lgkmcnt(0)
	v_mul_f32_e32 v12, v57, v11
	s_nop 1
	v_mov_b32_dpp v13, v12 quad_perm:[1,0,3,2] row_mask:0xf bank_mask:0xf
	s_and_saveexec_b64 s[12:13], vcc
	s_cbranch_execz .LBB0_1018
	s_waitcnt lgkmcnt(0)
	v_cvt_pk_bf16_f32 v13, v12, v13
	global_store_dword v[6:7], v13, off offset:64
.LBB0_1018:
	s_or_b64 exec, exec, s[12:13]
	s_waitcnt lgkmcnt(0)
	v_mul_f32_e32 v13, v41, v11
	s_nop 1
	v_mov_b32_dpp v14, v13 quad_perm:[1,0,3,2] row_mask:0xf bank_mask:0xf
	s_and_saveexec_b64 s[12:13], vcc
	s_cbranch_execz .LBB0_1020
	s_waitcnt lgkmcnt(0)
	v_cvt_pk_bf16_f32 v14, v13, v14
	global_store_dword v[6:7], v14, off offset:128
; template <int K> __device__ __forceinline__ float shx(float v) { static_assert(K < 32, "use sum32"); return __int_as_float(__builtin_amdgcn_ds_swizzle(__float_as_int(v), (K << 10) | 0x1f)); }
; __device__ __forceinline__ int crow(int r, int hi) { return (r & 3) + 8 * (r >> 2) + 4 * hi; }
; template <class TIn, class TOut, int ost, bool HAS_SS>
; __device__ __forceinline__ void causal_swa_block(const BlockRef<TIn, TOut>& cur_, const BlockRef<TIn, TOut>& nxt_, int skv, int W, char* lds, Seam<TIn>& S, int cbl  ) {
;     ...
;     for (int r = 0; r < 16; ++r) rli[r] = __builtin_amdgcn_rcpf(li_l[crow(r, hi)]);
;     int r32e = r32, hie = hi; asm volatile("" : "+v"(r32e), "+v"(hie));
;     char* Ob = (char*)cur.O; const unsigned ob0 = (unsigned)((wid * QBLK + 4 * hie) * ost + r32e) * 2u;
; #pragma unroll
;     for (int r = 0; r < 16; ++r) { const unsigned rowoff = ob0 + (unsigned)(((r & 3) + 8 * (r >> 2)) * ost * 2); float ss_ = 0.f;
; #pragma unroll
;         for (int d0 = 0; d0 < 4; ++d0) { const float v = o[d0][r] * rli[r]; ss_ += v * v;
;             const float vn = shx<1>(v);
;             if ((r32e & 1) == 0) *(unsigned*)(Ob + rowoff + d0 * 64) = cvtpk(v, vn); }
;         if (HAS_SS) { ss_ += shx<1>(ss_); ss_ += shx<2>(ss_); ss_ += shx<4>(ss_); ss_ += shx<8>(ss_); ss_ += shx<16>(ss_);
;             if (r32e == 0) *(float*)((char*)cur.SS + (unsigned)(wid * QBLK + 4 * hie + (r & 3) + 8 * (r >> 2)) * 32u) = ss_; }
.LBB0_1020:
	s_or_b64 exec, exec, s[12:13]
	v_mul_f32_e32 v11, v25, v11
	s_waitcnt lgkmcnt(0)
	s_nop 1
	v_mov_b32_dpp v14, v11 quad_perm:[1,0,3,2] row_mask:0xf bank_mask:0xf
	s_and_saveexec_b64 s[12:13], vcc
	s_cbranch_execz .LBB0_1022
	s_waitcnt lgkmcnt(0)
	v_cvt_pk_bf16_f32 v14, v11, v14
	global_store_dword v[6:7], v14, off offset:192
.LBB0_1022:
	s_or_b64 exec, exec, s[12:13]
	v_mul_f32_e32 v6, v12, v12
	v_fmac_f32_e32 v6, v0, v0
	v_fmac_f32_e32 v6, v13, v13
	v_fmac_f32_e32 v6, v11, v11
	s_nop 1
	v_mov_b32_dpp v0, v6 quad_perm:[1,0,3,2] row_mask:0xf bank_mask:0xf
	s_waitcnt lgkmcnt(0)
	v_add_f32_e32 v0, v6, v0
	ds_swizzle_b32 v6, v0 offset:swizzle(SWAP,2)
	s_waitcnt lgkmcnt(0)
	v_add_f32_e32 v0, v0, v6
	ds_swizzle_b32 v6, v0 offset:swizzle(SWAP,4)
	s_waitcnt lgkmcnt(0)
	v_add_f32_e32 v0, v0, v6
	ds_swizzle_b32 v6, v0 offset:swizzle(SWAP,8)
	s_waitcnt lgkmcnt(0)
	v_add_f32_e32 v0, v0, v6
	ds_swizzle_b32 v6, v0 offset:swizzle(SWAP,16)
	s_and_saveexec_b64 s[12:13], s[34:35]
	s_cbranch_execz .LBB0_1024
	s_waitcnt lgkmcnt(0)
	v_add_f32_e32 v11, v0, v6
	v_lshlrev_b32_e32 v0, 5, v10
	v_lshl_add_u64 v[6:7], s[86:87], 0, v[0:1]
	global_store_dword v[6:7], v11, off
.LBB0_1024:
	s_or_b64 exec, exec, s[12:13]
	v_rcp_f32_e32 v10, v8
	v_add_u32_e32 v8, 18, v80
	v_lshl_add_u32 v0, v8, 12, v84
	s_waitcnt lgkmcnt(0)
	v_lshl_add_u64 v[6:7], s[96:97], 0, v[0:1]
	v_mul_f32_e32 v0, v74, v10
	s_nop 1
	v_mov_b32_dpp v11, v0 quad_perm:[1,0,3,2] row_mask:0xf bank_mask:0xf
	s_and_saveexec_b64 s[12:13], vcc
	s_cbranch_execz .LBB0_1026
	s_waitcnt lgkmcnt(0)
	v_cvt_pk_bf16_f32 v11, v0, v11
	global_store_dword v[6:7], v11, off
.LBB0_1026:
	s_or_b64 exec, exec, s[12:13]
	s_waitcnt lgkmcnt(0)
	v_mul_f32_e32 v11, v58, v10
	s_nop 1
	v_mov_b32_dpp v12, v11 quad_perm:[1,0,3,2] row_mask:0xf bank_mask:0xf
	s_and_saveexec_b64 s[12:13], vcc
	s_cbranch_execz .LBB0_1028
	s_waitcnt lgkmcnt(0)
	v_cvt_pk_bf16_f32 v12, v11, v12
	global_store_dword v[6:7], v12, off offset:64
.LBB0_1028:
	s_or_b64 exec, exec, s[12:13]
	s_waitcnt lgkmcnt(0)
	v_mul_f32_e32 v12, v42, v10
	s_nop 1
	v_mov_b32_dpp v13, v12 quad_perm:[1,0,3,2] row_mask:0xf bank_mask:0xf
	s_and_saveexec_b64 s[12:13], vcc
	s_cbranch_execz .LBB0_1030
	s_waitcnt lgkmcnt(0)
	v_cvt_pk_bf16_f32 v13, v12, v13
	global_store_dword v[6:7], v13, off offset:128
.LBB0_1030:
	s_or_b64 exec, exec, s[12:13]
	v_mul_f32_e32 v10, v26, v10
	s_waitcnt lgkmcnt(0)
	s_nop 1
	v_mov_b32_dpp v13, v10 quad_perm:[1,0,3,2] row_mask:0xf bank_mask:0xf
	s_and_saveexec_b64 s[12:13], vcc
	s_cbranch_execz .LBB0_1032
	s_waitcnt lgkmcnt(0)
	v_cvt_pk_bf16_f32 v13, v10, v13
	global_store_dword v[6:7], v13, off offset:192
.LBB0_1032:
	s_or_b64 exec, exec, s[12:13]
	v_mul_f32_e32 v6, v11, v11
	v_fmac_f32_e32 v6, v0, v0
	v_fmac_f32_e32 v6, v12, v12
	v_fmac_f32_e32 v6, v10, v10
	s_nop 1
	v_mov_b32_dpp v0, v6 quad_perm:[1,0,3,2] row_mask:0xf bank_mask:0xf
	s_waitcnt lgkmcnt(0)
	v_add_f32_e32 v0, v6, v0
	ds_swizzle_b32 v6, v0 offset:swizzle(SWAP,2)
	s_waitcnt lgkmcnt(0)
	v_add_f32_e32 v0, v0, v6
	ds_swizzle_b32 v6, v0 offset:swizzle(SWAP,4)
	s_waitcnt lgkmcnt(0)
	v_add_f32_e32 v0, v0, v6
	ds_swizzle_b32 v6, v0 offset:swizzle(SWAP,8)
	s_waitcnt lgkmcnt(0)
	v_add_f32_e32 v0, v0, v6
	ds_swizzle_b32 v6, v0 offset:swizzle(SWAP,16)
	s_and_saveexec_b64 s[12:13], s[34:35]
	s_cbranch_execz .LBB0_1034
	s_waitcnt lgkmcnt(0)
	v_add_f32_e32 v10, v0, v6
	v_lshlrev_b32_e32 v0, 5, v8
	v_lshl_add_u64 v[6:7], s[86:87], 0, v[0:1]
	global_store_dword v[6:7], v10, off
.LBB0_1034:
	s_or_b64 exec, exec, s[12:13]
	v_rcp_f32_e32 v9, v9
	v_add_u32_e32 v8, 19, v80
	v_lshl_add_u32 v0, v8, 12, v84
	s_waitcnt lgkmcnt(0)
	v_lshl_add_u64 v[6:7], s[96:97], 0, v[0:1]
	v_mul_f32_e32 v0, v75, v9
	s_nop 1
	v_mov_b32_dpp v10, v0 quad_perm:[1,0,3,2] row_mask:0xf bank_mask:0xf
	s_and_saveexec_b64 s[12:13], vcc
	s_cbranch_execz .LBB0_1036
	s_waitcnt lgkmcnt(0)
	v_cvt_pk_bf16_f32 v10, v0, v10
	global_store_dword v[6:7], v10, off
.LBB0_1036:
	s_or_b64 exec, exec, s[12:13]
	s_waitcnt lgkmcnt(0)
	v_mul_f32_e32 v10, v59, v9
	s_nop 1
	v_mov_b32_dpp v11, v10 quad_perm:[1,0,3,2] row_mask:0xf bank_mask:0xf
	s_and_saveexec_b64 s[12:13], vcc
	s_cbranch_execz .LBB0_1038
	s_waitcnt lgkmcnt(0)
	v_cvt_pk_bf16_f32 v11, v10, v11
	global_store_dword v[6:7], v11, off offset:64
.LBB0_1038:
	s_or_b64 exec, exec, s[12:13]
	s_waitcnt lgkmcnt(0)
	v_mul_f32_e32 v11, v43, v9
	s_nop 1
	v_mov_b32_dpp v12, v11 quad_perm:[1,0,3,2] row_mask:0xf bank_mask:0xf
	s_and_saveexec_b64 s[12:13], vcc
	s_cbranch_execz .LBB0_1040
	s_waitcnt lgkmcnt(0)
	v_cvt_pk_bf16_f32 v12, v11, v12
	global_store_dword v[6:7], v12, off offset:128
.LBB0_1040:
	s_or_b64 exec, exec, s[12:13]
	v_mul_f32_e32 v9, v27, v9
	s_waitcnt lgkmcnt(0)
	s_nop 1
	v_mov_b32_dpp v12, v9 quad_perm:[1,0,3,2] row_mask:0xf bank_mask:0xf
	s_and_saveexec_b64 s[12:13], vcc
	s_cbranch_execz .LBB0_1042
	s_waitcnt lgkmcnt(0)
	v_cvt_pk_bf16_f32 v12, v9, v12
	global_store_dword v[6:7], v12, off offset:192
.LBB0_1042:
	s_or_b64 exec, exec, s[12:13]
	v_mul_f32_e32 v6, v10, v10
	v_fmac_f32_e32 v6, v0, v0
	v_fmac_f32_e32 v6, v11, v11
	v_fmac_f32_e32 v6, v9, v9
	s_nop 1
	v_mov_b32_dpp v0, v6 quad_perm:[1,0,3,2] row_mask:0xf bank_mask:0xf
	s_waitcnt lgkmcnt(0)
	v_add_f32_e32 v0, v6, v0
	ds_swizzle_b32 v6, v0 offset:swizzle(SWAP,2)
	s_waitcnt lgkmcnt(0)
	v_add_f32_e32 v0, v0, v6
	ds_swizzle_b32 v6, v0 offset:swizzle(SWAP,4)
	s_waitcnt lgkmcnt(0)
	v_add_f32_e32 v0, v0, v6
	ds_swizzle_b32 v6, v0 offset:swizzle(SWAP,8)
	s_waitcnt lgkmcnt(0)
	v_add_f32_e32 v0, v0, v6
	ds_swizzle_b32 v6, v0 offset:swizzle(SWAP,16)
	s_and_saveexec_b64 s[12:13], s[34:35]
	s_cbranch_execz .LBB0_1044
	s_waitcnt lgkmcnt(0)
	v_add_f32_e32 v9, v0, v6
	v_lshlrev_b32_e32 v0, 5, v8
	v_lshl_add_u64 v[6:7], s[86:87], 0, v[0:1]
	global_store_dword v[6:7], v9, off
; template <int K> __device__ __forceinline__ float shx(float v) { static_assert(K < 32, "use sum32"); return __int_as_float(__builtin_amdgcn_ds_swizzle(__float_as_int(v), (K << 10) | 0x1f)); }
; __device__ __forceinline__ int crow(int r, int hi) { return (r & 3) + 8 * (r >> 2) + 4 * hi; }
; template <class TIn, class TOut, int ost, bool HAS_SS>
; __device__ __forceinline__ void causal_swa_block(const BlockRef<TIn, TOut>& cur_, const BlockRef<TIn, TOut>& nxt_, int skv, int W, char* lds, Seam<TIn>& S, int cbl  ) {
;     ...
;     for (int r = 0; r < 16; ++r) rli[r] = __builtin_amdgcn_rcpf(li_l[crow(r, hi)]);
;     int r32e = r32, hie = hi; asm volatile("" : "+v"(r32e), "+v"(hie));
;     char* Ob = (char*)cur.O; const unsigned ob0 = (unsigned)((wid * QBLK + 4 * hie) * ost + r32e) * 2u;
; #pragma unroll
;     for (int r = 0; r < 16; ++r) { const unsigned rowoff = ob0 + (unsigned)(((r & 3) + 8 * (r >> 2)) * ost * 2); float ss_ = 0.f;
; #pragma unroll
;         for (int d0 = 0; d0 < 4; ++d0) { const float v = o[d0][r] * rli[r]; ss_ += v * v;
;             const float vn = shx<1>(v);
;             if ((r32e & 1) == 0) *(unsigned*)(Ob + rowoff + d0 * 64) = cvtpk(v, vn); }
;         if (HAS_SS) { ss_ += shx<1>(ss_); ss_ += shx<2>(ss_); ss_ += shx<4>(ss_); ss_ += shx<8>(ss_); ss_ += shx<16>(ss_);
;             if (r32e == 0) *(float*)((char*)cur.SS + (unsigned)(wid * QBLK + 4 * hie + (r & 3) + 8 * (r >> 2)) * 32u) = ss_; }
.LBB0_1044:
	s_or_b64 exec, exec, s[12:13]
	v_rcp_f32_e32 v8, v2
	v_add_u32_e32 v2, 24, v80
	v_lshl_add_u32 v0, v2, 12, v84
	s_waitcnt lgkmcnt(0)
	v_lshl_add_u64 v[6:7], s[96:97], 0, v[0:1]
	v_mul_f32_e32 v0, v76, v8
	s_nop 1
	v_mov_b32_dpp v9, v0 quad_perm:[1,0,3,2] row_mask:0xf bank_mask:0xf
	s_and_saveexec_b64 s[12:13], vcc
	s_cbranch_execz .LBB0_1046
	s_waitcnt lgkmcnt(0)
	v_cvt_pk_bf16_f32 v9, v0, v9
	global_store_dword v[6:7], v9, off
.LBB0_1046:
	s_or_b64 exec, exec, s[12:13]
	s_waitcnt lgkmcnt(0)
	v_mul_f32_e32 v9, v60, v8
	s_nop 1
	v_mov_b32_dpp v10, v9 quad_perm:[1,0,3,2] row_mask:0xf bank_mask:0xf
	s_and_saveexec_b64 s[12:13], vcc
	s_cbranch_execz .LBB0_1048
	s_waitcnt lgkmcnt(0)
	v_cvt_pk_bf16_f32 v10, v9, v10
	global_store_dword v[6:7], v10, off offset:64
.LBB0_1048:
	s_or_b64 exec, exec, s[12:13]
	s_waitcnt lgkmcnt(0)
	v_mul_f32_e32 v10, v44, v8
	s_nop 1
	v_mov_b32_dpp v11, v10 quad_perm:[1,0,3,2] row_mask:0xf bank_mask:0xf
	s_and_saveexec_b64 s[12:13], vcc
	s_cbranch_execz .LBB0_1050
	s_waitcnt lgkmcnt(0)
	v_cvt_pk_bf16_f32 v11, v10, v11
	global_store_dword v[6:7], v11, off offset:128
.LBB0_1050:
	s_or_b64 exec, exec, s[12:13]
	v_mul_f32_e32 v8, v28, v8
	s_waitcnt lgkmcnt(0)
	s_nop 1
	v_mov_b32_dpp v11, v8 quad_perm:[1,0,3,2] row_mask:0xf bank_mask:0xf
	s_and_saveexec_b64 s[12:13], vcc
	s_cbranch_execz .LBB0_1052
	s_waitcnt lgkmcnt(0)
	v_cvt_pk_bf16_f32 v11, v8, v11
	global_store_dword v[6:7], v11, off offset:192
.LBB0_1052:
	s_or_b64 exec, exec, s[12:13]
	v_mul_f32_e32 v6, v9, v9
	v_fmac_f32_e32 v6, v0, v0
	v_fmac_f32_e32 v6, v10, v10
	v_fmac_f32_e32 v6, v8, v8
	s_nop 1
	v_mov_b32_dpp v0, v6 quad_perm:[1,0,3,2] row_mask:0xf bank_mask:0xf
	s_waitcnt lgkmcnt(0)
	v_add_f32_e32 v0, v6, v0
	ds_swizzle_b32 v6, v0 offset:swizzle(SWAP,2)
	s_waitcnt lgkmcnt(0)
	v_add_f32_e32 v0, v0, v6
	ds_swizzle_b32 v6, v0 offset:swizzle(SWAP,4)
	s_waitcnt lgkmcnt(0)
	v_add_f32_e32 v0, v0, v6
	ds_swizzle_b32 v6, v0 offset:swizzle(SWAP,8)
	s_waitcnt lgkmcnt(0)
	v_add_f32_e32 v0, v0, v6
	ds_swizzle_b32 v6, v0 offset:swizzle(SWAP,16)
	s_and_saveexec_b64 s[12:13], s[34:35]
	s_cbranch_execz .LBB0_1054
	s_waitcnt lgkmcnt(0)
	v_add_f32_e32 v8, v0, v6
	v_lshlrev_b32_e32 v0, 5, v2
	v_lshl_add_u64 v[6:7], s[86:87], 0, v[0:1]
	global_store_dword v[6:7], v8, off
.LBB0_1054:
	s_or_b64 exec, exec, s[12:13]
	v_rcp_f32_e32 v7, v3
	s_waitcnt lgkmcnt(0)
	v_add_u32_e32 v6, 25, v80
	v_lshl_add_u32 v0, v6, 12, v84
	v_lshl_add_u64 v[2:3], s[96:97], 0, v[0:1]
	v_mul_f32_e32 v0, v77, v7
	s_nop 1
	v_mov_b32_dpp v8, v0 quad_perm:[1,0,3,2] row_mask:0xf bank_mask:0xf
	s_and_saveexec_b64 s[12:13], vcc
	s_cbranch_execz .LBB0_1056
	s_waitcnt lgkmcnt(0)
	v_cvt_pk_bf16_f32 v8, v0, v8
	global_store_dword v[2:3], v8, off
.LBB0_1056:
	s_or_b64 exec, exec, s[12:13]
	s_waitcnt lgkmcnt(0)
	v_mul_f32_e32 v8, v61, v7
	s_nop 1
	v_mov_b32_dpp v9, v8 quad_perm:[1,0,3,2] row_mask:0xf bank_mask:0xf
	s_and_saveexec_b64 s[12:13], vcc
	s_cbranch_execz .LBB0_1058
	s_waitcnt lgkmcnt(0)
	v_cvt_pk_bf16_f32 v9, v8, v9
	global_store_dword v[2:3], v9, off offset:64
.LBB0_1058:
	s_or_b64 exec, exec, s[12:13]
	s_waitcnt lgkmcnt(0)
	v_mul_f32_e32 v9, v45, v7
	s_nop 1
	v_mov_b32_dpp v10, v9 quad_perm:[1,0,3,2] row_mask:0xf bank_mask:0xf
	s_and_saveexec_b64 s[12:13], vcc
	s_cbranch_execz .LBB0_1060
	s_waitcnt lgkmcnt(0)
	v_cvt_pk_bf16_f32 v10, v9, v10
	global_store_dword v[2:3], v10, off offset:128
.LBB0_1060:
	s_or_b64 exec, exec, s[12:13]
	v_mul_f32_e32 v7, v29, v7
	s_waitcnt lgkmcnt(0)
	s_nop 1
	v_mov_b32_dpp v10, v7 quad_perm:[1,0,3,2] row_mask:0xf bank_mask:0xf
	s_and_saveexec_b64 s[12:13], vcc
	s_cbranch_execz .LBB0_1062
	s_waitcnt lgkmcnt(0)
	v_cvt_pk_bf16_f32 v10, v7, v10
	global_store_dword v[2:3], v10, off offset:192
.LBB0_1062:
	s_or_b64 exec, exec, s[12:13]
	v_mul_f32_e32 v2, v8, v8
	v_fmac_f32_e32 v2, v0, v0
	v_fmac_f32_e32 v2, v9, v9
	v_fmac_f32_e32 v2, v7, v7
	s_nop 1
	v_mov_b32_dpp v0, v2 quad_perm:[1,0,3,2] row_mask:0xf bank_mask:0xf
	s_waitcnt lgkmcnt(0)
	v_add_f32_e32 v0, v2, v0
	ds_swizzle_b32 v2, v0 offset:swizzle(SWAP,2)
	s_waitcnt lgkmcnt(0)
	v_add_f32_e32 v0, v0, v2
	ds_swizzle_b32 v2, v0 offset:swizzle(SWAP,4)
	s_waitcnt lgkmcnt(0)
	v_add_f32_e32 v0, v0, v2
	ds_swizzle_b32 v2, v0 offset:swizzle(SWAP,8)
	s_waitcnt lgkmcnt(0)
	v_add_f32_e32 v0, v0, v2
	ds_swizzle_b32 v2, v0 offset:swizzle(SWAP,16)
	s_and_saveexec_b64 s[12:13], s[34:35]
	s_cbranch_execz .LBB0_1064
	s_waitcnt lgkmcnt(0)
	v_add_f32_e32 v7, v0, v2
	v_lshlrev_b32_e32 v0, 5, v6
	v_lshl_add_u64 v[2:3], s[86:87], 0, v[0:1]
	global_store_dword v[2:3], v7, off
; template <int K> __device__ __forceinline__ float shx(float v) { static_assert(K < 32, "use sum32"); return __int_as_float(__builtin_amdgcn_ds_swizzle(__float_as_int(v), (K << 10) | 0x1f)); }
; __device__ __forceinline__ int crow(int r, int hi) { return (r & 3) + 8 * (r >> 2) + 4 * hi; }
; template <class TIn, class TOut, int ost, bool HAS_SS>
; __device__ __forceinline__ void causal_swa_block(const BlockRef<TIn, TOut>& cur_, const BlockRef<TIn, TOut>& nxt_, int skv, int W, char* lds, Seam<TIn>& S, int cbl  ) {
;     ...
;     for (int r = 0; r < 16; ++r) rli[r] = __builtin_amdgcn_rcpf(li_l[crow(r, hi)]);
;     int r32e = r32, hie = hi; asm volatile("" : "+v"(r32e), "+v"(hie));
;     char* Ob = (char*)cur.O; const unsigned ob0 = (unsigned)((wid * QBLK + 4 * hie) * ost + r32e) * 2u;
; #pragma unroll
;     for (int r = 0; r < 16; ++r) { const unsigned rowoff = ob0 + (unsigned)(((r & 3) + 8 * (r >> 2)) * ost * 2); float ss_ = 0.f;
; #pragma unroll
;         for (int d0 = 0; d0 < 4; ++d0) { const float v = o[d0][r] * rli[r]; ss_ += v * v;
;             const float vn = shx<1>(v);
;             if ((r32e & 1) == 0) *(unsigned*)(Ob + rowoff + d0 * 64) = cvtpk(v, vn); }
;         if (HAS_SS) { ss_ += shx<1>(ss_); ss_ += shx<2>(ss_); ss_ += shx<4>(ss_); ss_ += shx<8>(ss_); ss_ += shx<16>(ss_);
;             if (r32e == 0) *(float*)((char*)cur.SS + (unsigned)(wid * QBLK + 4 * hie + (r & 3) + 8 * (r >> 2)) * 32u) = ss_; }
.LBB0_1064:
	s_or_b64 exec, exec, s[12:13]
	v_rcp_f32_e32 v6, v4
	v_add_u32_e32 v4, 26, v80
	v_lshl_add_u32 v0, v4, 12, v84
	s_waitcnt lgkmcnt(0)
	v_lshl_add_u64 v[2:3], s[96:97], 0, v[0:1]
	v_mul_f32_e32 v0, v78, v6
	s_nop 1
	v_mov_b32_dpp v7, v0 quad_perm:[1,0,3,2] row_mask:0xf bank_mask:0xf
	s_and_saveexec_b64 s[12:13], vcc
	s_cbranch_execz .LBB0_1066
	s_waitcnt lgkmcnt(0)
	v_cvt_pk_bf16_f32 v7, v0, v7
	global_store_dword v[2:3], v7, off
.LBB0_1066:
	s_or_b64 exec, exec, s[12:13]
	s_waitcnt lgkmcnt(0)
	v_mul_f32_e32 v7, v62, v6
	s_nop 1
	v_mov_b32_dpp v8, v7 quad_perm:[1,0,3,2] row_mask:0xf bank_mask:0xf
	s_and_saveexec_b64 s[12:13], vcc
	s_cbranch_execz .LBB0_1068
	s_waitcnt lgkmcnt(0)
	v_cvt_pk_bf16_f32 v8, v7, v8
	global_store_dword v[2:3], v8, off offset:64
.LBB0_1068:
	s_or_b64 exec, exec, s[12:13]
	s_waitcnt lgkmcnt(0)
	v_mul_f32_e32 v8, v46, v6
	s_nop 1
	v_mov_b32_dpp v9, v8 quad_perm:[1,0,3,2] row_mask:0xf bank_mask:0xf
	s_and_saveexec_b64 s[12:13], vcc
	s_cbranch_execz .LBB0_1070
	s_waitcnt lgkmcnt(0)
	v_cvt_pk_bf16_f32 v9, v8, v9
	global_store_dword v[2:3], v9, off offset:128
.LBB0_1070:
	s_or_b64 exec, exec, s[12:13]
	v_mul_f32_e32 v6, v30, v6
	s_waitcnt lgkmcnt(0)
	s_nop 1
	v_mov_b32_dpp v9, v6 quad_perm:[1,0,3,2] row_mask:0xf bank_mask:0xf
	s_and_saveexec_b64 s[12:13], vcc
	s_cbranch_execz .LBB0_1072
	s_waitcnt lgkmcnt(0)
	v_cvt_pk_bf16_f32 v9, v6, v9
	global_store_dword v[2:3], v9, off offset:192
.LBB0_1072:
	s_or_b64 exec, exec, s[12:13]
	v_mul_f32_e32 v2, v7, v7
	v_fmac_f32_e32 v2, v0, v0
	v_fmac_f32_e32 v2, v8, v8
	v_fmac_f32_e32 v2, v6, v6
	s_nop 1
	v_mov_b32_dpp v0, v2 quad_perm:[1,0,3,2] row_mask:0xf bank_mask:0xf
	s_waitcnt lgkmcnt(0)
	v_add_f32_e32 v0, v2, v0
	ds_swizzle_b32 v2, v0 offset:swizzle(SWAP,2)
	s_waitcnt lgkmcnt(0)
	v_add_f32_e32 v0, v0, v2
	ds_swizzle_b32 v2, v0 offset:swizzle(SWAP,4)
	s_waitcnt lgkmcnt(0)
	v_add_f32_e32 v0, v0, v2
	ds_swizzle_b32 v2, v0 offset:swizzle(SWAP,8)
	s_waitcnt lgkmcnt(0)
	v_add_f32_e32 v0, v0, v2
	ds_swizzle_b32 v2, v0 offset:swizzle(SWAP,16)
	s_and_saveexec_b64 s[12:13], s[34:35]
	s_cbranch_execz .LBB0_1074
	s_waitcnt lgkmcnt(0)
	v_add_f32_e32 v6, v0, v2
	v_lshlrev_b32_e32 v0, 5, v4
	v_lshl_add_u64 v[2:3], s[86:87], 0, v[0:1]
	global_store_dword v[2:3], v6, off
.LBB0_1074:
	s_or_b64 exec, exec, s[12:13]
	v_rcp_f32_e32 v6, v5
	s_nop 0
	v_mul_f32_e32 v5, v79, v6
	s_nop 1
	v_mov_b32_dpp v7, v5 quad_perm:[1,0,3,2] row_mask:0xf bank_mask:0xf
	v_add_u32_e32 v4, 27, v80
	v_lshl_add_u32 v0, v4, 12, v84
	s_waitcnt lgkmcnt(0)
	v_lshl_add_u64 v[2:3], s[96:97], 0, v[0:1]
	s_and_saveexec_b64 s[12:13], vcc
	s_cbranch_execz .LBB0_1076
	v_cvt_pk_bf16_f32 v0, v5, v7
	global_store_dword v[2:3], v0, off
.LBB0_1076:
	s_or_b64 exec, exec, s[12:13]
	v_mul_f32_e32 v0, v63, v6
	s_nop 1
	v_mov_b32_dpp v7, v0 quad_perm:[1,0,3,2] row_mask:0xf bank_mask:0xf
	s_and_saveexec_b64 s[12:13], vcc
	s_cbranch_execz .LBB0_1078
	s_waitcnt lgkmcnt(0)
	v_cvt_pk_bf16_f32 v7, v0, v7
	global_store_dword v[2:3], v7, off offset:64
.LBB0_1078:
	s_or_b64 exec, exec, s[12:13]
	s_waitcnt lgkmcnt(0)
	v_mul_f32_e32 v7, v47, v6
	s_nop 1
	v_mov_b32_dpp v8, v7 quad_perm:[1,0,3,2] row_mask:0xf bank_mask:0xf
	s_and_saveexec_b64 s[12:13], vcc
	s_cbranch_execz .LBB0_1080
	s_waitcnt lgkmcnt(0)
	v_cvt_pk_bf16_f32 v8, v7, v8
	global_store_dword v[2:3], v8, off offset:128
.LBB0_1080:
	s_or_b64 exec, exec, s[12:13]
	v_mul_f32_e32 v6, v31, v6
	s_waitcnt lgkmcnt(0)
	s_nop 1
	v_mov_b32_dpp v8, v6 quad_perm:[1,0,3,2] row_mask:0xf bank_mask:0xf
	s_and_saveexec_b64 s[12:13], vcc
	s_cbranch_execz .LBB0_1082
	s_waitcnt lgkmcnt(0)
	v_cvt_pk_bf16_f32 v8, v6, v8
	global_store_dword v[2:3], v8, off offset:192
.LBB0_1082:
	s_or_b64 exec, exec, s[12:13]
	v_mul_f32_e32 v0, v0, v0
	v_fmac_f32_e32 v0, v5, v5
	v_fmac_f32_e32 v0, v7, v7
	v_fmac_f32_e32 v0, v6, v6
	s_nop 1
	v_mov_b32_dpp v2, v0 quad_perm:[1,0,3,2] row_mask:0xf bank_mask:0xf
	s_waitcnt lgkmcnt(0)
	v_add_f32_e32 v0, v0, v2
	ds_swizzle_b32 v2, v0 offset:swizzle(SWAP,2)
	s_waitcnt lgkmcnt(0)
	v_add_f32_e32 v0, v0, v2
	ds_swizzle_b32 v2, v0 offset:swizzle(SWAP,4)
	s_waitcnt lgkmcnt(0)
	v_add_f32_e32 v0, v0, v2
	ds_swizzle_b32 v2, v0 offset:swizzle(SWAP,8)
	s_waitcnt lgkmcnt(0)
	v_add_f32_e32 v0, v0, v2
	ds_swizzle_b32 v2, v0 offset:swizzle(SWAP,16)
	s_and_saveexec_b64 s[12:13], s[34:35]
	s_cbranch_execz .LBB0_882
	s_waitcnt lgkmcnt(0)
	v_add_f32_e32 v5, v0, v2
	v_lshlrev_b32_e32 v0, 5, v4
	v_lshl_add_u64 v[2:3], s[86:87], 0, v[0:1]
	global_store_dword v[2:3], v5, off
	s_branch .LBB0_882

; template <int K> __device__ __forceinline__ float shx(float v) { static_assert(K < 32, "use sum32"); return __int_as_float(__builtin_amdgcn_ds_swizzle(__float_as_int(v), (K << 10) | 0x1f)); }
; __device__ __forceinline__ unsigned pk2(float lo, float hi) { return f2bf(lo) | (f2bf(hi) << 16); }
; __device__ __forceinline__ float bflo(unsigned w) { return __uint_as_float(w << 16); }
; __device__ __forceinline__ float bfhi(unsigned w) { return __uint_as_float(w & 0xffff0000u); }
; __global__ void __launch_bounds__(NTHR, LB2) hymba_fwd(Args a) {
;     ...
;         for (int p = 0; p < 8; ++p) { const unsigned row = (unsigned)(pm * 256 + p * 32 + (tid >> 4)), o = (row * 1024u + c8) * 2u;
;             const v4u hw = __builtin_nontemporal_load((const v4u*)((const char*)HL + o)), aw = __builtin_nontemporal_load((const v4u*)((const char*)AC + o)), gw = __builtin_nontemporal_load((const v4u*)((const char*)GG + o));
;             const f32x4 y0 = ((f32x4){bflo(hw.x), bfhi(hw.x), bflo(hw.y), bfhi(hw.y)} + (f32x4){bflo(aw.x), bfhi(aw.x), bflo(aw.y), bfhi(aw.y)} * hi0) * (f32x4){bflo(gw.x), bfhi(gw.x), bflo(gw.y), bfhi(gw.y)};
;             const f32x4 y1 = ((f32x4){bflo(hw.z), bfhi(hw.z), bflo(hw.w), bfhi(hw.w)} + (f32x4){bflo(aw.z), bfhi(aw.z), bflo(aw.w), bfhi(aw.w)} * hi1) * (f32x4){bflo(gw.z), bfhi(gw.z), bflo(gw.w), bfhi(gw.w)};
;             float ss = (y0.x * y0.x + y0.y * y0.y) + (y0.z * y0.z + y0.w * y0.w) + (y1.x * y1.x + y1.y * y1.y) + (y1.z * y1.z + y1.w * y1.w);
;             v4u ow; ow.x = pk2(y0.x, y0.y); ow.y = pk2(y0.z, y0.w); ow.z = pk2(y1.x, y1.y); ow.w = pk2(y1.z, y1.w);
;             *(v4u*)((char*)MIX + ((size_t)row * 2048 + 1024 + c8) * 2) = ow;
;             ss += shx<1>(ss); ss += shx<2>(ss); ss += shx<4>(ss); ss += shx<8>(ss);
;             if ((tid & 15) == 0) SSQL[row * 8 + nblk] = ss; } } }
.LBB0_1145:
	s_waitcnt lgkmcnt(0)
	global_load_dwordx4 v[0:3], v23, s[26:27] nt
	global_load_dwordx4 v[24:27], v23, s[28:29] nt
	global_load_dwordx4 v[28:31], v23, s[20:21] nt
	s_mov_b32 s0, 0xf000000
	s_waitcnt vmcnt(0)
	v_lshlrev_b32_e32 v32, 16, v0
	v_and_b32_e32 v33, 0xffff0000, v0
	v_lshlrev_b32_e32 v0, 16, v1
	v_and_b32_e32 v1, 0xffff0000, v1
	v_lshlrev_b32_e32 v34, 16, v24
	v_and_b32_e32 v35, 0xffff0000, v24
	v_lshlrev_b32_e32 v24, 16, v25
	v_and_b32_e32 v25, 0xffff0000, v25
	v_pk_fma_f32 v[32:33], v[6:7], v[34:35], v[32:33]
	v_pk_fma_f32 v[0:1], v[8:9], v[24:25], v[0:1]
	v_lshlrev_b32_e32 v24, 16, v28
	v_and_b32_e32 v25, 0xffff0000, v28
	v_lshlrev_b32_e32 v28, 16, v29
	v_and_b32_e32 v29, 0xffff0000, v29
	v_pk_mul_f32 v[0:1], v[0:1], v[28:29]
	v_pk_mul_f32 v[28:29], v[32:33], v[24:25]
	v_lshlrev_b32_e32 v24, 16, v2
	v_and_b32_e32 v25, 0xffff0000, v2
	v_lshlrev_b32_e32 v2, 16, v3
	v_and_b32_e32 v3, 0xffff0000, v3
	v_lshlrev_b32_e32 v32, 16, v26
	v_and_b32_e32 v33, 0xffff0000, v26
	v_lshlrev_b32_e32 v26, 16, v27
	v_and_b32_e32 v27, 0xffff0000, v27
	v_pk_fma_f32 v[24:25], v[10:11], v[32:33], v[24:25]
	v_pk_fma_f32 v[2:3], v[12:13], v[26:27], v[2:3]
	v_lshlrev_b32_e32 v26, 16, v30
	v_and_b32_e32 v27, 0xffff0000, v30
	v_pk_mul_f32 v[26:27], v[24:25], v[26:27]
	v_mul_f32_e32 v24, v29, v29
	v_mul_f32_e32 v25, v1, v1
	v_fmac_f32_e32 v24, v28, v28
	v_fmac_f32_e32 v25, v0, v0
	v_lshlrev_b32_e32 v30, 16, v31
	v_and_b32_e32 v31, 0xffff0000, v31
	v_add_f32_e32 v24, v24, v25
	v_mul_f32_e32 v25, v27, v27
	v_pk_mul_f32 v[2:3], v[2:3], v[30:31]
	v_fmac_f32_e32 v25, v26, v26
	v_add_f32_e32 v24, v25, v24
	v_mul_f32_e32 v25, v3, v3
	v_fmac_f32_e32 v25, v2, v2
	v_add_f32_e32 v24, v25, v24
	v_and_b32_sdwa v25, v0, v21 dst_sel:DWORD dst_unused:UNUSED_PAD src0_sel:WORD_1 src1_sel:DWORD
	v_and_b32_sdwa v30, v28, v21 dst_sel:DWORD dst_unused:UNUSED_PAD src0_sel:WORD_1 src1_sel:DWORD
	v_add3_u32 v28, v28, v30, s4
	v_add3_u32 v0, v0, v25, s4
	v_and_b32_sdwa v25, v1, v21 dst_sel:DWORD dst_unused:UNUSED_PAD src0_sel:WORD_1 src1_sel:DWORD
	v_and_b32_sdwa v30, v29, v21 dst_sel:DWORD dst_unused:UNUSED_PAD src0_sel:WORD_1 src1_sel:DWORD
	v_add3_u32 v1, v1, v25, s4
	v_add3_u32 v25, v29, v30, s4
	v_and_b32_e32 v1, 0xffff0000, v1
	v_and_b32_e32 v25, 0xffff0000, v25
	v_or_b32_sdwa v1, v1, v0 dst_sel:DWORD dst_unused:UNUSED_PAD src0_sel:DWORD src1_sel:WORD_1
	v_or_b32_sdwa v0, v25, v28 dst_sel:DWORD dst_unused:UNUSED_PAD src0_sel:DWORD src1_sel:WORD_1
	v_and_b32_sdwa v25, v2, v21 dst_sel:DWORD dst_unused:UNUSED_PAD src0_sel:WORD_1 src1_sel:DWORD
	v_and_b32_sdwa v28, v26, v21 dst_sel:DWORD dst_unused:UNUSED_PAD src0_sel:WORD_1 src1_sel:DWORD
	v_add3_u32 v26, v26, v28, s4
	v_add3_u32 v2, v2, v25, s4
	v_and_b32_sdwa v25, v3, v21 dst_sel:DWORD dst_unused:UNUSED_PAD src0_sel:WORD_1 src1_sel:DWORD
	v_and_b32_sdwa v28, v27, v21 dst_sel:DWORD dst_unused:UNUSED_PAD src0_sel:WORD_1 src1_sel:DWORD
	v_add3_u32 v3, v3, v25, s4
	v_add3_u32 v25, v27, v28, s4
	v_and_b32_e32 v3, 0xffff0000, v3
	v_and_b32_e32 v25, 0xffff0000, v25
	v_or_b32_sdwa v3, v3, v2 dst_sel:DWORD dst_unused:UNUSED_PAD src0_sel:DWORD src1_sel:WORD_1
	v_or_b32_sdwa v2, v25, v26 dst_sel:DWORD dst_unused:UNUSED_PAD src0_sel:DWORD src1_sel:WORD_1
	v_lshlrev_b64 v[26:27], 12, v[4:5]
	v_lshl_add_u64 v[26:27], v[14:15], 0, v[26:27]
	v_add_co_u32_e32 v26, vcc, s0, v26
	s_nop 1
	v_addc_co_u32_e32 v27, vcc, 0, v27, vcc
	global_store_dwordx4 v[26:27], v[0:3], off offset:2048
	s_nop 1
	v_mov_b32_dpp v0, v24 quad_perm:[1,0,3,2] row_mask:0xf bank_mask:0xf
	s_waitcnt lgkmcnt(0)
	v_add_f32_e32 v0, v24, v0
	ds_swizzle_b32 v1, v0 offset:swizzle(SWAP,2)
	s_waitcnt lgkmcnt(0)
	v_add_f32_e32 v0, v0, v1
	ds_swizzle_b32 v1, v0 offset:swizzle(SWAP,4)
	s_waitcnt lgkmcnt(0)
	v_add_f32_e32 v2, v0, v1
	ds_swizzle_b32 v3, v2 offset:swizzle(SWAP,8)
	v_add_u32_e32 v0, s7, v22
	s_and_saveexec_b64 s[0:1], s[34:35]
	s_cbranch_execz .LBB0_1147
	v_mov_b32_e32 v1, v5
	v_lshl_add_u64 v[24:25], v[0:1], 2, s[24:25]
	s_waitcnt lgkmcnt(0)
	v_add_f32_e32 v1, v2, v3
	global_store_dword v[24:25], v1, off
; template <int K> __device__ __forceinline__ float shx(float v) { static_assert(K < 32, "use sum32"); return __int_as_float(__builtin_amdgcn_ds_swizzle(__float_as_int(v), (K << 10) | 0x1f)); }
; __device__ __forceinline__ unsigned pk2(float lo, float hi) { return f2bf(lo) | (f2bf(hi) << 16); }
; __device__ __forceinline__ float bflo(unsigned w) { return __uint_as_float(w << 16); }
; __device__ __forceinline__ float bfhi(unsigned w) { return __uint_as_float(w & 0xffff0000u); }
; __global__ void __launch_bounds__(NTHR, LB2) hymba_fwd(Args a) {
;     ...
;         for (int p = 0; p < 8; ++p) { const unsigned row = (unsigned)(pm * 256 + p * 32 + (tid >> 4)), o = (row * 1024u + c8) * 2u;
;             const v4u hw = __builtin_nontemporal_load((const v4u*)((const char*)HL + o)), aw = __builtin_nontemporal_load((const v4u*)((const char*)AC + o)), gw = __builtin_nontemporal_load((const v4u*)((const char*)GG + o));
;             const f32x4 y0 = ((f32x4){bflo(hw.x), bfhi(hw.x), bflo(hw.y), bfhi(hw.y)} + (f32x4){bflo(aw.x), bfhi(aw.x), bflo(aw.y), bfhi(aw.y)} * hi0) * (f32x4){bflo(gw.x), bfhi(gw.x), bflo(gw.y), bfhi(gw.y)};
;             const f32x4 y1 = ((f32x4){bflo(hw.z), bfhi(hw.z), bflo(hw.w), bfhi(hw.w)} + (f32x4){bflo(aw.z), bfhi(aw.z), bflo(aw.w), bfhi(aw.w)} * hi1) * (f32x4){bflo(gw.z), bfhi(gw.z), bflo(gw.w), bfhi(gw.w)};
;             float ss = (y0.x * y0.x + y0.y * y0.y) + (y0.z * y0.z + y0.w * y0.w) + (y1.x * y1.x + y1.y * y1.y) + (y1.z * y1.z + y1.w * y1.w);
;             v4u ow; ow.x = pk2(y0.x, y0.y); ow.y = pk2(y0.z, y0.w); ow.z = pk2(y1.x, y1.y); ow.w = pk2(y1.z, y1.w);
;             *(v4u*)((char*)MIX + ((size_t)row * 2048 + 1024 + c8) * 2) = ow;
;             ss += shx<1>(ss); ss += shx<2>(ss); ss += shx<4>(ss); ss += shx<8>(ss);
;             if ((tid & 15) == 0) SSQL[row * 8 + nblk] = ss; } } }
.LBB0_1147:
	s_or_b64 exec, exec, s[0:1]
	v_add_u32_e32 v1, 0x10000, v23
	global_load_dwordx4 v[24:27], v1, s[26:27] nt
	global_load_dwordx4 v[28:31], v1, s[28:29] nt
	global_load_dwordx4 v[32:35], v1, s[20:21] nt
	v_add_u32_e32 v2, 32, v4
	s_waitcnt vmcnt(2)
	v_lshlrev_b32_e32 v36, 16, v24
	v_and_b32_e32 v37, 0xffff0000, v24
	v_lshlrev_b32_e32 v24, 16, v25
	v_and_b32_e32 v25, 0xffff0000, v25
	s_waitcnt vmcnt(1)
	v_lshlrev_b32_e32 v38, 16, v28
	v_and_b32_e32 v39, 0xffff0000, v28
	v_lshlrev_b32_e32 v28, 16, v29
	v_and_b32_e32 v29, 0xffff0000, v29
	v_pk_fma_f32 v[36:37], v[6:7], v[38:39], v[36:37]
	v_pk_fma_f32 v[24:25], v[8:9], v[28:29], v[24:25]
	s_waitcnt vmcnt(0)
	v_lshlrev_b32_e32 v28, 16, v32
	v_and_b32_e32 v29, 0xffff0000, v32
	v_lshlrev_b32_e32 v32, 16, v33
	v_and_b32_e32 v33, 0xffff0000, v33
	v_pk_mul_f32 v[24:25], v[24:25], v[32:33]
	v_pk_mul_f32 v[28:29], v[36:37], v[28:29]
	v_lshlrev_b32_e32 v32, 16, v26
	v_and_b32_e32 v33, 0xffff0000, v26
	v_lshlrev_b32_e32 v26, 16, v27
	v_and_b32_e32 v27, 0xffff0000, v27
	v_lshlrev_b32_e32 v36, 16, v30
	v_and_b32_e32 v37, 0xffff0000, v30
	v_lshlrev_b32_e32 v30, 16, v31
	v_and_b32_e32 v31, 0xffff0000, v31
	v_pk_fma_f32 v[32:33], v[10:11], v[36:37], v[32:33]
	v_pk_fma_f32 v[26:27], v[12:13], v[30:31], v[26:27]
	v_lshlrev_b32_e32 v30, 16, v34
	v_and_b32_e32 v31, 0xffff0000, v34
	v_mul_f32_e32 v1, v29, v29
	s_waitcnt lgkmcnt(0)
	v_mul_f32_e32 v3, v25, v25
	v_pk_mul_f32 v[30:31], v[32:33], v[30:31]
	v_fmac_f32_e32 v1, v28, v28
	v_fmac_f32_e32 v3, v24, v24
	v_lshlrev_b32_e32 v34, 16, v35
	v_and_b32_e32 v35, 0xffff0000, v35
	v_add_f32_e32 v1, v1, v3
	v_mul_f32_e32 v3, v31, v31
	v_pk_mul_f32 v[26:27], v[26:27], v[34:35]
	v_fmac_f32_e32 v3, v30, v30
	v_add_f32_e32 v1, v3, v1
	v_mul_f32_e32 v3, v27, v27
	v_fmac_f32_e32 v3, v26, v26
	v_add_f32_e32 v1, v3, v1
	v_and_b32_sdwa v3, v24, v21 dst_sel:DWORD dst_unused:UNUSED_PAD src0_sel:WORD_1 src1_sel:DWORD
	v_and_b32_sdwa v32, v28, v21 dst_sel:DWORD dst_unused:UNUSED_PAD src0_sel:WORD_1 src1_sel:DWORD
	v_add3_u32 v3, v24, v3, s4
	v_and_b32_sdwa v24, v25, v21 dst_sel:DWORD dst_unused:UNUSED_PAD src0_sel:WORD_1 src1_sel:DWORD
	v_add3_u32 v28, v28, v32, s4
	v_and_b32_sdwa v32, v29, v21 dst_sel:DWORD dst_unused:UNUSED_PAD src0_sel:WORD_1 src1_sel:DWORD
	v_add3_u32 v24, v25, v24, s4
	v_add3_u32 v25, v29, v32, s4
	v_and_b32_e32 v24, 0xffff0000, v24
	v_and_b32_e32 v29, 0xffff0000, v25
	v_or_b32_sdwa v25, v24, v3 dst_sel:DWORD dst_unused:UNUSED_PAD src0_sel:DWORD src1_sel:WORD_1
	v_and_b32_sdwa v3, v26, v21 dst_sel:DWORD dst_unused:UNUSED_PAD src0_sel:WORD_1 src1_sel:DWORD
	v_add3_u32 v3, v26, v3, s4
	v_and_b32_sdwa v26, v27, v21 dst_sel:DWORD dst_unused:UNUSED_PAD src0_sel:WORD_1 src1_sel:DWORD
	v_or_b32_sdwa v24, v29, v28 dst_sel:DWORD dst_unused:UNUSED_PAD src0_sel:DWORD src1_sel:WORD_1
	v_and_b32_sdwa v29, v31, v21 dst_sel:DWORD dst_unused:UNUSED_PAD src0_sel:WORD_1 src1_sel:DWORD
	v_add3_u32 v26, v27, v26, s4
	v_add3_u32 v27, v31, v29, s4
	v_and_b32_e32 v26, 0xffff0000, v26
	v_and_b32_e32 v29, 0xffff0000, v27
	v_or_b32_sdwa v27, v26, v3 dst_sel:DWORD dst_unused:UNUSED_PAD src0_sel:DWORD src1_sel:WORD_1
	v_mov_b32_e32 v3, v5
	v_lshlrev_b64 v[2:3], 12, v[2:3]
	v_and_b32_sdwa v28, v30, v21 dst_sel:DWORD dst_unused:UNUSED_PAD src0_sel:WORD_1 src1_sel:DWORD
	v_lshl_add_u64 v[2:3], v[14:15], 0, v[2:3]
	v_add3_u32 v28, v30, v28, s4
	v_add_co_u32_e32 v2, vcc, 0xf000000, v2
	v_or_b32_sdwa v26, v29, v28 dst_sel:DWORD dst_unused:UNUSED_PAD src0_sel:DWORD src1_sel:WORD_1
	s_nop 0
	v_addc_co_u32_e32 v3, vcc, 0, v3, vcc
	global_store_dwordx4 v[2:3], v[24:27], off offset:2048
	s_nop 1
	v_mov_b32_dpp v2, v1 quad_perm:[1,0,3,2] row_mask:0xf bank_mask:0xf
	s_waitcnt lgkmcnt(0)
	v_add_f32_e32 v1, v1, v2
	ds_swizzle_b32 v2, v1 offset:swizzle(SWAP,2)
	s_waitcnt lgkmcnt(0)
	v_add_f32_e32 v1, v1, v2
	ds_swizzle_b32 v2, v1 offset:swizzle(SWAP,4)
	s_waitcnt lgkmcnt(0)
	v_add_f32_e32 v1, v1, v2
	ds_swizzle_b32 v2, v1 offset:swizzle(SWAP,8)
	s_and_saveexec_b64 s[0:1], s[34:35]
	s_cbranch_execz .LBB0_1144
	v_add_u32_e32 v24, 0x100, v0
	v_mov_b32_e32 v25, v5
	v_lshl_add_u64 v[24:25], v[24:25], 2, s[24:25]
	s_waitcnt lgkmcnt(0)
	v_add_f32_e32 v0, v1, v2
	global_store_dword v[24:25], v0, off
	s_branch .LBB0_1144

; __device__ __forceinline__ float sum_f(const float* p, int n4) { float s = 0.f; for (int i = 0; i < n4; ++i) { const f32x4 v = *(const f32x4*)(p + 4 * i); s += (v[0] + v[1]) + (v[2] + v[3]); } return s; }
;     __device__ __forceinline__ void mid(f32x4 (&acc)[2][2][4][2], const Unit& u, int wr, int wc, int fr, int fq) const {
;     ...
;             for (int m = 0; m < 4; ++m) { const size_t row = (size_t)u.pm * BM + ai * HALF + wr * 64 + m * 16 + fr;
;                 const float rf = __builtin_amdgcn_rsqf(sum_f(ssqf + row * 8, 2) * (1.0f / 1024.0f) + RMS_EPS), rl = __builtin_amdgcn_rsqf(sum_f(ssql + row * 8, 2) * (1.0f / 1024.0f) + RMS_EPS);
;                 const float ratio = rf / rl;
; #pragma unroll
;                 for (int bj = 0; bj < 2; ++bj)
; #pragma unroll
;                     for (int n = 0; n < 2; ++n) acc[ai][bj][m][n] = acc[ai][bj][m][n] * ratio;
;                 __builtin_amdgcn_sched_barrier(0); }
.LBB0_1218:
	s_cmpk_lg_i32 s18, 0x800
	s_cbranch_scc1 .LBB0_1217
	v_mov_b32_e32 v2, v152
	v_mov_b32_e32 v1, v153
	s_nop 0
	v_ashrrev_i32_e32 v3, 31, v2
	v_lshl_add_u64 v[2:3], v[2:3], 0, s[26:27]
	v_lshlrev_b64 v[2:3], 3, v[2:3]
	v_lshl_add_u64 v[222:223], v[2:3], 0, s[84:85]
	v_lshlrev_b64 v[222:223], 2, v[222:223]
	v_lshl_add_u64 v[224:225], s[40:41], 0, v[222:223]
	v_lshl_add_u64 v[226:227], s[24:25], 0, v[222:223]
	global_load_dwordx4 v[158:161], v[224:225], off
	global_load_dwordx4 v[162:165], v[224:225], off offset:16
	global_load_dwordx4 v[166:169], v[226:227], off
	global_load_dwordx4 v[170:173], v[226:227], off offset:16
	v_lshl_add_u64 v[222:223], v[2:3], 0, s[86:87]
	v_lshlrev_b64 v[222:223], 2, v[222:223]
	v_lshl_add_u64 v[224:225], s[40:41], 0, v[222:223]
	v_lshl_add_u64 v[226:227], s[24:25], 0, v[222:223]
	global_load_dwordx4 v[174:177], v[224:225], off
	global_load_dwordx4 v[178:181], v[224:225], off offset:16
	global_load_dwordx4 v[182:185], v[226:227], off
	global_load_dwordx4 v[186:189], v[226:227], off offset:16
	v_lshl_add_u64 v[222:223], v[2:3], 0, s[96:97]
	v_lshlrev_b64 v[222:223], 2, v[222:223]
	v_lshl_add_u64 v[224:225], s[40:41], 0, v[222:223]
	v_lshl_add_u64 v[226:227], s[24:25], 0, v[222:223]
	global_load_dwordx4 v[190:193], v[224:225], off
	global_load_dwordx4 v[194:197], v[224:225], off offset:16
	global_load_dwordx4 v[198:201], v[226:227], off
	global_load_dwordx4 v[202:205], v[226:227], off offset:16
	v_lshl_add_u64 v[222:223], v[2:3], 0, s[34:35]
	v_lshlrev_b64 v[222:223], 2, v[222:223]
	v_lshl_add_u64 v[224:225], s[40:41], 0, v[222:223]
	v_lshl_add_u64 v[226:227], s[24:25], 0, v[222:223]
	global_load_dwordx4 v[206:209], v[224:225], off
	global_load_dwordx4 v[210:213], v[224:225], off offset:16
	global_load_dwordx4 v[214:217], v[226:227], off
	global_load_dwordx4 v[218:221], v[226:227], off offset:16
	s_waitcnt vmcnt(12)
	v_add_f32_e32 v228, v158, v159
	v_add_f32_e32 v229, v160, v161
	v_add_f32_e32 v230, v162, v163
	v_add_f32_e32 v231, v164, v165
	v_add_f32_e32 v228, v228, v229
	v_add_f32_e32 v230, v230, v231
	v_add_f32_e32 v232, 0, v228
	v_add_f32_e32 v232, v232, v230
	v_fmamk_f32 v232, v232, 0x3a800000, v155
	v_rsq_f32_e32 v232, v232
	v_add_f32_e32 v228, v166, v167
	v_add_f32_e32 v229, v168, v169
	v_add_f32_e32 v230, v170, v171
	v_add_f32_e32 v231, v172, v173
	v_add_f32_e32 v228, v228, v229
	v_add_f32_e32 v230, v230, v231
	v_add_f32_e32 v240, 0, v228
	v_add_f32_e32 v240, v240, v230
	v_fmamk_f32 v240, v240, 0x3a800000, v155
	v_rsq_f32_e32 v240, v240
	s_nop 0
	v_div_scale_f32 v234, s[42:43], v240, v240, v232
	v_rcp_f32_e32 v235, v234
	s_nop 0
	v_fma_f32 v236, -v234, v235, 1.0
	v_fmac_f32_e32 v235, v236, v235
	v_div_scale_f32 v236, vcc, v232, v240, v232
	v_mul_f32_e32 v237, v236, v235
	v_fma_f32 v238, -v234, v237, v236
	v_fmac_f32_e32 v237, v238, v235
	v_fma_f32 v234, -v234, v237, v236
	v_div_fmas_f32 v234, v234, v235, v237
	v_div_fixup_f32 v234, v234, v240, v232
	v_pk_mul_f32 v[130:131], v[130:131], v[234:235] op_sel_hi:[1,0]
	v_pk_mul_f32 v[128:129], v[128:129], v[234:235] op_sel_hi:[1,0]
	v_pk_mul_f32 v[126:127], v[126:127], v[234:235] op_sel_hi:[1,0]
	v_pk_mul_f32 v[124:125], v[124:125], v[234:235] op_sel_hi:[1,0]
	v_pk_mul_f32 v[122:123], v[122:123], v[234:235] op_sel_hi:[1,0]
	v_pk_mul_f32 v[120:121], v[120:121], v[234:235] op_sel_hi:[1,0]
	v_pk_mul_f32 v[118:119], v[118:119], v[234:235] op_sel_hi:[1,0]
	v_pk_mul_f32 v[116:117], v[116:117], v[234:235] op_sel_hi:[1,0]
	s_waitcnt vmcnt(8)
	v_add_f32_e32 v228, v174, v175
	v_add_f32_e32 v229, v176, v177
	v_add_f32_e32 v230, v178, v179
	v_add_f32_e32 v231, v180, v181
	v_add_f32_e32 v228, v228, v229
	v_add_f32_e32 v230, v230, v231
	v_add_f32_e32 v232, 0, v228
	v_add_f32_e32 v232, v232, v230
	v_fmamk_f32 v232, v232, 0x3a800000, v155
	v_rsq_f32_e32 v232, v232
	v_add_f32_e32 v228, v182, v183
	v_add_f32_e32 v229, v184, v185
	v_add_f32_e32 v230, v186, v187
	v_add_f32_e32 v231, v188, v189
	v_add_f32_e32 v228, v228, v229
	v_add_f32_e32 v230, v230, v231
	v_add_f32_e32 v241, 0, v228
	v_add_f32_e32 v241, v241, v230
	v_fmamk_f32 v241, v241, 0x3a800000, v155
	v_rsq_f32_e32 v241, v241
	s_nop 0
	v_div_scale_f32 v234, s[42:43], v241, v241, v232
	v_rcp_f32_e32 v235, v234
	s_nop 0
	v_fma_f32 v236, -v234, v235, 1.0
	v_fmac_f32_e32 v235, v236, v235
	v_div_scale_f32 v236, vcc, v232, v241, v232
	v_mul_f32_e32 v237, v236, v235
	v_fma_f32 v238, -v234, v237, v236
	v_fmac_f32_e32 v237, v238, v235
	v_fma_f32 v234, -v234, v237, v236
	v_div_fmas_f32 v234, v234, v235, v237
	v_div_fixup_f32 v234, v234, v241, v232
	v_pk_mul_f32 v[114:115], v[114:115], v[234:235] op_sel_hi:[1,0]
	v_pk_mul_f32 v[112:113], v[112:113], v[234:235] op_sel_hi:[1,0]
	v_pk_mul_f32 v[110:111], v[110:111], v[234:235] op_sel_hi:[1,0]
	v_pk_mul_f32 v[108:109], v[108:109], v[234:235] op_sel_hi:[1,0]
	v_pk_mul_f32 v[106:107], v[106:107], v[234:235] op_sel_hi:[1,0]
	v_pk_mul_f32 v[104:105], v[104:105], v[234:235] op_sel_hi:[1,0]
	v_pk_mul_f32 v[102:103], v[102:103], v[234:235] op_sel_hi:[1,0]
	v_pk_mul_f32 v[100:101], v[100:101], v[234:235] op_sel_hi:[1,0]
	s_waitcnt vmcnt(4)
; __device__ __forceinline__ float sum_f(const float* p, int n4) { float s = 0.f; for (int i = 0; i < n4; ++i) { const f32x4 v = *(const f32x4*)(p + 4 * i); s += (v[0] + v[1]) + (v[2] + v[3]); } return s; }
;     __device__ __forceinline__ void mid(f32x4 (&acc)[2][2][4][2], const Unit& u, int wr, int wc, int fr, int fq) const {
;     ...
;             for (int m = 0; m < 4; ++m) { const size_t row = (size_t)u.pm * BM + ai * HALF + wr * 64 + m * 16 + fr;
;                 const float rf = __builtin_amdgcn_rsqf(sum_f(ssqf + row * 8, 2) * (1.0f / 1024.0f) + RMS_EPS), rl = __builtin_amdgcn_rsqf(sum_f(ssql + row * 8, 2) * (1.0f / 1024.0f) + RMS_EPS);
;                 const float ratio = rf / rl;
; #pragma unroll
;                 for (int bj = 0; bj < 2; ++bj)
; #pragma unroll
;                     for (int n = 0; n < 2; ++n) acc[ai][bj][m][n] = acc[ai][bj][m][n] * ratio;
;                 __builtin_amdgcn_sched_barrier(0); }
	v_add_f32_e32 v228, v190, v191
	v_add_f32_e32 v229, v192, v193
	v_add_f32_e32 v230, v194, v195
	v_add_f32_e32 v231, v196, v197
	v_add_f32_e32 v228, v228, v229
	v_add_f32_e32 v230, v230, v231
	v_add_f32_e32 v232, 0, v228
	v_add_f32_e32 v232, v232, v230
	v_fmamk_f32 v232, v232, 0x3a800000, v155
	v_rsq_f32_e32 v232, v232
	v_add_f32_e32 v228, v198, v199
	v_add_f32_e32 v229, v200, v201
	v_add_f32_e32 v230, v202, v203
	v_add_f32_e32 v231, v204, v205
	v_add_f32_e32 v228, v228, v229
	v_add_f32_e32 v230, v230, v231
	v_add_f32_e32 v242, 0, v228
	v_add_f32_e32 v242, v242, v230
	v_fmamk_f32 v242, v242, 0x3a800000, v155
	v_rsq_f32_e32 v242, v242
	s_nop 0
	v_div_scale_f32 v234, s[42:43], v242, v242, v232
	v_rcp_f32_e32 v235, v234
	s_nop 0
	v_fma_f32 v236, -v234, v235, 1.0
	v_fmac_f32_e32 v235, v236, v235
	v_div_scale_f32 v236, vcc, v232, v242, v232
	v_mul_f32_e32 v237, v236, v235
	v_fma_f32 v238, -v234, v237, v236
	v_fmac_f32_e32 v237, v238, v235
	v_fma_f32 v234, -v234, v237, v236
	v_div_fmas_f32 v234, v234, v235, v237
	v_div_fixup_f32 v234, v234, v242, v232
	v_pk_mul_f32 v[98:99], v[98:99], v[234:235] op_sel_hi:[1,0]
	v_pk_mul_f32 v[96:97], v[96:97], v[234:235] op_sel_hi:[1,0]
	v_pk_mul_f32 v[94:95], v[94:95], v[234:235] op_sel_hi:[1,0]
	v_pk_mul_f32 v[92:93], v[92:93], v[234:235] op_sel_hi:[1,0]
	v_pk_mul_f32 v[90:91], v[90:91], v[234:235] op_sel_hi:[1,0]
	v_pk_mul_f32 v[88:89], v[88:89], v[234:235] op_sel_hi:[1,0]
	v_pk_mul_f32 v[86:87], v[86:87], v[234:235] op_sel_hi:[1,0]
	v_pk_mul_f32 v[84:85], v[84:85], v[234:235] op_sel_hi:[1,0]
	s_waitcnt vmcnt(0)
	v_add_f32_e32 v228, v206, v207
	v_add_f32_e32 v229, v208, v209
	v_add_f32_e32 v230, v210, v211
	v_add_f32_e32 v231, v212, v213
	v_add_f32_e32 v228, v228, v229
	v_add_f32_e32 v230, v230, v231
	v_add_f32_e32 v232, 0, v228
	v_add_f32_e32 v232, v232, v230
	v_fmamk_f32 v232, v232, 0x3a800000, v155
	v_rsq_f32_e32 v232, v232
	v_add_f32_e32 v228, v214, v215
	v_add_f32_e32 v229, v216, v217
	v_add_f32_e32 v230, v218, v219
	v_add_f32_e32 v231, v220, v221
	v_add_f32_e32 v228, v228, v229
	v_add_f32_e32 v230, v230, v231
	v_add_f32_e32 v243, 0, v228
	v_add_f32_e32 v243, v243, v230
	v_fmamk_f32 v243, v243, 0x3a800000, v155
	v_rsq_f32_e32 v243, v243
	s_nop 0
	v_div_scale_f32 v234, s[42:43], v243, v243, v232
	v_rcp_f32_e32 v235, v234
	s_nop 0
	v_fma_f32 v236, -v234, v235, 1.0
	v_fmac_f32_e32 v235, v236, v235
	v_div_scale_f32 v236, vcc, v232, v243, v232
	v_mul_f32_e32 v237, v236, v235
	v_fma_f32 v238, -v234, v237, v236
	v_fmac_f32_e32 v237, v238, v235
	v_fma_f32 v234, -v234, v237, v236
	v_div_fmas_f32 v234, v234, v235, v237
	v_div_fixup_f32 v234, v234, v243, v232
	v_pk_mul_f32 v[82:83], v[82:83], v[234:235] op_sel_hi:[1,0]
	v_pk_mul_f32 v[80:81], v[80:81], v[234:235] op_sel_hi:[1,0]
	v_pk_mul_f32 v[78:79], v[78:79], v[234:235] op_sel_hi:[1,0]
	v_pk_mul_f32 v[76:77], v[76:77], v[234:235] op_sel_hi:[1,0]
	v_pk_mul_f32 v[74:75], v[74:75], v[234:235] op_sel_hi:[1,0]
	v_pk_mul_f32 v[72:73], v[72:73], v[234:235] op_sel_hi:[1,0]
	v_pk_mul_f32 v[70:71], v[70:71], v[234:235] op_sel_hi:[1,0]
	v_pk_mul_f32 v[68:69], v[68:69], v[234:235] op_sel_hi:[1,0]
	v_lshl_add_u64 v[222:223], v[2:3], 0, s[82:83]
	v_lshlrev_b64 v[222:223], 2, v[222:223]
	v_lshl_add_u64 v[224:225], s[40:41], 0, v[222:223]
	v_lshl_add_u64 v[226:227], s[24:25], 0, v[222:223]
	global_load_dwordx4 v[158:161], v[224:225], off
	global_load_dwordx4 v[162:165], v[224:225], off offset:16
	global_load_dwordx4 v[166:169], v[226:227], off
	global_load_dwordx4 v[170:173], v[226:227], off offset:16
	v_lshl_add_u64 v[222:223], v[2:3], 0, s[20:21]
	v_lshlrev_b64 v[222:223], 2, v[222:223]
	v_lshl_add_u64 v[224:225], s[40:41], 0, v[222:223]
	v_lshl_add_u64 v[226:227], s[24:25], 0, v[222:223]
	global_load_dwordx4 v[174:177], v[224:225], off
	global_load_dwordx4 v[178:181], v[224:225], off offset:16
	global_load_dwordx4 v[182:185], v[226:227], off
	global_load_dwordx4 v[186:189], v[226:227], off offset:16
	v_lshl_add_u64 v[222:223], v[2:3], 0, s[12:13]
	v_lshlrev_b64 v[222:223], 2, v[222:223]
	v_lshl_add_u64 v[224:225], s[40:41], 0, v[222:223]
	v_lshl_add_u64 v[226:227], s[24:25], 0, v[222:223]
	global_load_dwordx4 v[190:193], v[224:225], off
	global_load_dwordx4 v[194:197], v[224:225], off offset:16
	global_load_dwordx4 v[198:201], v[226:227], off
	global_load_dwordx4 v[202:205], v[226:227], off offset:16
	v_lshl_add_u64 v[222:223], v[2:3], 0, s[16:17]
	v_lshlrev_b64 v[222:223], 2, v[222:223]
	v_lshl_add_u64 v[224:225], s[40:41], 0, v[222:223]
	v_lshl_add_u64 v[226:227], s[24:25], 0, v[222:223]
	global_load_dwordx4 v[206:209], v[224:225], off
	global_load_dwordx4 v[210:213], v[224:225], off offset:16
	global_load_dwordx4 v[214:217], v[226:227], off
	global_load_dwordx4 v[218:221], v[226:227], off offset:16
	s_waitcnt vmcnt(12)
; __device__ __forceinline__ float sum_f(const float* p, int n4) { float s = 0.f; for (int i = 0; i < n4; ++i) { const f32x4 v = *(const f32x4*)(p + 4 * i); s += (v[0] + v[1]) + (v[2] + v[3]); } return s; }
;     __device__ __forceinline__ void mid(f32x4 (&acc)[2][2][4][2], const Unit& u, int wr, int wc, int fr, int fq) const {
;     ...
;             for (int m = 0; m < 4; ++m) { const size_t row = (size_t)u.pm * BM + ai * HALF + wr * 64 + m * 16 + fr;
;                 const float rf = __builtin_amdgcn_rsqf(sum_f(ssqf + row * 8, 2) * (1.0f / 1024.0f) + RMS_EPS), rl = __builtin_amdgcn_rsqf(sum_f(ssql + row * 8, 2) * (1.0f / 1024.0f) + RMS_EPS);
;                 const float ratio = rf / rl;
; #pragma unroll
;                 for (int bj = 0; bj < 2; ++bj)
; #pragma unroll
;                     for (int n = 0; n < 2; ++n) acc[ai][bj][m][n] = acc[ai][bj][m][n] * ratio;
;                 __builtin_amdgcn_sched_barrier(0); }
	v_add_f32_e32 v228, v158, v159
	v_add_f32_e32 v229, v160, v161
	v_add_f32_e32 v230, v162, v163
	v_add_f32_e32 v231, v164, v165
	v_add_f32_e32 v228, v228, v229
	v_add_f32_e32 v230, v230, v231
	v_add_f32_e32 v232, 0, v228
	v_add_f32_e32 v232, v232, v230
	v_fmamk_f32 v232, v232, 0x3a800000, v155
	v_rsq_f32_e32 v232, v232
	v_add_f32_e32 v228, v166, v167
	v_add_f32_e32 v229, v168, v169
	v_add_f32_e32 v230, v170, v171
	v_add_f32_e32 v231, v172, v173
	v_add_f32_e32 v228, v228, v229
	v_add_f32_e32 v230, v230, v231
	v_add_f32_e32 v244, 0, v228
	v_add_f32_e32 v244, v244, v230
	v_fmamk_f32 v244, v244, 0x3a800000, v155
	v_rsq_f32_e32 v244, v244
	s_nop 0
	v_div_scale_f32 v234, s[42:43], v244, v244, v232
	v_rcp_f32_e32 v235, v234
	s_nop 0
	v_fma_f32 v236, -v234, v235, 1.0
	v_fmac_f32_e32 v235, v236, v235
	v_div_scale_f32 v236, vcc, v232, v244, v232
	v_mul_f32_e32 v237, v236, v235
	v_fma_f32 v238, -v234, v237, v236
	v_fmac_f32_e32 v237, v238, v235
	v_fma_f32 v234, -v234, v237, v236
	v_div_fmas_f32 v234, v234, v235, v237
	v_div_fixup_f32 v234, v234, v244, v232
	v_pk_mul_f32 v[66:67], v[66:67], v[234:235] op_sel_hi:[1,0]
	v_pk_mul_f32 v[64:65], v[64:65], v[234:235] op_sel_hi:[1,0]
	v_pk_mul_f32 v[62:63], v[62:63], v[234:235] op_sel_hi:[1,0]
	v_pk_mul_f32 v[60:61], v[60:61], v[234:235] op_sel_hi:[1,0]
	v_pk_mul_f32 v[58:59], v[58:59], v[234:235] op_sel_hi:[1,0]
	v_pk_mul_f32 v[56:57], v[56:57], v[234:235] op_sel_hi:[1,0]
	v_pk_mul_f32 v[54:55], v[54:55], v[234:235] op_sel_hi:[1,0]
	v_pk_mul_f32 v[52:53], v[52:53], v[234:235] op_sel_hi:[1,0]
	s_waitcnt vmcnt(8)
	v_add_f32_e32 v228, v174, v175
	v_add_f32_e32 v229, v176, v177
	v_add_f32_e32 v230, v178, v179
	v_add_f32_e32 v231, v180, v181
	v_add_f32_e32 v228, v228, v229
	v_add_f32_e32 v230, v230, v231
	v_add_f32_e32 v232, 0, v228
	v_add_f32_e32 v232, v232, v230
	v_fmamk_f32 v232, v232, 0x3a800000, v155
	v_rsq_f32_e32 v232, v232
	v_add_f32_e32 v228, v182, v183
	v_add_f32_e32 v229, v184, v185
	v_add_f32_e32 v230, v186, v187
	v_add_f32_e32 v231, v188, v189
	v_add_f32_e32 v228, v228, v229
	v_add_f32_e32 v230, v230, v231
	v_add_f32_e32 v245, 0, v228
	v_add_f32_e32 v245, v245, v230
	v_fmamk_f32 v245, v245, 0x3a800000, v155
	v_rsq_f32_e32 v245, v245
	s_nop 0
	v_div_scale_f32 v234, s[42:43], v245, v245, v232
	v_rcp_f32_e32 v235, v234
	s_nop 0
	v_fma_f32 v236, -v234, v235, 1.0
	v_fmac_f32_e32 v235, v236, v235
	v_div_scale_f32 v236, vcc, v232, v245, v232
	v_mul_f32_e32 v237, v236, v235
	v_fma_f32 v238, -v234, v237, v236
	v_fmac_f32_e32 v237, v238, v235
	v_fma_f32 v234, -v234, v237, v236
	v_div_fmas_f32 v234, v234, v235, v237
	v_div_fixup_f32 v234, v234, v245, v232
	v_pk_mul_f32 v[50:51], v[50:51], v[234:235] op_sel_hi:[1,0]
	v_pk_mul_f32 v[48:49], v[48:49], v[234:235] op_sel_hi:[1,0]
	v_pk_mul_f32 v[46:47], v[46:47], v[234:235] op_sel_hi:[1,0]
	v_pk_mul_f32 v[44:45], v[44:45], v[234:235] op_sel_hi:[1,0]
	v_pk_mul_f32 v[42:43], v[42:43], v[234:235] op_sel_hi:[1,0]
	v_pk_mul_f32 v[40:41], v[40:41], v[234:235] op_sel_hi:[1,0]
	v_pk_mul_f32 v[38:39], v[38:39], v[234:235] op_sel_hi:[1,0]
	v_pk_mul_f32 v[36:37], v[36:37], v[234:235] op_sel_hi:[1,0]
	s_waitcnt vmcnt(4)
	v_add_f32_e32 v228, v190, v191
	v_add_f32_e32 v229, v192, v193
	v_add_f32_e32 v230, v194, v195
	v_add_f32_e32 v231, v196, v197
	v_add_f32_e32 v228, v228, v229
	v_add_f32_e32 v230, v230, v231
	v_add_f32_e32 v232, 0, v228
	v_add_f32_e32 v232, v232, v230
	v_fmamk_f32 v232, v232, 0x3a800000, v155
	v_rsq_f32_e32 v232, v232
	v_add_f32_e32 v228, v198, v199
	v_add_f32_e32 v229, v200, v201
	v_add_f32_e32 v230, v202, v203
	v_add_f32_e32 v231, v204, v205
	v_add_f32_e32 v228, v228, v229
	v_add_f32_e32 v230, v230, v231
	v_add_f32_e32 v246, 0, v228
	v_add_f32_e32 v246, v246, v230
	v_fmamk_f32 v246, v246, 0x3a800000, v155
	v_rsq_f32_e32 v246, v246
	s_nop 0
	v_div_scale_f32 v234, s[42:43], v246, v246, v232
	v_rcp_f32_e32 v235, v234
	s_nop 0
	v_fma_f32 v236, -v234, v235, 1.0
	v_fmac_f32_e32 v235, v236, v235
	v_div_scale_f32 v236, vcc, v232, v246, v232
	v_mul_f32_e32 v237, v236, v235
	v_fma_f32 v238, -v234, v237, v236
	v_fmac_f32_e32 v237, v238, v235
	v_fma_f32 v234, -v234, v237, v236
	v_div_fmas_f32 v234, v234, v235, v237
	v_div_fixup_f32 v234, v234, v246, v232
	v_pk_mul_f32 v[34:35], v[34:35], v[234:235] op_sel_hi:[1,0]
	v_pk_mul_f32 v[32:33], v[32:33], v[234:235] op_sel_hi:[1,0]
	v_pk_mul_f32 v[30:31], v[30:31], v[234:235] op_sel_hi:[1,0]
	v_pk_mul_f32 v[28:29], v[28:29], v[234:235] op_sel_hi:[1,0]
	v_pk_mul_f32 v[26:27], v[26:27], v[234:235] op_sel_hi:[1,0]
	v_pk_mul_f32 v[24:25], v[24:25], v[234:235] op_sel_hi:[1,0]
	v_pk_mul_f32 v[22:23], v[22:23], v[234:235] op_sel_hi:[1,0]
	v_pk_mul_f32 v[20:21], v[20:21], v[234:235] op_sel_hi:[1,0]
	s_waitcnt vmcnt(0)
	v_add_f32_e32 v228, v206, v207
	v_add_f32_e32 v229, v208, v209
	v_add_f32_e32 v230, v210, v211
	v_add_f32_e32 v231, v212, v213
	v_add_f32_e32 v228, v228, v229
	v_add_f32_e32 v230, v230, v231
	v_add_f32_e32 v232, 0, v228
	v_add_f32_e32 v232, v232, v230
	v_fmamk_f32 v232, v232, 0x3a800000, v155
	v_rsq_f32_e32 v232, v232
	v_add_f32_e32 v228, v214, v215
	v_add_f32_e32 v229, v216, v217
	v_add_f32_e32 v230, v218, v219
	v_add_f32_e32 v231, v220, v221
	v_add_f32_e32 v228, v228, v229
	v_add_f32_e32 v230, v230, v231
	v_add_f32_e32 v247, 0, v228
	v_add_f32_e32 v247, v247, v230
	v_fmamk_f32 v247, v247, 0x3a800000, v155
	v_rsq_f32_e32 v247, v247
	s_nop 0
	v_div_scale_f32 v234, s[42:43], v247, v247, v232
	v_rcp_f32_e32 v235, v234
	s_nop 0
	v_fma_f32 v236, -v234, v235, 1.0
	v_fmac_f32_e32 v235, v236, v235
	v_div_scale_f32 v236, vcc, v232, v247, v232
	v_mul_f32_e32 v237, v236, v235
	v_fma_f32 v238, -v234, v237, v236
	v_fmac_f32_e32 v237, v238, v235
	v_fma_f32 v234, -v234, v237, v236
	v_div_fmas_f32 v234, v234, v235, v237
	v_div_fixup_f32 v234, v234, v247, v232
	v_pk_mul_f32 v[18:19], v[18:19], v[234:235] op_sel_hi:[1,0]
	v_pk_mul_f32 v[16:17], v[16:17], v[234:235] op_sel_hi:[1,0]
	v_pk_mul_f32 v[14:15], v[14:15], v[234:235] op_sel_hi:[1,0]
	v_pk_mul_f32 v[12:13], v[12:13], v[234:235] op_sel_hi:[1,0]
	v_pk_mul_f32 v[10:11], v[10:11], v[234:235] op_sel_hi:[1,0]
	v_pk_mul_f32 v[8:9], v[8:9], v[234:235] op_sel_hi:[1,0]
	v_pk_mul_f32 v[6:7], v[6:7], v[234:235] op_sel_hi:[1,0]
	v_pk_mul_f32 v[4:5], v[4:5], v[234:235] op_sel_hi:[1,0]
	s_branch .LBB0_1217

; template <int K> __device__ __forceinline__ float shx(float v) { static_assert(K < 32, "use sum32"); return __int_as_float(__builtin_amdgcn_ds_swizzle(__float_as_int(v), (K << 10) | 0x1f)); }
; __device__ __forceinline__ float sum32(float v) { auto rr = __builtin_amdgcn_permlane32_swap(__float_as_uint(v), __float_as_uint(v), false, false); return __uint_as_float(rr[0]) + __uint_as_float(rr[1]); }
;     __device__ __forceinline__ void operator()(const f32x4 (&acc)[2][2][4][2], const Unit& u, int wr, int wc, int fr, int fq) const {
;     ...
;             for (int m = 0; m < 4; ++m) { const size_t row = (size_t)u.pm * BM + ai * HALF + wr * 64 + m * 16 + fr;
;                 float sc = 1.f; if (MID) sc = __builtin_amdgcn_rsqf(sum_f(ssql + row * 8, 2) * (1.0f / 1024.0f) + RMS_EPS);
;                 float ss = 0.f;
; #pragma unroll
;                 for (int bj = 0; bj < 2; ++bj) { const size_t o = row * 2048 + u.pn * BM + bj * HALF + wc * 32 + fq * 8;
;                     f32x4 r0, r1;
;                     if (residb) { const u32x4 w = __builtin_nontemporal_load((const u32x4*)(residb + o));     r0 = (f32x4){__uint_as_float(w.x << 16), __uint_as_float(w.x & 0xffff0000u), __uint_as_float(w.y << 16), __uint_as_float(w.y & 0xffff0000u)};
;                                   r1 = (f32x4){__uint_as_float(w.z << 16), __uint_as_float(w.z & 0xffff0000u), __uint_as_float(w.w << 16), __uint_as_float(w.w & 0xffff0000u)}; }
;                     else { r0 = __builtin_nontemporal_load((const f32x4*)(resid + o)); r1 = __builtin_nontemporal_load((const f32x4*)(resid + o + 4)); }
;                     const f32x4 v0 = r0 + acc[ai][bj][m][0] * sc, v1 = r1 + acc[ai][bj][m][1] * sc;
;                     if (outf) { __builtin_nontemporal_store(v0, (f32x4*)(outf + o)); __builtin_nontemporal_store(v1, (f32x4*)(outf + o + 4)); }
;                     ss += (v0[0] * v0[0] + v0[1] * v0[1]) + (v0[2] * v0[2] + v0[3] * v0[3]) + (v1[0] * v1[0] + v1[1] * v1[1]) + (v1[2] * v1[2] + v1[3] * v1[3]);
;                     if (outb) *(u32x4*)(outb + o) = pack8(v0, v1); }
;                 if (ssq_out) { ss += shx<16>(ss); ss = sum32(ss); if (fq == 0) ssq_out[row * 32 + u.pn * 4 + wc] = ss; }
;                 __builtin_amdgcn_sched_barrier(0); }
.LBB0_1222:
	s_lshl_b64 s[12:13], s[60:61], 8
	v_mov_b32_e32 v2, v152
	v_mov_b32_e32 v1, v153
	s_add_u32 s12, s12, s26
	s_addc_u32 s13, s13, s27
	v_ashrrev_i32_e32 v3, 31, v2
	v_lshl_add_u64 v[148:149], s[12:13], 0, v[2:3]
	s_lshl_b32 s12, s0, 8
	s_ashr_i32 s13, s12, 31
	v_lshlrev_b32_e32 v2, 3, v1
	v_ashrrev_i32_e32 v3, 31, v2
	s_or_b64 s[12:13], s[12:13], s[28:29]
	v_lshl_add_u64 v[2:3], s[12:13], 0, v[2:3]
	v_readlane_b32 s80, v252, 8
	v_readlane_b32 s81, v252, 9
	v_cmp_eq_u32_e32 vcc, 0, v1
	s_lshl_b32 s60, s0, 2
	s_ashr_i32 s61, s60, 31
	v_readlane_b32 s82, v252, 10
	v_readlane_b32 s83, v252, 11
	v_readlane_b32 s84, v252, 12
	v_readlane_b32 s85, v252, 13
	v_readlane_b32 s86, v252, 14
	v_readlane_b32 s87, v252, 15
	v_readlane_b32 s88, v252, 16
	v_readlane_b32 s89, v252, 17
	v_readlane_b32 s90, v252, 18
	v_readlane_b32 s91, v252, 19
	v_readlane_b32 s92, v252, 20
	v_readlane_b32 s93, v252, 21
	v_readlane_b32 s94, v252, 22
	v_readlane_b32 s95, v252, 23
	v_lshlrev_b64 v[158:159], 11, v[148:149]
	v_lshl_add_u64 v[166:167], v[2:3], 0, v[158:159]
	v_lshl_add_u64 v[168:169], v[166:167], 2, s[80:81]
	global_load_dwordx4 v[158:161], v[168:169], off offset:16 nt
	global_load_dwordx4 v[162:165], v[168:169], off nt
	v_mov_b32_e32 v150, v240
	s_waitcnt vmcnt(1)
	v_pk_fma_f32 v[160:161], v[126:127], v[150:151], v[160:161] op_sel_hi:[1,0,1]
	s_waitcnt vmcnt(0)
	v_pk_fma_f32 v[130:131], v[130:131], v[150:151], v[164:165] op_sel_hi:[1,0,1]
	v_pk_fma_f32 v[128:129], v[128:129], v[150:151], v[162:163] op_sel_hi:[1,0,1]
	v_pk_fma_f32 v[126:127], v[124:125], v[150:151], v[158:159] op_sel_hi:[1,0,1]
	v_mul_f32_e32 v1, v129, v129
	v_mul_f32_e32 v124, v131, v131
	v_fmac_f32_e32 v1, v128, v128
	v_fmac_f32_e32 v124, v130, v130
	v_add_f32_e32 v1, v1, v124
	v_mul_f32_e32 v124, v127, v127
	v_fmac_f32_e32 v124, v126, v126
	v_add_f32_e32 v1, v124, v1
	v_mul_f32_e32 v124, v161, v161
	v_fmac_f32_e32 v124, v160, v160
	v_lshl_add_u64 v[158:159], v[166:167], 1, s[54:55]
	v_add_f32_e32 v1, v124, v1
	v_cvt_pk_bf16_f32 v124, v128, v129
	v_cvt_pk_bf16_f32 v125, v130, v131
	v_cvt_pk_bf16_f32 v126, v126, v127
	v_cvt_pk_bf16_f32 v127, v160, v161
	global_store_dwordx4 v[158:159], v[124:127], off
	global_load_dwordx4 v[124:127], v[168:169], off offset:528 nt
	s_nop 0
	global_load_dwordx4 v[128:131], v[168:169], off offset:512 nt
	s_waitcnt vmcnt(1)
	v_pk_fma_f32 v[126:127], v[118:119], v[150:151], v[126:127] op_sel_hi:[1,0,1]
	s_waitcnt vmcnt(0)
	v_pk_fma_f32 v[122:123], v[122:123], v[150:151], v[130:131] op_sel_hi:[1,0,1]
	v_pk_fma_f32 v[120:121], v[120:121], v[150:151], v[128:129] op_sel_hi:[1,0,1]
	v_pk_fma_f32 v[118:119], v[116:117], v[150:151], v[124:125] op_sel_hi:[1,0,1]
	v_mul_f32_e32 v116, v121, v121
	v_mul_f32_e32 v117, v123, v123
	v_fmac_f32_e32 v116, v120, v120
	v_fmac_f32_e32 v117, v122, v122
	v_add_f32_e32 v116, v116, v117
	v_mul_f32_e32 v117, v119, v119
	v_fmac_f32_e32 v117, v118, v118
	v_add_f32_e32 v116, v117, v116
	v_mul_f32_e32 v117, v127, v127
	v_fmac_f32_e32 v117, v126, v126
	v_add_f32_e32 v116, v117, v116
	v_add_f32_e32 v1, v1, v116
	v_cvt_pk_bf16_f32 v116, v120, v121
	v_cvt_pk_bf16_f32 v117, v122, v123
	v_cvt_pk_bf16_f32 v118, v118, v119
	v_cvt_pk_bf16_f32 v119, v126, v127
	global_store_dwordx4 v[158:159], v[116:119], off offset:256
	ds_swizzle_b32 v116, v1 offset:swizzle(SWAP,16)
	s_waitcnt lgkmcnt(0)
	v_add_f32_e32 v1, v1, v116
	v_mov_b32_e32 v116, v1
	s_nop 1
	v_permlane32_swap_b32_e32 v1, v116
	s_and_saveexec_b64 s[12:13], vcc
	v_readlane_b32 s18, v251, 1
	v_readlane_b32 s19, v251, 2
	s_cbranch_execz .LBB0_1224
	v_lshlrev_b64 v[118:119], 7, v[148:149]
	v_lshl_add_u64 v[118:119], s[22:23], 0, v[118:119]
	v_lshl_add_u64 v[118:119], s[60:61], 2, v[118:119]
	s_lshl_b32 s0, s46, 2
	v_lshl_add_u64 v[118:119], v[118:119], 0, s[0:1]
	v_add_f32_e32 v1, v1, v116
	global_store_dword v[118:119], v1, off
.LBB0_1224:
	s_or_b64 exec, exec, s[12:13]
	v_lshl_add_u64 v[116:117], v[148:149], 0, 16
	v_readlane_b32 s80, v252, 8
	v_readlane_b32 s81, v252, 9
	v_readlane_b32 s82, v252, 10
	v_readlane_b32 s83, v252, 11
	v_readlane_b32 s84, v252, 12
	v_readlane_b32 s85, v252, 13
	v_readlane_b32 s86, v252, 14
	v_readlane_b32 s87, v252, 15
	v_readlane_b32 s88, v252, 16
	v_readlane_b32 s89, v252, 17
	v_readlane_b32 s90, v252, 18
	v_readlane_b32 s91, v252, 19
	v_readlane_b32 s92, v252, 20
	v_readlane_b32 s93, v252, 21
	v_readlane_b32 s94, v252, 22
	v_readlane_b32 s95, v252, 23
	v_lshlrev_b64 v[120:121], 11, v[116:117]
	v_lshl_add_u64 v[128:129], v[120:121], 0, v[2:3]
	v_lshl_add_u64 v[130:131], v[128:129], 2, s[80:81]
	global_load_dwordx4 v[120:123], v[130:131], off offset:16 nt
	global_load_dwordx4 v[124:127], v[130:131], off nt
	v_mov_b32_e32 v118, v241
	s_waitcnt vmcnt(1)
	v_pk_fma_f32 v[122:123], v[110:111], v[118:119], v[122:123] op_sel_hi:[1,0,1]
	s_waitcnt vmcnt(0)
	v_pk_fma_f32 v[114:115], v[114:115], v[118:119], v[126:127] op_sel_hi:[1,0,1]
	v_pk_fma_f32 v[112:113], v[112:113], v[118:119], v[124:125] op_sel_hi:[1,0,1]
	v_pk_fma_f32 v[110:111], v[108:109], v[118:119], v[120:121] op_sel_hi:[1,0,1]
	v_mul_f32_e32 v1, v113, v113
	v_mul_f32_e32 v108, v115, v115
	v_fmac_f32_e32 v1, v112, v112
	v_fmac_f32_e32 v108, v114, v114
	v_add_f32_e32 v1, v1, v108
	v_mul_f32_e32 v108, v111, v111
	v_fmac_f32_e32 v108, v110, v110
	v_add_f32_e32 v1, v108, v1
	v_mul_f32_e32 v108, v123, v123
	v_fmac_f32_e32 v108, v122, v122
	v_lshl_add_u64 v[120:121], v[128:129], 1, s[54:55]
	v_add_f32_e32 v1, v108, v1
	v_cvt_pk_bf16_f32 v108, v112, v113
	v_cvt_pk_bf16_f32 v109, v114, v115
	v_cvt_pk_bf16_f32 v110, v110, v111
	v_cvt_pk_bf16_f32 v111, v122, v123
	global_store_dwordx4 v[120:121], v[108:111], off
	global_load_dwordx4 v[108:111], v[130:131], off offset:528 nt
	s_nop 0
	global_load_dwordx4 v[112:115], v[130:131], off offset:512 nt
	s_waitcnt vmcnt(1)
	v_pk_fma_f32 v[110:111], v[102:103], v[118:119], v[110:111] op_sel_hi:[1,0,1]
	s_waitcnt vmcnt(0)
	v_pk_fma_f32 v[106:107], v[106:107], v[118:119], v[114:115] op_sel_hi:[1,0,1]
	v_pk_fma_f32 v[104:105], v[104:105], v[118:119], v[112:113] op_sel_hi:[1,0,1]
	v_pk_fma_f32 v[102:103], v[100:101], v[118:119], v[108:109] op_sel_hi:[1,0,1]
	v_mul_f32_e32 v100, v105, v105
	v_mul_f32_e32 v101, v107, v107
	v_fmac_f32_e32 v100, v104, v104
	v_fmac_f32_e32 v101, v106, v106
	v_add_f32_e32 v100, v100, v101
	v_mul_f32_e32 v101, v103, v103
	v_fmac_f32_e32 v101, v102, v102
	v_add_f32_e32 v100, v101, v100
	v_mul_f32_e32 v101, v111, v111
	v_fmac_f32_e32 v101, v110, v110
	v_add_f32_e32 v100, v101, v100
	v_add_f32_e32 v1, v1, v100
	v_cvt_pk_bf16_f32 v100, v104, v105
	v_cvt_pk_bf16_f32 v101, v106, v107
	v_cvt_pk_bf16_f32 v102, v102, v103
	v_cvt_pk_bf16_f32 v103, v110, v111
	global_store_dwordx4 v[120:121], v[100:103], off offset:256
	ds_swizzle_b32 v100, v1 offset:swizzle(SWAP,16)
	s_waitcnt lgkmcnt(0)
	v_add_f32_e32 v1, v1, v100
	v_mov_b32_e32 v100, v1
	s_nop 1
	v_permlane32_swap_b32_e32 v1, v100
	s_and_saveexec_b64 s[12:13], vcc
	s_cbranch_execz .LBB0_1226
; template <int K> __device__ __forceinline__ float shx(float v) { static_assert(K < 32, "use sum32"); return __int_as_float(__builtin_amdgcn_ds_swizzle(__float_as_int(v), (K << 10) | 0x1f)); }
; __device__ __forceinline__ float sum32(float v) { auto rr = __builtin_amdgcn_permlane32_swap(__float_as_uint(v), __float_as_uint(v), false, false); return __uint_as_float(rr[0]) + __uint_as_float(rr[1]); }
;     __device__ __forceinline__ void operator()(const f32x4 (&acc)[2][2][4][2], const Unit& u, int wr, int wc, int fr, int fq) const {
;     ...
;             for (int m = 0; m < 4; ++m) { const size_t row = (size_t)u.pm * BM + ai * HALF + wr * 64 + m * 16 + fr;
;                 float sc = 1.f; if (MID) sc = __builtin_amdgcn_rsqf(sum_f(ssql + row * 8, 2) * (1.0f / 1024.0f) + RMS_EPS);
;                 float ss = 0.f;
; #pragma unroll
;                 for (int bj = 0; bj < 2; ++bj) { const size_t o = row * 2048 + u.pn * BM + bj * HALF + wc * 32 + fq * 8;
;                     f32x4 r0, r1;
;                     if (residb) { const u32x4 w = __builtin_nontemporal_load((const u32x4*)(residb + o));     r0 = (f32x4){__uint_as_float(w.x << 16), __uint_as_float(w.x & 0xffff0000u), __uint_as_float(w.y << 16), __uint_as_float(w.y & 0xffff0000u)};
;                                   r1 = (f32x4){__uint_as_float(w.z << 16), __uint_as_float(w.z & 0xffff0000u), __uint_as_float(w.w << 16), __uint_as_float(w.w & 0xffff0000u)}; }
;                     else { r0 = __builtin_nontemporal_load((const f32x4*)(resid + o)); r1 = __builtin_nontemporal_load((const f32x4*)(resid + o + 4)); }
;                     const f32x4 v0 = r0 + acc[ai][bj][m][0] * sc, v1 = r1 + acc[ai][bj][m][1] * sc;
;                     if (outf) { __builtin_nontemporal_store(v0, (f32x4*)(outf + o)); __builtin_nontemporal_store(v1, (f32x4*)(outf + o + 4)); }
;                     ss += (v0[0] * v0[0] + v0[1] * v0[1]) + (v0[2] * v0[2] + v0[3] * v0[3]) + (v1[0] * v1[0] + v1[1] * v1[1]) + (v1[2] * v1[2] + v1[3] * v1[3]);
;                     if (outb) *(u32x4*)(outb + o) = pack8(v0, v1); }
;                 if (ssq_out) { ss += shx<16>(ss); ss = sum32(ss); if (fq == 0) ssq_out[row * 32 + u.pn * 4 + wc] = ss; }
;                 __builtin_amdgcn_sched_barrier(0); }
	v_lshlrev_b64 v[102:103], 7, v[116:117]
	v_lshl_add_u64 v[102:103], s[22:23], 0, v[102:103]
	v_lshl_add_u64 v[102:103], s[60:61], 2, v[102:103]
	s_lshl_b32 s0, s46, 2
	v_lshl_add_u64 v[102:103], v[102:103], 0, s[0:1]
	v_add_f32_e32 v1, v1, v100
	global_store_dword v[102:103], v1, off
.LBB0_1226:
	s_or_b64 exec, exec, s[12:13]
	v_lshl_add_u64 v[100:101], v[148:149], 0, 32
	v_readlane_b32 s80, v252, 8
	v_readlane_b32 s81, v252, 9
	v_readlane_b32 s82, v252, 10
	v_readlane_b32 s83, v252, 11
	v_readlane_b32 s84, v252, 12
	v_readlane_b32 s85, v252, 13
	v_readlane_b32 s86, v252, 14
	v_readlane_b32 s87, v252, 15
	v_readlane_b32 s88, v252, 16
	v_readlane_b32 s89, v252, 17
	v_readlane_b32 s90, v252, 18
	v_readlane_b32 s91, v252, 19
	v_readlane_b32 s92, v252, 20
	v_readlane_b32 s93, v252, 21
	v_readlane_b32 s94, v252, 22
	v_readlane_b32 s95, v252, 23
	v_lshlrev_b64 v[104:105], 11, v[100:101]
	v_lshl_add_u64 v[112:113], v[104:105], 0, v[2:3]
	v_lshl_add_u64 v[114:115], v[112:113], 2, s[80:81]
	global_load_dwordx4 v[104:107], v[114:115], off offset:16 nt
	global_load_dwordx4 v[108:111], v[114:115], off nt
	v_mov_b32_e32 v102, v242
	s_waitcnt vmcnt(1)
	v_pk_fma_f32 v[106:107], v[94:95], v[102:103], v[106:107] op_sel_hi:[1,0,1]
	s_waitcnt vmcnt(0)
	v_pk_fma_f32 v[98:99], v[98:99], v[102:103], v[110:111] op_sel_hi:[1,0,1]
	v_pk_fma_f32 v[96:97], v[96:97], v[102:103], v[108:109] op_sel_hi:[1,0,1]
	v_pk_fma_f32 v[94:95], v[92:93], v[102:103], v[104:105] op_sel_hi:[1,0,1]
	v_mul_f32_e32 v1, v97, v97
	v_mul_f32_e32 v92, v99, v99
	v_fmac_f32_e32 v1, v96, v96
	v_fmac_f32_e32 v92, v98, v98
	v_add_f32_e32 v1, v1, v92
	v_mul_f32_e32 v92, v95, v95
	v_fmac_f32_e32 v92, v94, v94
	v_add_f32_e32 v1, v92, v1
	v_mul_f32_e32 v92, v107, v107
	v_fmac_f32_e32 v92, v106, v106
	v_lshl_add_u64 v[104:105], v[112:113], 1, s[54:55]
	v_add_f32_e32 v1, v92, v1
	v_cvt_pk_bf16_f32 v92, v96, v97
	v_cvt_pk_bf16_f32 v93, v98, v99
	v_cvt_pk_bf16_f32 v94, v94, v95
	v_cvt_pk_bf16_f32 v95, v106, v107
	global_store_dwordx4 v[104:105], v[92:95], off
	global_load_dwordx4 v[92:95], v[114:115], off offset:528 nt
	s_nop 0
	global_load_dwordx4 v[96:99], v[114:115], off offset:512 nt
	s_waitcnt vmcnt(1)
	v_pk_fma_f32 v[94:95], v[86:87], v[102:103], v[94:95] op_sel_hi:[1,0,1]
	s_waitcnt vmcnt(0)
	v_pk_fma_f32 v[90:91], v[90:91], v[102:103], v[98:99] op_sel_hi:[1,0,1]
	v_pk_fma_f32 v[88:89], v[88:89], v[102:103], v[96:97] op_sel_hi:[1,0,1]
	v_pk_fma_f32 v[86:87], v[84:85], v[102:103], v[92:93] op_sel_hi:[1,0,1]
	v_mul_f32_e32 v84, v89, v89
	v_mul_f32_e32 v85, v91, v91
	v_fmac_f32_e32 v84, v88, v88
	v_fmac_f32_e32 v85, v90, v90
	v_add_f32_e32 v84, v84, v85
	v_mul_f32_e32 v85, v87, v87
	v_fmac_f32_e32 v85, v86, v86
	v_add_f32_e32 v84, v85, v84
	v_mul_f32_e32 v85, v95, v95
	v_fmac_f32_e32 v85, v94, v94
	v_add_f32_e32 v84, v85, v84
	v_add_f32_e32 v1, v1, v84
	v_cvt_pk_bf16_f32 v84, v88, v89
	v_cvt_pk_bf16_f32 v85, v90, v91
	v_cvt_pk_bf16_f32 v86, v86, v87
	v_cvt_pk_bf16_f32 v87, v94, v95
	global_store_dwordx4 v[104:105], v[84:87], off offset:256
	ds_swizzle_b32 v84, v1 offset:swizzle(SWAP,16)
	s_waitcnt lgkmcnt(0)
	v_add_f32_e32 v1, v1, v84
	v_mov_b32_e32 v84, v1
	s_nop 1
	v_permlane32_swap_b32_e32 v1, v84
	s_and_saveexec_b64 s[12:13], vcc
	s_cbranch_execz .LBB0_1228
	v_lshlrev_b64 v[86:87], 7, v[100:101]
	v_lshl_add_u64 v[86:87], s[22:23], 0, v[86:87]
	v_lshl_add_u64 v[86:87], s[60:61], 2, v[86:87]
	s_lshl_b32 s0, s46, 2
	v_lshl_add_u64 v[86:87], v[86:87], 0, s[0:1]
	v_add_f32_e32 v1, v1, v84
	global_store_dword v[86:87], v1, off
.LBB0_1228:
	s_or_b64 exec, exec, s[12:13]
	v_lshl_add_u64 v[84:85], v[148:149], 0, 48
	v_readlane_b32 s80, v252, 8
	v_readlane_b32 s81, v252, 9
	v_readlane_b32 s82, v252, 10
	v_readlane_b32 s83, v252, 11
	v_readlane_b32 s84, v252, 12
	v_readlane_b32 s85, v252, 13
	v_readlane_b32 s86, v252, 14
	v_readlane_b32 s87, v252, 15
	v_readlane_b32 s88, v252, 16
	v_readlane_b32 s89, v252, 17
	v_readlane_b32 s90, v252, 18
	v_readlane_b32 s91, v252, 19
	v_readlane_b32 s92, v252, 20
	v_readlane_b32 s93, v252, 21
	v_readlane_b32 s94, v252, 22
	v_readlane_b32 s95, v252, 23
	v_lshlrev_b64 v[88:89], 11, v[84:85]
	v_lshl_add_u64 v[96:97], v[88:89], 0, v[2:3]
	v_lshl_add_u64 v[98:99], v[96:97], 2, s[80:81]
	global_load_dwordx4 v[88:91], v[98:99], off offset:16 nt
	global_load_dwordx4 v[92:95], v[98:99], off nt
	v_mov_b32_e32 v86, v243
	s_waitcnt vmcnt(1)
	v_pk_fma_f32 v[90:91], v[78:79], v[86:87], v[90:91] op_sel_hi:[1,0,1]
	s_waitcnt vmcnt(0)
	v_pk_fma_f32 v[82:83], v[82:83], v[86:87], v[94:95] op_sel_hi:[1,0,1]
	v_pk_fma_f32 v[80:81], v[80:81], v[86:87], v[92:93] op_sel_hi:[1,0,1]
	v_pk_fma_f32 v[78:79], v[76:77], v[86:87], v[88:89] op_sel_hi:[1,0,1]
	v_mul_f32_e32 v1, v81, v81
	v_mul_f32_e32 v76, v83, v83
	v_fmac_f32_e32 v1, v80, v80
	v_fmac_f32_e32 v76, v82, v82
	v_add_f32_e32 v1, v1, v76
	v_mul_f32_e32 v76, v79, v79
	v_fmac_f32_e32 v76, v78, v78
	v_add_f32_e32 v1, v76, v1
	v_mul_f32_e32 v76, v91, v91
	v_fmac_f32_e32 v76, v90, v90
	v_lshl_add_u64 v[88:89], v[96:97], 1, s[54:55]
	v_add_f32_e32 v1, v76, v1
	v_cvt_pk_bf16_f32 v76, v80, v81
	v_cvt_pk_bf16_f32 v77, v82, v83
	v_cvt_pk_bf16_f32 v78, v78, v79
	v_cvt_pk_bf16_f32 v79, v90, v91
	global_store_dwordx4 v[88:89], v[76:79], off
	global_load_dwordx4 v[76:79], v[98:99], off offset:528 nt
	s_nop 0
	global_load_dwordx4 v[80:83], v[98:99], off offset:512 nt
	s_waitcnt vmcnt(1)
	v_pk_fma_f32 v[78:79], v[70:71], v[86:87], v[78:79] op_sel_hi:[1,0,1]
	s_waitcnt vmcnt(0)
	v_pk_fma_f32 v[74:75], v[74:75], v[86:87], v[82:83] op_sel_hi:[1,0,1]
	v_pk_fma_f32 v[72:73], v[72:73], v[86:87], v[80:81] op_sel_hi:[1,0,1]
	v_pk_fma_f32 v[70:71], v[68:69], v[86:87], v[76:77] op_sel_hi:[1,0,1]
	v_mul_f32_e32 v68, v73, v73
	v_mul_f32_e32 v69, v75, v75
	v_fmac_f32_e32 v68, v72, v72
	v_fmac_f32_e32 v69, v74, v74
	v_add_f32_e32 v68, v68, v69
	v_mul_f32_e32 v69, v71, v71
	v_fmac_f32_e32 v69, v70, v70
	v_add_f32_e32 v68, v69, v68
	v_mul_f32_e32 v69, v79, v79
	v_fmac_f32_e32 v69, v78, v78
	v_add_f32_e32 v68, v69, v68
	v_add_f32_e32 v1, v1, v68
	v_cvt_pk_bf16_f32 v68, v72, v73
	v_cvt_pk_bf16_f32 v69, v74, v75
	v_cvt_pk_bf16_f32 v70, v70, v71
	v_cvt_pk_bf16_f32 v71, v78, v79
	global_store_dwordx4 v[88:89], v[68:71], off offset:256
	ds_swizzle_b32 v68, v1 offset:swizzle(SWAP,16)
	s_waitcnt lgkmcnt(0)
	v_add_f32_e32 v1, v1, v68
	v_mov_b32_e32 v68, v1
	s_nop 1
	v_permlane32_swap_b32_e32 v1, v68
	s_and_saveexec_b64 s[12:13], vcc
	s_cbranch_execz .LBB0_1230
	v_lshlrev_b64 v[70:71], 7, v[84:85]
	v_lshl_add_u64 v[70:71], s[22:23], 0, v[70:71]
	v_lshl_add_u64 v[70:71], s[60:61], 2, v[70:71]
	s_lshl_b32 s0, s46, 2
	v_lshl_add_u64 v[70:71], v[70:71], 0, s[0:1]
	v_add_f32_e32 v1, v1, v68
	global_store_dword v[70:71], v1, off
; template <int K> __device__ __forceinline__ float shx(float v) { static_assert(K < 32, "use sum32"); return __int_as_float(__builtin_amdgcn_ds_swizzle(__float_as_int(v), (K << 10) | 0x1f)); }
; __device__ __forceinline__ float sum32(float v) { auto rr = __builtin_amdgcn_permlane32_swap(__float_as_uint(v), __float_as_uint(v), false, false); return __uint_as_float(rr[0]) + __uint_as_float(rr[1]); }
;     __device__ __forceinline__ void operator()(const f32x4 (&acc)[2][2][4][2], const Unit& u, int wr, int wc, int fr, int fq) const {
;     ...
;             for (int m = 0; m < 4; ++m) { const size_t row = (size_t)u.pm * BM + ai * HALF + wr * 64 + m * 16 + fr;
;                 float sc = 1.f; if (MID) sc = __builtin_amdgcn_rsqf(sum_f(ssql + row * 8, 2) * (1.0f / 1024.0f) + RMS_EPS);
;                 float ss = 0.f;
; #pragma unroll
;                 for (int bj = 0; bj < 2; ++bj) { const size_t o = row * 2048 + u.pn * BM + bj * HALF + wc * 32 + fq * 8;
;                     f32x4 r0, r1;
;                     if (residb) { const u32x4 w = __builtin_nontemporal_load((const u32x4*)(residb + o));     r0 = (f32x4){__uint_as_float(w.x << 16), __uint_as_float(w.x & 0xffff0000u), __uint_as_float(w.y << 16), __uint_as_float(w.y & 0xffff0000u)};
;                                   r1 = (f32x4){__uint_as_float(w.z << 16), __uint_as_float(w.z & 0xffff0000u), __uint_as_float(w.w << 16), __uint_as_float(w.w & 0xffff0000u)}; }
;                     else { r0 = __builtin_nontemporal_load((const f32x4*)(resid + o)); r1 = __builtin_nontemporal_load((const f32x4*)(resid + o + 4)); }
;                     const f32x4 v0 = r0 + acc[ai][bj][m][0] * sc, v1 = r1 + acc[ai][bj][m][1] * sc;
;                     if (outf) { __builtin_nontemporal_store(v0, (f32x4*)(outf + o)); __builtin_nontemporal_store(v1, (f32x4*)(outf + o + 4)); }
;                     ss += (v0[0] * v0[0] + v0[1] * v0[1]) + (v0[2] * v0[2] + v0[3] * v0[3]) + (v1[0] * v1[0] + v1[1] * v1[1]) + (v1[2] * v1[2] + v1[3] * v1[3]);
;                     if (outb) *(u32x4*)(outb + o) = pack8(v0, v1); }
;                 if (ssq_out) { ss += shx<16>(ss); ss = sum32(ss); if (fq == 0) ssq_out[row * 32 + u.pn * 4 + wc] = ss; }
;                 __builtin_amdgcn_sched_barrier(0); }
.LBB0_1230:
	s_or_b64 exec, exec, s[12:13]
	v_lshl_add_u64 v[68:69], v[148:149], 0, s[30:31]
	v_readlane_b32 s80, v252, 8
	v_readlane_b32 s81, v252, 9
	v_readlane_b32 s82, v252, 10
	v_readlane_b32 s83, v252, 11
	v_readlane_b32 s84, v252, 12
	v_readlane_b32 s85, v252, 13
	v_readlane_b32 s86, v252, 14
	v_readlane_b32 s87, v252, 15
	v_readlane_b32 s88, v252, 16
	v_readlane_b32 s89, v252, 17
	v_readlane_b32 s90, v252, 18
	v_readlane_b32 s91, v252, 19
	v_readlane_b32 s92, v252, 20
	v_readlane_b32 s93, v252, 21
	v_readlane_b32 s94, v252, 22
	v_readlane_b32 s95, v252, 23
	v_lshlrev_b64 v[72:73], 11, v[68:69]
	v_lshl_add_u64 v[80:81], v[72:73], 0, v[2:3]
	v_lshl_add_u64 v[82:83], v[80:81], 2, s[80:81]
	global_load_dwordx4 v[72:75], v[82:83], off offset:16 nt
	global_load_dwordx4 v[76:79], v[82:83], off nt
	v_mov_b32_e32 v70, v244
	s_waitcnt vmcnt(1)
	v_pk_fma_f32 v[74:75], v[62:63], v[70:71], v[74:75] op_sel_hi:[1,0,1]
	s_waitcnt vmcnt(0)
	v_pk_fma_f32 v[66:67], v[66:67], v[70:71], v[78:79] op_sel_hi:[1,0,1]
	v_pk_fma_f32 v[64:65], v[64:65], v[70:71], v[76:77] op_sel_hi:[1,0,1]
	v_pk_fma_f32 v[62:63], v[60:61], v[70:71], v[72:73] op_sel_hi:[1,0,1]
	v_mul_f32_e32 v1, v65, v65
	v_mul_f32_e32 v60, v67, v67
	v_fmac_f32_e32 v1, v64, v64
	v_fmac_f32_e32 v60, v66, v66
	v_add_f32_e32 v1, v1, v60
	v_mul_f32_e32 v60, v63, v63
	v_fmac_f32_e32 v60, v62, v62
	v_add_f32_e32 v1, v60, v1
	v_mul_f32_e32 v60, v75, v75
	v_fmac_f32_e32 v60, v74, v74
	v_lshl_add_u64 v[72:73], v[80:81], 1, s[54:55]
	v_add_f32_e32 v1, v60, v1
	v_cvt_pk_bf16_f32 v60, v64, v65
	v_cvt_pk_bf16_f32 v61, v66, v67
	v_cvt_pk_bf16_f32 v62, v62, v63
	v_cvt_pk_bf16_f32 v63, v74, v75
	global_store_dwordx4 v[72:73], v[60:63], off
	global_load_dwordx4 v[60:63], v[82:83], off offset:528 nt
	s_nop 0
	global_load_dwordx4 v[64:67], v[82:83], off offset:512 nt
	s_waitcnt vmcnt(1)
	v_pk_fma_f32 v[62:63], v[54:55], v[70:71], v[62:63] op_sel_hi:[1,0,1]
	s_waitcnt vmcnt(0)
	v_pk_fma_f32 v[58:59], v[58:59], v[70:71], v[66:67] op_sel_hi:[1,0,1]
	v_pk_fma_f32 v[56:57], v[56:57], v[70:71], v[64:65] op_sel_hi:[1,0,1]
	v_pk_fma_f32 v[54:55], v[52:53], v[70:71], v[60:61] op_sel_hi:[1,0,1]
	v_mul_f32_e32 v52, v57, v57
	v_mul_f32_e32 v53, v59, v59
	v_fmac_f32_e32 v52, v56, v56
	v_fmac_f32_e32 v53, v58, v58
	v_add_f32_e32 v52, v52, v53
	v_mul_f32_e32 v53, v55, v55
	v_fmac_f32_e32 v53, v54, v54
	v_add_f32_e32 v52, v53, v52
	v_mul_f32_e32 v53, v63, v63
	v_fmac_f32_e32 v53, v62, v62
	v_add_f32_e32 v52, v53, v52
	v_add_f32_e32 v1, v1, v52
	v_cvt_pk_bf16_f32 v52, v56, v57
	v_cvt_pk_bf16_f32 v53, v58, v59
	v_cvt_pk_bf16_f32 v54, v54, v55
	v_cvt_pk_bf16_f32 v55, v62, v63
	global_store_dwordx4 v[72:73], v[52:55], off offset:256
	ds_swizzle_b32 v52, v1 offset:swizzle(SWAP,16)
	s_waitcnt lgkmcnt(0)
	v_add_f32_e32 v1, v1, v52
	v_mov_b32_e32 v52, v1
	s_nop 1
	v_permlane32_swap_b32_e32 v1, v52
	s_and_saveexec_b64 s[12:13], vcc
	s_cbranch_execz .LBB0_1232
	v_lshlrev_b64 v[54:55], 7, v[68:69]
	v_lshl_add_u64 v[54:55], s[22:23], 0, v[54:55]
	v_lshl_add_u64 v[54:55], s[60:61], 2, v[54:55]
	s_lshl_b32 s0, s46, 2
	v_lshl_add_u64 v[54:55], v[54:55], 0, s[0:1]
	v_add_f32_e32 v1, v1, v52
	global_store_dword v[54:55], v1, off
.LBB0_1232:
	s_or_b64 exec, exec, s[12:13]
	s_mov_b64 s[12:13], 0x90
	v_lshl_add_u64 v[52:53], v[148:149], 0, s[12:13]
	v_readlane_b32 s80, v252, 8
	v_readlane_b32 s81, v252, 9
	v_readlane_b32 s82, v252, 10
	v_readlane_b32 s83, v252, 11
	v_readlane_b32 s84, v252, 12
	v_readlane_b32 s85, v252, 13
	v_readlane_b32 s86, v252, 14
	v_readlane_b32 s87, v252, 15
	v_readlane_b32 s88, v252, 16
	v_readlane_b32 s89, v252, 17
	v_readlane_b32 s90, v252, 18
	v_readlane_b32 s91, v252, 19
	v_readlane_b32 s92, v252, 20
	v_readlane_b32 s93, v252, 21
	v_readlane_b32 s94, v252, 22
	v_readlane_b32 s95, v252, 23
	v_lshlrev_b64 v[56:57], 11, v[52:53]
	v_lshl_add_u64 v[64:65], v[56:57], 0, v[2:3]
	v_lshl_add_u64 v[66:67], v[64:65], 2, s[80:81]
	global_load_dwordx4 v[56:59], v[66:67], off offset:16 nt
	global_load_dwordx4 v[60:63], v[66:67], off nt
	v_mov_b32_e32 v54, v245
	s_waitcnt vmcnt(1)
	v_pk_fma_f32 v[58:59], v[46:47], v[54:55], v[58:59] op_sel_hi:[1,0,1]
	s_waitcnt vmcnt(0)
	v_pk_fma_f32 v[50:51], v[50:51], v[54:55], v[62:63] op_sel_hi:[1,0,1]
	v_pk_fma_f32 v[48:49], v[48:49], v[54:55], v[60:61] op_sel_hi:[1,0,1]
	v_pk_fma_f32 v[46:47], v[44:45], v[54:55], v[56:57] op_sel_hi:[1,0,1]
	v_mul_f32_e32 v1, v49, v49
	v_mul_f32_e32 v44, v51, v51
	v_fmac_f32_e32 v1, v48, v48
	v_fmac_f32_e32 v44, v50, v50
	v_add_f32_e32 v1, v1, v44
	v_mul_f32_e32 v44, v47, v47
	v_fmac_f32_e32 v44, v46, v46
	v_add_f32_e32 v1, v44, v1
	v_mul_f32_e32 v44, v59, v59
	v_fmac_f32_e32 v44, v58, v58
	v_lshl_add_u64 v[56:57], v[64:65], 1, s[54:55]
	v_add_f32_e32 v1, v44, v1
	v_cvt_pk_bf16_f32 v44, v48, v49
	v_cvt_pk_bf16_f32 v45, v50, v51
	v_cvt_pk_bf16_f32 v46, v46, v47
	v_cvt_pk_bf16_f32 v47, v58, v59
	global_store_dwordx4 v[56:57], v[44:47], off
	global_load_dwordx4 v[44:47], v[66:67], off offset:528 nt
	s_nop 0
	global_load_dwordx4 v[48:51], v[66:67], off offset:512 nt
	s_waitcnt vmcnt(1)
	v_pk_fma_f32 v[46:47], v[38:39], v[54:55], v[46:47] op_sel_hi:[1,0,1]
	s_waitcnt vmcnt(0)
	v_pk_fma_f32 v[42:43], v[42:43], v[54:55], v[50:51] op_sel_hi:[1,0,1]
	v_pk_fma_f32 v[40:41], v[40:41], v[54:55], v[48:49] op_sel_hi:[1,0,1]
	v_pk_fma_f32 v[38:39], v[36:37], v[54:55], v[44:45] op_sel_hi:[1,0,1]
	v_mul_f32_e32 v36, v41, v41
	v_mul_f32_e32 v37, v43, v43
	v_fmac_f32_e32 v36, v40, v40
	v_fmac_f32_e32 v37, v42, v42
	v_add_f32_e32 v36, v36, v37
	v_mul_f32_e32 v37, v39, v39
	v_fmac_f32_e32 v37, v38, v38
	v_add_f32_e32 v36, v37, v36
	v_mul_f32_e32 v37, v47, v47
	v_fmac_f32_e32 v37, v46, v46
	v_add_f32_e32 v36, v37, v36
	v_add_f32_e32 v1, v1, v36
	v_cvt_pk_bf16_f32 v36, v40, v41
	v_cvt_pk_bf16_f32 v37, v42, v43
	v_cvt_pk_bf16_f32 v38, v38, v39
	v_cvt_pk_bf16_f32 v39, v46, v47
	global_store_dwordx4 v[56:57], v[36:39], off offset:256
	ds_swizzle_b32 v36, v1 offset:swizzle(SWAP,16)
	s_waitcnt lgkmcnt(0)
	v_add_f32_e32 v1, v1, v36
	v_mov_b32_e32 v36, v1
	s_nop 1
	v_permlane32_swap_b32_e32 v1, v36
	s_and_saveexec_b64 s[12:13], vcc
	s_cbranch_execz .LBB0_1234
	v_lshlrev_b64 v[38:39], 7, v[52:53]
	v_lshl_add_u64 v[38:39], s[22:23], 0, v[38:39]
	v_lshl_add_u64 v[38:39], s[60:61], 2, v[38:39]
	s_lshl_b32 s0, s46, 2
	v_lshl_add_u64 v[38:39], v[38:39], 0, s[0:1]
	v_add_f32_e32 v1, v1, v36
	global_store_dword v[38:39], v1, off
; template <int K> __device__ __forceinline__ float shx(float v) { static_assert(K < 32, "use sum32"); return __int_as_float(__builtin_amdgcn_ds_swizzle(__float_as_int(v), (K << 10) | 0x1f)); }
; __device__ __forceinline__ float sum32(float v) { auto rr = __builtin_amdgcn_permlane32_swap(__float_as_uint(v), __float_as_uint(v), false, false); return __uint_as_float(rr[0]) + __uint_as_float(rr[1]); }
;     __device__ __forceinline__ void operator()(const f32x4 (&acc)[2][2][4][2], const Unit& u, int wr, int wc, int fr, int fq) const {
;     ...
;             for (int m = 0; m < 4; ++m) { const size_t row = (size_t)u.pm * BM + ai * HALF + wr * 64 + m * 16 + fr;
;                 float sc = 1.f; if (MID) sc = __builtin_amdgcn_rsqf(sum_f(ssql + row * 8, 2) * (1.0f / 1024.0f) + RMS_EPS);
;                 float ss = 0.f;
; #pragma unroll
;                 for (int bj = 0; bj < 2; ++bj) { const size_t o = row * 2048 + u.pn * BM + bj * HALF + wc * 32 + fq * 8;
;                     f32x4 r0, r1;
;                     if (residb) { const u32x4 w = __builtin_nontemporal_load((const u32x4*)(residb + o));     r0 = (f32x4){__uint_as_float(w.x << 16), __uint_as_float(w.x & 0xffff0000u), __uint_as_float(w.y << 16), __uint_as_float(w.y & 0xffff0000u)};
;                                   r1 = (f32x4){__uint_as_float(w.z << 16), __uint_as_float(w.z & 0xffff0000u), __uint_as_float(w.w << 16), __uint_as_float(w.w & 0xffff0000u)}; }
;                     else { r0 = __builtin_nontemporal_load((const f32x4*)(resid + o)); r1 = __builtin_nontemporal_load((const f32x4*)(resid + o + 4)); }
;                     const f32x4 v0 = r0 + acc[ai][bj][m][0] * sc, v1 = r1 + acc[ai][bj][m][1] * sc;
;                     if (outf) { __builtin_nontemporal_store(v0, (f32x4*)(outf + o)); __builtin_nontemporal_store(v1, (f32x4*)(outf + o + 4)); }
;                     ss += (v0[0] * v0[0] + v0[1] * v0[1]) + (v0[2] * v0[2] + v0[3] * v0[3]) + (v1[0] * v1[0] + v1[1] * v1[1]) + (v1[2] * v1[2] + v1[3] * v1[3]);
;                     if (outb) *(u32x4*)(outb + o) = pack8(v0, v1); }
;                 if (ssq_out) { ss += shx<16>(ss); ss = sum32(ss); if (fq == 0) ssq_out[row * 32 + u.pn * 4 + wc] = ss; }
;                 __builtin_amdgcn_sched_barrier(0); }
.LBB0_1234:
	s_or_b64 exec, exec, s[12:13]
	s_mov_b64 s[12:13], 0xa0
	v_lshl_add_u64 v[36:37], v[148:149], 0, s[12:13]
	v_readlane_b32 s80, v252, 8
	v_readlane_b32 s81, v252, 9
	v_readlane_b32 s82, v252, 10
	v_readlane_b32 s83, v252, 11
	v_readlane_b32 s84, v252, 12
	v_readlane_b32 s85, v252, 13
	v_readlane_b32 s86, v252, 14
	v_readlane_b32 s87, v252, 15
	v_readlane_b32 s88, v252, 16
	v_readlane_b32 s89, v252, 17
	v_readlane_b32 s90, v252, 18
	v_readlane_b32 s91, v252, 19
	v_readlane_b32 s92, v252, 20
	v_readlane_b32 s93, v252, 21
	v_readlane_b32 s94, v252, 22
	v_readlane_b32 s95, v252, 23
	v_lshlrev_b64 v[40:41], 11, v[36:37]
	v_lshl_add_u64 v[48:49], v[40:41], 0, v[2:3]
	v_lshl_add_u64 v[50:51], v[48:49], 2, s[80:81]
	global_load_dwordx4 v[40:43], v[50:51], off offset:16 nt
	global_load_dwordx4 v[44:47], v[50:51], off nt
	v_mov_b32_e32 v38, v246
	s_waitcnt vmcnt(1)
	v_pk_fma_f32 v[42:43], v[30:31], v[38:39], v[42:43] op_sel_hi:[1,0,1]
	s_waitcnt vmcnt(0)
	v_pk_fma_f32 v[34:35], v[34:35], v[38:39], v[46:47] op_sel_hi:[1,0,1]
	v_pk_fma_f32 v[32:33], v[32:33], v[38:39], v[44:45] op_sel_hi:[1,0,1]
	v_pk_fma_f32 v[30:31], v[28:29], v[38:39], v[40:41] op_sel_hi:[1,0,1]
	v_mul_f32_e32 v1, v33, v33
	v_mul_f32_e32 v28, v35, v35
	v_fmac_f32_e32 v1, v32, v32
	v_fmac_f32_e32 v28, v34, v34
	v_add_f32_e32 v1, v1, v28
	v_mul_f32_e32 v28, v31, v31
	v_fmac_f32_e32 v28, v30, v30
	v_add_f32_e32 v1, v28, v1
	v_mul_f32_e32 v28, v43, v43
	v_fmac_f32_e32 v28, v42, v42
	v_lshl_add_u64 v[40:41], v[48:49], 1, s[54:55]
	v_add_f32_e32 v1, v28, v1
	v_cvt_pk_bf16_f32 v28, v32, v33
	v_cvt_pk_bf16_f32 v29, v34, v35
	v_cvt_pk_bf16_f32 v30, v30, v31
	v_cvt_pk_bf16_f32 v31, v42, v43
	global_store_dwordx4 v[40:41], v[28:31], off
	global_load_dwordx4 v[28:31], v[50:51], off offset:528 nt
	s_nop 0
	global_load_dwordx4 v[32:35], v[50:51], off offset:512 nt
	s_waitcnt vmcnt(1)
	v_pk_fma_f32 v[30:31], v[22:23], v[38:39], v[30:31] op_sel_hi:[1,0,1]
	s_waitcnt vmcnt(0)
	v_pk_fma_f32 v[26:27], v[26:27], v[38:39], v[34:35] op_sel_hi:[1,0,1]
	v_pk_fma_f32 v[24:25], v[24:25], v[38:39], v[32:33] op_sel_hi:[1,0,1]
	v_pk_fma_f32 v[22:23], v[20:21], v[38:39], v[28:29] op_sel_hi:[1,0,1]
	v_mul_f32_e32 v20, v25, v25
	v_mul_f32_e32 v21, v27, v27
	v_fmac_f32_e32 v20, v24, v24
	v_fmac_f32_e32 v21, v26, v26
	v_add_f32_e32 v20, v20, v21
	v_mul_f32_e32 v21, v23, v23
	v_fmac_f32_e32 v21, v22, v22
	v_add_f32_e32 v20, v21, v20
	v_mul_f32_e32 v21, v31, v31
	v_fmac_f32_e32 v21, v30, v30
	v_add_f32_e32 v20, v21, v20
	v_add_f32_e32 v1, v1, v20
	v_cvt_pk_bf16_f32 v20, v24, v25
	v_cvt_pk_bf16_f32 v21, v26, v27
	v_cvt_pk_bf16_f32 v22, v22, v23
	v_cvt_pk_bf16_f32 v23, v30, v31
	global_store_dwordx4 v[40:41], v[20:23], off offset:256
	ds_swizzle_b32 v20, v1 offset:swizzle(SWAP,16)
	s_waitcnt lgkmcnt(0)
	v_add_f32_e32 v1, v1, v20
	v_mov_b32_e32 v20, v1
	s_nop 1
	v_permlane32_swap_b32_e32 v1, v20
	s_and_saveexec_b64 s[12:13], vcc
	s_cbranch_execz .LBB0_1236
	v_lshlrev_b64 v[22:23], 7, v[36:37]
	v_lshl_add_u64 v[22:23], s[22:23], 0, v[22:23]
	v_lshl_add_u64 v[22:23], s[60:61], 2, v[22:23]
	s_lshl_b32 s0, s46, 2
	v_lshl_add_u64 v[22:23], v[22:23], 0, s[0:1]
	v_add_f32_e32 v1, v1, v20
	global_store_dword v[22:23], v1, off
.LBB0_1236:
	s_or_b64 exec, exec, s[12:13]
	s_mov_b64 s[12:13], 0xb0
	v_lshl_add_u64 v[20:21], v[148:149], 0, s[12:13]
	v_readlane_b32 s80, v252, 8
	v_readlane_b32 s81, v252, 9
	v_readlane_b32 s82, v252, 10
	v_readlane_b32 s83, v252, 11
	v_readlane_b32 s84, v252, 12
	v_readlane_b32 s85, v252, 13
	v_readlane_b32 s86, v252, 14
	v_readlane_b32 s87, v252, 15
	v_readlane_b32 s88, v252, 16
	v_readlane_b32 s89, v252, 17
	v_readlane_b32 s90, v252, 18
	v_readlane_b32 s91, v252, 19
	v_readlane_b32 s92, v252, 20
	v_readlane_b32 s93, v252, 21
	v_readlane_b32 s94, v252, 22
	v_readlane_b32 s95, v252, 23
	v_lshlrev_b64 v[24:25], 11, v[20:21]
	v_lshl_add_u64 v[2:3], v[24:25], 0, v[2:3]
	v_lshl_add_u64 v[32:33], v[2:3], 2, s[80:81]
	global_load_dwordx4 v[24:27], v[32:33], off offset:16 nt
	global_load_dwordx4 v[28:31], v[32:33], off nt
	v_mov_b32_e32 v22, v247
	s_waitcnt vmcnt(1)
	v_pk_fma_f32 v[26:27], v[14:15], v[22:23], v[26:27] op_sel_hi:[1,0,1]
	s_waitcnt vmcnt(0)
	v_pk_fma_f32 v[18:19], v[18:19], v[22:23], v[30:31] op_sel_hi:[1,0,1]
	v_pk_fma_f32 v[16:17], v[16:17], v[22:23], v[28:29] op_sel_hi:[1,0,1]
	v_pk_fma_f32 v[14:15], v[12:13], v[22:23], v[24:25] op_sel_hi:[1,0,1]
	v_mul_f32_e32 v1, v17, v17
	v_mul_f32_e32 v12, v19, v19
	v_fmac_f32_e32 v1, v16, v16
	v_fmac_f32_e32 v12, v18, v18
	v_add_f32_e32 v1, v1, v12
	v_mul_f32_e32 v12, v15, v15
	v_fmac_f32_e32 v12, v14, v14
	v_add_f32_e32 v1, v12, v1
	v_mul_f32_e32 v12, v27, v27
	v_fmac_f32_e32 v12, v26, v26
	v_lshl_add_u64 v[24:25], v[2:3], 1, s[54:55]
	v_add_f32_e32 v1, v12, v1
	v_cvt_pk_bf16_f32 v12, v16, v17
	v_cvt_pk_bf16_f32 v13, v18, v19
	v_cvt_pk_bf16_f32 v14, v14, v15
	v_cvt_pk_bf16_f32 v15, v26, v27
	global_store_dwordx4 v[24:25], v[12:15], off
	global_load_dwordx4 v[12:15], v[32:33], off offset:528 nt
	s_nop 0
	global_load_dwordx4 v[16:19], v[32:33], off offset:512 nt
	s_waitcnt vmcnt(1)
	v_pk_fma_f32 v[4:5], v[4:5], v[22:23], v[12:13] op_sel_hi:[1,0,1]
	s_waitcnt vmcnt(0)
	v_pk_fma_f32 v[10:11], v[10:11], v[22:23], v[18:19] op_sel_hi:[1,0,1]
	v_pk_fma_f32 v[2:3], v[8:9], v[22:23], v[16:17] op_sel_hi:[1,0,1]
	v_mul_f32_e32 v9, v11, v11
	v_mul_f32_e32 v8, v3, v3
	v_fmac_f32_e32 v8, v2, v2
	v_fmac_f32_e32 v9, v10, v10
	v_add_f32_e32 v8, v8, v9
	v_mul_f32_e32 v9, v5, v5
	v_pk_fma_f32 v[6:7], v[6:7], v[22:23], v[14:15] op_sel_hi:[1,0,1]
	v_fmac_f32_e32 v9, v4, v4
	v_add_f32_e32 v8, v9, v8
	v_mul_f32_e32 v9, v7, v7
	v_fmac_f32_e32 v9, v6, v6
	v_add_f32_e32 v8, v9, v8
	v_add_f32_e32 v1, v1, v8
	v_cvt_pk_bf16_f32 v2, v2, v3
	v_cvt_pk_bf16_f32 v3, v10, v11
	v_cvt_pk_bf16_f32 v4, v4, v5
	v_cvt_pk_bf16_f32 v5, v6, v7
	global_store_dwordx4 v[24:25], v[2:5], off offset:256
	ds_swizzle_b32 v2, v1 offset:swizzle(SWAP,16)
	s_waitcnt lgkmcnt(0)
	v_add_f32_e32 v1, v1, v2
	v_mov_b32_e32 v2, v1
	s_nop 1
	v_permlane32_swap_b32_e32 v1, v2
	s_and_saveexec_b64 s[12:13], vcc
	s_cbranch_execz .LBB0_1238
	v_lshlrev_b64 v[4:5], 7, v[20:21]
	v_lshl_add_u64 v[4:5], s[22:23], 0, v[4:5]
	v_lshl_add_u64 v[4:5], s[60:61], 2, v[4:5]
	s_lshl_b32 s0, s46, 2
	v_lshl_add_u64 v[4:5], v[4:5], 0, s[0:1]
	v_add_f32_e32 v1, v1, v2
	global_store_dword v[4:5], v1, off

; template <int K> __device__ __forceinline__ float shx(float v) { static_assert(K < 32, "use sum32"); return __int_as_float(__builtin_amdgcn_ds_swizzle(__float_as_int(v), (K << 10) | 0x1f)); }
; __device__ __forceinline__ int crow(int r, int hi) { return (r & 3) + 8 * (r >> 2) + 4 * hi; }
; template <class TIn, class TOut, int ost, bool HAS_SS>
; __device__ __forceinline__ void causal_swa_block(const BlockRef<TIn, TOut>& cur_, const BlockRef<TIn, TOut>& nxt_, int skv, int W, char* lds, Seam<TIn>& S, int cbl  ) {
;     ...
;     if (hi == 0) li_l[r32] = l_reg; asm volatile("s_waitcnt lgkmcnt(0)" ::: "memory");
;     float rli[16];
; #pragma unroll
;     for (int r = 0; r < 16; ++r) rli[r] = __builtin_amdgcn_rcpf(li_l[crow(r, hi)]);
;     int r32e = r32, hie = hi; asm volatile("" : "+v"(r32e), "+v"(hie));
;     char* Ob = (char*)cur.O; const unsigned ob0 = (unsigned)((wid * QBLK + 4 * hie) * ost + r32e) * 2u;
; #pragma unroll
;     for (int r = 0; r < 16; ++r) { const unsigned rowoff = ob0 + (unsigned)(((r & 3) + 8 * (r >> 2)) * ost * 2); float ss_ = 0.f;
; #pragma unroll
;         for (int d0 = 0; d0 < 4; ++d0) { const float v = o[d0][r] * rli[r]; ss_ += v * v;
;             const float vn = shx<1>(v);
;             if ((r32e & 1) == 0) *(unsigned*)(Ob + rowoff + d0 * 64) = cvtpk(v, vn); }
.LBB0_1543:
	s_or_b64 exec, exec, s[12:13]
	s_waitcnt lgkmcnt(0)
	ds_read_b128 v[76:79], v157
	ds_read_b128 v[72:75], v157 offset:32
	ds_read_b128 v[68:71], v157 offset:64
	ds_read_b128 v[64:67], v157 offset:96
	s_waitcnt lgkmcnt(3)
	v_rcp_f32_e32 v76, v76
	v_lshlrev_b32_e32 v80, 12, v151
	s_lshl_b32 s12, s23, 10
	v_lshlrev_b32_e32 v81, 1, v150
	v_mul_f32_e32 v0, v0, v76
	s_nop 1
	v_mov_b32_dpp v82, v0 quad_perm:[1,0,3,2] row_mask:0xf bank_mask:0xf
	v_add3_u32 v144, v81, s12, v80
	v_and_b32_e32 v80, 1, v150
	v_cmp_eq_u32_e32 vcc, 0, v80
	v_lshl_add_u64 v[80:81], s[0:1], 0, v[144:145]
	s_and_saveexec_b64 s[12:13], vcc
	s_cbranch_execz .LBB0_1545
	s_waitcnt lgkmcnt(0)
	v_cvt_pk_bf16_f32 v0, v0, v82
	global_store_dword v[80:81], v0, off
.LBB0_1545:
	s_or_b64 exec, exec, s[12:13]
	v_mul_f32_e32 v0, v16, v76
	s_nop 1
	v_mov_b32_dpp v16, v0 quad_perm:[1,0,3,2] row_mask:0xf bank_mask:0xf
	s_and_saveexec_b64 s[12:13], vcc
	s_cbranch_execz .LBB0_1547
	s_waitcnt lgkmcnt(0)
	v_cvt_pk_bf16_f32 v0, v0, v16
	global_store_dword v[80:81], v0, off offset:64
.LBB0_1547:
	s_or_b64 exec, exec, s[12:13]
	v_mul_f32_e32 v0, v32, v76
	s_waitcnt lgkmcnt(0)
	s_nop 1
	v_mov_b32_dpp v16, v0 quad_perm:[1,0,3,2] row_mask:0xf bank_mask:0xf
	s_and_saveexec_b64 s[12:13], vcc
	s_cbranch_execz .LBB0_1549
	s_waitcnt lgkmcnt(0)
	v_cvt_pk_bf16_f32 v0, v0, v16
	global_store_dword v[80:81], v0, off offset:128
.LBB0_1549:
	s_or_b64 exec, exec, s[12:13]
	v_mul_f32_e32 v0, v48, v76
	s_waitcnt lgkmcnt(0)
	s_nop 1
	v_mov_b32_dpp v16, v0 quad_perm:[1,0,3,2] row_mask:0xf bank_mask:0xf
	s_and_saveexec_b64 s[12:13], vcc
	s_cbranch_execz .LBB0_1551
	s_waitcnt lgkmcnt(0)
	v_cvt_pk_bf16_f32 v0, v0, v16
	global_store_dword v[80:81], v0, off offset:192
.LBB0_1551:
	s_or_b64 exec, exec, s[12:13]
	s_waitcnt lgkmcnt(0)
	v_rcp_f32_e32 v16, v77
	s_nop 0
	v_mul_f32_e32 v32, v1, v16
	s_nop 1
	v_mov_b32_dpp v48, v32 quad_perm:[1,0,3,2] row_mask:0xf bank_mask:0xf
	v_add_u32_e32 v0, 0x400, v144
	v_mov_b32_e32 v1, v145
	v_lshl_add_u64 v[0:1], s[0:1], 0, v[0:1]
	s_and_saveexec_b64 s[12:13], vcc
	s_cbranch_execz .LBB0_1553
	s_waitcnt lgkmcnt(0)
	v_cvt_pk_bf16_f32 v32, v32, v48
	global_store_dword v[0:1], v32, off
.LBB0_1553:
	s_or_b64 exec, exec, s[12:13]
	v_mul_f32_e32 v17, v17, v16
	s_nop 1
	v_mov_b32_dpp v32, v17 quad_perm:[1,0,3,2] row_mask:0xf bank_mask:0xf
	s_and_saveexec_b64 s[12:13], vcc
	s_cbranch_execz .LBB0_1555
	s_waitcnt lgkmcnt(0)
	v_cvt_pk_bf16_f32 v17, v17, v32
	global_store_dword v[0:1], v17, off offset:64
.LBB0_1555:
	s_or_b64 exec, exec, s[12:13]
	v_mul_f32_e32 v17, v33, v16
	s_waitcnt lgkmcnt(0)
	s_nop 1
	v_mov_b32_dpp v32, v17 quad_perm:[1,0,3,2] row_mask:0xf bank_mask:0xf
	s_and_saveexec_b64 s[12:13], vcc
	s_cbranch_execz .LBB0_1557
	s_waitcnt lgkmcnt(0)
	v_cvt_pk_bf16_f32 v17, v17, v32
	global_store_dword v[0:1], v17, off offset:128
.LBB0_1557:
	s_or_b64 exec, exec, s[12:13]
	v_mul_f32_e32 v16, v49, v16
	s_nop 1
	v_mov_b32_dpp v17, v16 quad_perm:[1,0,3,2] row_mask:0xf bank_mask:0xf
	s_and_saveexec_b64 s[12:13], vcc
	s_cbranch_execz .LBB0_1559
	s_waitcnt lgkmcnt(0)
	v_cvt_pk_bf16_f32 v16, v16, v17
	global_store_dword v[0:1], v16, off offset:192
.LBB0_1559:
	s_or_b64 exec, exec, s[12:13]
	v_rcp_f32_e32 v16, v78
	s_nop 0
	v_mul_f32_e32 v2, v2, v16
	s_waitcnt lgkmcnt(0)
	s_nop 1
	v_mov_b32_dpp v17, v2 quad_perm:[1,0,3,2] row_mask:0xf bank_mask:0xf
	v_add_u32_e32 v0, 0x800, v144
	v_mov_b32_e32 v1, v145
	v_lshl_add_u64 v[0:1], s[0:1], 0, v[0:1]
	s_and_saveexec_b64 s[12:13], vcc
	s_cbranch_execz .LBB0_1561
	s_waitcnt lgkmcnt(0)
	v_cvt_pk_bf16_f32 v2, v2, v17
	global_store_dword v[0:1], v2, off
.LBB0_1561:
	s_or_b64 exec, exec, s[12:13]
	v_mul_f32_e32 v2, v18, v16
	s_waitcnt lgkmcnt(0)
	s_nop 1
	v_mov_b32_dpp v17, v2 quad_perm:[1,0,3,2] row_mask:0xf bank_mask:0xf
	s_and_saveexec_b64 s[12:13], vcc
	s_cbranch_execz .LBB0_1563
	s_waitcnt lgkmcnt(0)
	v_cvt_pk_bf16_f32 v2, v2, v17
	global_store_dword v[0:1], v2, off offset:64
.LBB0_1563:
	s_or_b64 exec, exec, s[12:13]
	v_mul_f32_e32 v2, v34, v16
	s_waitcnt lgkmcnt(0)
	s_nop 1
	v_mov_b32_dpp v17, v2 quad_perm:[1,0,3,2] row_mask:0xf bank_mask:0xf
	s_and_saveexec_b64 s[12:13], vcc
	s_cbranch_execz .LBB0_1565
	s_waitcnt lgkmcnt(0)
	v_cvt_pk_bf16_f32 v2, v2, v17
	global_store_dword v[0:1], v2, off offset:128
.LBB0_1565:
	s_or_b64 exec, exec, s[12:13]
	v_mul_f32_e32 v2, v50, v16
	s_nop 1
	v_mov_b32_dpp v16, v2 quad_perm:[1,0,3,2] row_mask:0xf bank_mask:0xf
	s_and_saveexec_b64 s[12:13], vcc
	s_cbranch_execz .LBB0_1567
	s_waitcnt lgkmcnt(0)
	v_cvt_pk_bf16_f32 v2, v2, v16
	global_store_dword v[0:1], v2, off offset:192
.LBB0_1567:
	s_or_b64 exec, exec, s[12:13]
	v_rcp_f32_e32 v2, v79
	s_nop 0
	v_mul_f32_e32 v3, v3, v2
	s_waitcnt lgkmcnt(0)
	s_nop 1
	v_mov_b32_dpp v16, v3 quad_perm:[1,0,3,2] row_mask:0xf bank_mask:0xf
	v_add_u32_e32 v0, 0xc00, v144
	v_mov_b32_e32 v1, v145
	v_lshl_add_u64 v[0:1], s[0:1], 0, v[0:1]
	s_and_saveexec_b64 s[12:13], vcc
	s_cbranch_execz .LBB0_1569
	s_waitcnt lgkmcnt(0)
	v_cvt_pk_bf16_f32 v3, v3, v16
	global_store_dword v[0:1], v3, off
.LBB0_1569:
	s_or_b64 exec, exec, s[12:13]
	v_mul_f32_e32 v3, v19, v2
	s_waitcnt lgkmcnt(0)
	s_nop 1
	v_mov_b32_dpp v16, v3 quad_perm:[1,0,3,2] row_mask:0xf bank_mask:0xf
	s_and_saveexec_b64 s[12:13], vcc
	s_cbranch_execz .LBB0_1571
	s_waitcnt lgkmcnt(0)
	v_cvt_pk_bf16_f32 v3, v3, v16
	global_store_dword v[0:1], v3, off offset:64
.LBB0_1571:
	s_or_b64 exec, exec, s[12:13]
	v_mul_f32_e32 v3, v35, v2
	s_waitcnt lgkmcnt(0)
	s_nop 1
	v_mov_b32_dpp v16, v3 quad_perm:[1,0,3,2] row_mask:0xf bank_mask:0xf
	s_and_saveexec_b64 s[12:13], vcc
	s_cbranch_execz .LBB0_1573
	s_waitcnt lgkmcnt(0)
	v_cvt_pk_bf16_f32 v3, v3, v16
	global_store_dword v[0:1], v3, off offset:128
; template <int K> __device__ __forceinline__ float shx(float v) { static_assert(K < 32, "use sum32"); return __int_as_float(__builtin_amdgcn_ds_swizzle(__float_as_int(v), (K << 10) | 0x1f)); }
; __device__ __forceinline__ int crow(int r, int hi) { return (r & 3) + 8 * (r >> 2) + 4 * hi; }
; template <class TIn, class TOut, int ost, bool HAS_SS>
; __device__ __forceinline__ void causal_swa_block(const BlockRef<TIn, TOut>& cur_, const BlockRef<TIn, TOut>& nxt_, int skv, int W, char* lds, Seam<TIn>& S, int cbl  ) {
;     ...
;     if (hi == 0) li_l[r32] = l_reg; asm volatile("s_waitcnt lgkmcnt(0)" ::: "memory");
;     float rli[16];
; #pragma unroll
;     for (int r = 0; r < 16; ++r) rli[r] = __builtin_amdgcn_rcpf(li_l[crow(r, hi)]);
;     int r32e = r32, hie = hi; asm volatile("" : "+v"(r32e), "+v"(hie));
;     char* Ob = (char*)cur.O; const unsigned ob0 = (unsigned)((wid * QBLK + 4 * hie) * ost + r32e) * 2u;
; #pragma unroll
;     for (int r = 0; r < 16; ++r) { const unsigned rowoff = ob0 + (unsigned)(((r & 3) + 8 * (r >> 2)) * ost * 2); float ss_ = 0.f;
; #pragma unroll
;         for (int d0 = 0; d0 < 4; ++d0) { const float v = o[d0][r] * rli[r]; ss_ += v * v;
;             const float vn = shx<1>(v);
;             if ((r32e & 1) == 0) *(unsigned*)(Ob + rowoff + d0 * 64) = cvtpk(v, vn); }
.LBB0_1573:
	s_or_b64 exec, exec, s[12:13]
	v_mul_f32_e32 v2, v51, v2
	s_nop 1
	v_mov_b32_dpp v3, v2 quad_perm:[1,0,3,2] row_mask:0xf bank_mask:0xf
	s_and_saveexec_b64 s[12:13], vcc
	s_cbranch_execz .LBB0_1575
	s_waitcnt lgkmcnt(0)
	v_cvt_pk_bf16_f32 v2, v2, v3
	global_store_dword v[0:1], v2, off offset:192
.LBB0_1575:
	s_or_b64 exec, exec, s[12:13]
	v_rcp_f32_e32 v2, v72
	s_waitcnt lgkmcnt(0)
	v_mul_f32_e32 v3, v4, v2
	s_nop 1
	v_mov_b32_dpp v4, v3 quad_perm:[1,0,3,2] row_mask:0xf bank_mask:0xf
	v_add_u32_e32 v0, 0x2000, v144
	v_mov_b32_e32 v1, v145
	v_lshl_add_u64 v[0:1], s[0:1], 0, v[0:1]
	s_and_saveexec_b64 s[12:13], vcc
	s_cbranch_execz .LBB0_1577
	s_waitcnt lgkmcnt(0)
	v_cvt_pk_bf16_f32 v3, v3, v4
	global_store_dword v[0:1], v3, off
.LBB0_1577:
	s_or_b64 exec, exec, s[12:13]
	v_mul_f32_e32 v3, v20, v2
	s_waitcnt lgkmcnt(0)
	s_nop 1
	v_mov_b32_dpp v4, v3 quad_perm:[1,0,3,2] row_mask:0xf bank_mask:0xf
	s_and_saveexec_b64 s[12:13], vcc
	s_cbranch_execz .LBB0_1579
	s_waitcnt lgkmcnt(0)
	v_cvt_pk_bf16_f32 v3, v3, v4
	global_store_dword v[0:1], v3, off offset:64
.LBB0_1579:
	s_or_b64 exec, exec, s[12:13]
	v_mul_f32_e32 v3, v36, v2
	s_waitcnt lgkmcnt(0)
	s_nop 1
	v_mov_b32_dpp v4, v3 quad_perm:[1,0,3,2] row_mask:0xf bank_mask:0xf
	s_and_saveexec_b64 s[12:13], vcc
	s_cbranch_execz .LBB0_1581
	s_waitcnt lgkmcnt(0)
	v_cvt_pk_bf16_f32 v3, v3, v4
	global_store_dword v[0:1], v3, off offset:128
.LBB0_1581:
	s_or_b64 exec, exec, s[12:13]
	v_mul_f32_e32 v2, v52, v2
	s_nop 1
	v_mov_b32_dpp v3, v2 quad_perm:[1,0,3,2] row_mask:0xf bank_mask:0xf
	s_and_saveexec_b64 s[12:13], vcc
	s_cbranch_execz .LBB0_1583
	s_waitcnt lgkmcnt(0)
	v_cvt_pk_bf16_f32 v2, v2, v3
	global_store_dword v[0:1], v2, off offset:192
.LBB0_1583:
	s_or_b64 exec, exec, s[12:13]
	v_rcp_f32_e32 v2, v73
	s_waitcnt lgkmcnt(0)
	v_mul_f32_e32 v3, v5, v2
	s_nop 1
	v_mov_b32_dpp v4, v3 quad_perm:[1,0,3,2] row_mask:0xf bank_mask:0xf
	v_add_u32_e32 v0, 0x2400, v144
	v_mov_b32_e32 v1, v145
	v_lshl_add_u64 v[0:1], s[0:1], 0, v[0:1]
	s_and_saveexec_b64 s[12:13], vcc
	s_cbranch_execz .LBB0_1585
	s_waitcnt lgkmcnt(0)
	v_cvt_pk_bf16_f32 v3, v3, v4
	global_store_dword v[0:1], v3, off
.LBB0_1585:
	s_or_b64 exec, exec, s[12:13]
	v_mul_f32_e32 v3, v21, v2
	s_waitcnt lgkmcnt(0)
	s_nop 1
	v_mov_b32_dpp v4, v3 quad_perm:[1,0,3,2] row_mask:0xf bank_mask:0xf
	s_and_saveexec_b64 s[12:13], vcc
	s_cbranch_execz .LBB0_1587
	s_waitcnt lgkmcnt(0)
	v_cvt_pk_bf16_f32 v3, v3, v4
	global_store_dword v[0:1], v3, off offset:64
.LBB0_1587:
	s_or_b64 exec, exec, s[12:13]
	v_mul_f32_e32 v3, v37, v2
	s_waitcnt lgkmcnt(0)
	s_nop 1
	v_mov_b32_dpp v4, v3 quad_perm:[1,0,3,2] row_mask:0xf bank_mask:0xf
	s_and_saveexec_b64 s[12:13], vcc
	s_cbranch_execz .LBB0_1589
	s_waitcnt lgkmcnt(0)
	v_cvt_pk_bf16_f32 v3, v3, v4
	global_store_dword v[0:1], v3, off offset:128
.LBB0_1589:
	s_or_b64 exec, exec, s[12:13]
	v_mul_f32_e32 v2, v53, v2
	s_nop 1
	v_mov_b32_dpp v3, v2 quad_perm:[1,0,3,2] row_mask:0xf bank_mask:0xf
	s_and_saveexec_b64 s[12:13], vcc
	s_cbranch_execz .LBB0_1591
	s_waitcnt lgkmcnt(0)
	v_cvt_pk_bf16_f32 v2, v2, v3
	global_store_dword v[0:1], v2, off offset:192
.LBB0_1591:
	s_or_b64 exec, exec, s[12:13]
	v_rcp_f32_e32 v2, v74
	s_waitcnt lgkmcnt(0)
	v_mul_f32_e32 v3, v6, v2
	s_nop 1
	v_mov_b32_dpp v4, v3 quad_perm:[1,0,3,2] row_mask:0xf bank_mask:0xf
	v_add_u32_e32 v0, 0x2800, v144
	v_mov_b32_e32 v1, v145
	v_lshl_add_u64 v[0:1], s[0:1], 0, v[0:1]
	s_and_saveexec_b64 s[12:13], vcc
	s_cbranch_execz .LBB0_1593
	s_waitcnt lgkmcnt(0)
	v_cvt_pk_bf16_f32 v3, v3, v4
	global_store_dword v[0:1], v3, off
.LBB0_1593:
	s_or_b64 exec, exec, s[12:13]
	v_mul_f32_e32 v3, v22, v2
	s_waitcnt lgkmcnt(0)
	s_nop 1
	v_mov_b32_dpp v4, v3 quad_perm:[1,0,3,2] row_mask:0xf bank_mask:0xf
	s_and_saveexec_b64 s[12:13], vcc
	s_cbranch_execz .LBB0_1595
	s_waitcnt lgkmcnt(0)
	v_cvt_pk_bf16_f32 v3, v3, v4
	global_store_dword v[0:1], v3, off offset:64
.LBB0_1595:
	s_or_b64 exec, exec, s[12:13]
	v_mul_f32_e32 v3, v38, v2
	s_waitcnt lgkmcnt(0)
	s_nop 1
	v_mov_b32_dpp v4, v3 quad_perm:[1,0,3,2] row_mask:0xf bank_mask:0xf
	s_and_saveexec_b64 s[12:13], vcc
	s_cbranch_execz .LBB0_1597
	s_waitcnt lgkmcnt(0)
	v_cvt_pk_bf16_f32 v3, v3, v4
	global_store_dword v[0:1], v3, off offset:128
.LBB0_1597:
	s_or_b64 exec, exec, s[12:13]
	v_mul_f32_e32 v2, v54, v2
	s_nop 1
	v_mov_b32_dpp v3, v2 quad_perm:[1,0,3,2] row_mask:0xf bank_mask:0xf
	s_and_saveexec_b64 s[12:13], vcc
	s_cbranch_execz .LBB0_1599
	s_waitcnt lgkmcnt(0)
	v_cvt_pk_bf16_f32 v2, v2, v3
	global_store_dword v[0:1], v2, off offset:192
.LBB0_1599:
	s_or_b64 exec, exec, s[12:13]
	v_rcp_f32_e32 v2, v75
	s_waitcnt lgkmcnt(0)
	v_mul_f32_e32 v3, v7, v2
	s_nop 1
	v_mov_b32_dpp v4, v3 quad_perm:[1,0,3,2] row_mask:0xf bank_mask:0xf
	v_add_u32_e32 v0, 0x2c00, v144
	v_mov_b32_e32 v1, v145
	v_lshl_add_u64 v[0:1], s[0:1], 0, v[0:1]
	s_and_saveexec_b64 s[12:13], vcc
	s_cbranch_execz .LBB0_1601
	s_waitcnt lgkmcnt(0)
	v_cvt_pk_bf16_f32 v3, v3, v4
	global_store_dword v[0:1], v3, off
.LBB0_1601:
	s_or_b64 exec, exec, s[12:13]
	v_mul_f32_e32 v3, v23, v2
	s_waitcnt lgkmcnt(0)
	s_nop 1
	v_mov_b32_dpp v4, v3 quad_perm:[1,0,3,2] row_mask:0xf bank_mask:0xf
	s_and_saveexec_b64 s[12:13], vcc
	s_cbranch_execz .LBB0_1603
	s_waitcnt lgkmcnt(0)
	v_cvt_pk_bf16_f32 v3, v3, v4
	global_store_dword v[0:1], v3, off offset:64
.LBB0_1603:
	s_or_b64 exec, exec, s[12:13]
	v_mul_f32_e32 v3, v39, v2
	s_waitcnt lgkmcnt(0)
	s_nop 1
	v_mov_b32_dpp v4, v3 quad_perm:[1,0,3,2] row_mask:0xf bank_mask:0xf
	s_and_saveexec_b64 s[12:13], vcc
	s_cbranch_execz .LBB0_1605
	s_waitcnt lgkmcnt(0)
	v_cvt_pk_bf16_f32 v3, v3, v4
	global_store_dword v[0:1], v3, off offset:128
; template <int K> __device__ __forceinline__ float shx(float v) { static_assert(K < 32, "use sum32"); return __int_as_float(__builtin_amdgcn_ds_swizzle(__float_as_int(v), (K << 10) | 0x1f)); }
; __device__ __forceinline__ int crow(int r, int hi) { return (r & 3) + 8 * (r >> 2) + 4 * hi; }
; template <class TIn, class TOut, int ost, bool HAS_SS>
; __device__ __forceinline__ void causal_swa_block(const BlockRef<TIn, TOut>& cur_, const BlockRef<TIn, TOut>& nxt_, int skv, int W, char* lds, Seam<TIn>& S, int cbl  ) {
;     ...
;     if (hi == 0) li_l[r32] = l_reg; asm volatile("s_waitcnt lgkmcnt(0)" ::: "memory");
;     float rli[16];
; #pragma unroll
;     for (int r = 0; r < 16; ++r) rli[r] = __builtin_amdgcn_rcpf(li_l[crow(r, hi)]);
;     int r32e = r32, hie = hi; asm volatile("" : "+v"(r32e), "+v"(hie));
;     char* Ob = (char*)cur.O; const unsigned ob0 = (unsigned)((wid * QBLK + 4 * hie) * ost + r32e) * 2u;
; #pragma unroll
;     for (int r = 0; r < 16; ++r) { const unsigned rowoff = ob0 + (unsigned)(((r & 3) + 8 * (r >> 2)) * ost * 2); float ss_ = 0.f;
; #pragma unroll
;         for (int d0 = 0; d0 < 4; ++d0) { const float v = o[d0][r] * rli[r]; ss_ += v * v;
;             const float vn = shx<1>(v);
;             if ((r32e & 1) == 0) *(unsigned*)(Ob + rowoff + d0 * 64) = cvtpk(v, vn); }
.LBB0_1605:
	s_or_b64 exec, exec, s[12:13]
	v_mul_f32_e32 v2, v55, v2
	s_nop 1
	v_mov_b32_dpp v3, v2 quad_perm:[1,0,3,2] row_mask:0xf bank_mask:0xf
	s_and_saveexec_b64 s[12:13], vcc
	s_cbranch_execz .LBB0_1607
	s_waitcnt lgkmcnt(0)
	v_cvt_pk_bf16_f32 v2, v2, v3
	global_store_dword v[0:1], v2, off offset:192
.LBB0_1607:
	s_or_b64 exec, exec, s[12:13]
	v_rcp_f32_e32 v2, v68
	s_waitcnt lgkmcnt(0)
	v_mul_f32_e32 v3, v8, v2
	s_nop 1
	v_mov_b32_dpp v4, v3 quad_perm:[1,0,3,2] row_mask:0xf bank_mask:0xf
	v_add_u32_e32 v0, 0x4000, v144
	v_mov_b32_e32 v1, v145
	v_lshl_add_u64 v[0:1], s[0:1], 0, v[0:1]
	s_and_saveexec_b64 s[12:13], vcc
	s_cbranch_execz .LBB0_1609
	s_waitcnt lgkmcnt(0)
	v_cvt_pk_bf16_f32 v3, v3, v4
	global_store_dword v[0:1], v3, off
.LBB0_1609:
	s_or_b64 exec, exec, s[12:13]
	v_mul_f32_e32 v3, v24, v2
	s_waitcnt lgkmcnt(0)
	s_nop 1
	v_mov_b32_dpp v4, v3 quad_perm:[1,0,3,2] row_mask:0xf bank_mask:0xf
	s_and_saveexec_b64 s[12:13], vcc
	s_cbranch_execz .LBB0_1611
	s_waitcnt lgkmcnt(0)
	v_cvt_pk_bf16_f32 v3, v3, v4
	global_store_dword v[0:1], v3, off offset:64
.LBB0_1611:
	s_or_b64 exec, exec, s[12:13]
	v_mul_f32_e32 v3, v40, v2
	s_waitcnt lgkmcnt(0)
	s_nop 1
	v_mov_b32_dpp v4, v3 quad_perm:[1,0,3,2] row_mask:0xf bank_mask:0xf
	s_and_saveexec_b64 s[12:13], vcc
	s_cbranch_execz .LBB0_1613
	s_waitcnt lgkmcnt(0)
	v_cvt_pk_bf16_f32 v3, v3, v4
	global_store_dword v[0:1], v3, off offset:128
.LBB0_1613:
	s_or_b64 exec, exec, s[12:13]
	v_mul_f32_e32 v2, v56, v2
	s_nop 1
	v_mov_b32_dpp v3, v2 quad_perm:[1,0,3,2] row_mask:0xf bank_mask:0xf
	s_and_saveexec_b64 s[12:13], vcc
	s_cbranch_execz .LBB0_1615
	s_waitcnt lgkmcnt(0)
	v_cvt_pk_bf16_f32 v2, v2, v3
	global_store_dword v[0:1], v2, off offset:192
.LBB0_1615:
	s_or_b64 exec, exec, s[12:13]
	v_rcp_f32_e32 v2, v69
	s_waitcnt lgkmcnt(0)
	v_mul_f32_e32 v3, v9, v2
	s_nop 1
	v_mov_b32_dpp v4, v3 quad_perm:[1,0,3,2] row_mask:0xf bank_mask:0xf
	v_add_u32_e32 v0, 0x4400, v144
	v_mov_b32_e32 v1, v145
	v_lshl_add_u64 v[0:1], s[0:1], 0, v[0:1]
	s_and_saveexec_b64 s[12:13], vcc
	s_cbranch_execz .LBB0_1617
	s_waitcnt lgkmcnt(0)
	v_cvt_pk_bf16_f32 v3, v3, v4
	global_store_dword v[0:1], v3, off
.LBB0_1617:
	s_or_b64 exec, exec, s[12:13]
	v_mul_f32_e32 v3, v25, v2
	s_waitcnt lgkmcnt(0)
	s_nop 1
	v_mov_b32_dpp v4, v3 quad_perm:[1,0,3,2] row_mask:0xf bank_mask:0xf
	s_and_saveexec_b64 s[12:13], vcc
	s_cbranch_execz .LBB0_1619
	s_waitcnt lgkmcnt(0)
	v_cvt_pk_bf16_f32 v3, v3, v4
	global_store_dword v[0:1], v3, off offset:64
.LBB0_1619:
	s_or_b64 exec, exec, s[12:13]
	v_mul_f32_e32 v3, v41, v2
	s_waitcnt lgkmcnt(0)
	s_nop 1
	v_mov_b32_dpp v4, v3 quad_perm:[1,0,3,2] row_mask:0xf bank_mask:0xf
	s_and_saveexec_b64 s[12:13], vcc
	s_cbranch_execz .LBB0_1621
	s_waitcnt lgkmcnt(0)
	v_cvt_pk_bf16_f32 v3, v3, v4
	global_store_dword v[0:1], v3, off offset:128
.LBB0_1621:
	s_or_b64 exec, exec, s[12:13]
	v_mul_f32_e32 v2, v57, v2
	s_nop 1
	v_mov_b32_dpp v3, v2 quad_perm:[1,0,3,2] row_mask:0xf bank_mask:0xf
	s_and_saveexec_b64 s[12:13], vcc
	s_cbranch_execz .LBB0_1623
	s_waitcnt lgkmcnt(0)
	v_cvt_pk_bf16_f32 v2, v2, v3
	global_store_dword v[0:1], v2, off offset:192
.LBB0_1623:
	s_or_b64 exec, exec, s[12:13]
	v_rcp_f32_e32 v2, v70
	s_waitcnt lgkmcnt(0)
	v_mul_f32_e32 v3, v10, v2
	s_nop 1
	v_mov_b32_dpp v4, v3 quad_perm:[1,0,3,2] row_mask:0xf bank_mask:0xf
	v_add_u32_e32 v0, 0x4800, v144
	v_mov_b32_e32 v1, v145
	v_lshl_add_u64 v[0:1], s[0:1], 0, v[0:1]
	s_and_saveexec_b64 s[12:13], vcc
	s_cbranch_execz .LBB0_1625
	s_waitcnt lgkmcnt(0)
	v_cvt_pk_bf16_f32 v3, v3, v4
	global_store_dword v[0:1], v3, off
.LBB0_1625:
	s_or_b64 exec, exec, s[12:13]
	v_mul_f32_e32 v3, v26, v2
	s_waitcnt lgkmcnt(0)
	s_nop 1
	v_mov_b32_dpp v4, v3 quad_perm:[1,0,3,2] row_mask:0xf bank_mask:0xf
	s_and_saveexec_b64 s[12:13], vcc
	s_cbranch_execz .LBB0_1627
	s_waitcnt lgkmcnt(0)
	v_cvt_pk_bf16_f32 v3, v3, v4
	global_store_dword v[0:1], v3, off offset:64
.LBB0_1627:
	s_or_b64 exec, exec, s[12:13]
	v_mul_f32_e32 v3, v42, v2
	s_waitcnt lgkmcnt(0)
	s_nop 1
	v_mov_b32_dpp v4, v3 quad_perm:[1,0,3,2] row_mask:0xf bank_mask:0xf
	s_and_saveexec_b64 s[12:13], vcc
	s_cbranch_execz .LBB0_1629
	s_waitcnt lgkmcnt(0)
	v_cvt_pk_bf16_f32 v3, v3, v4
	global_store_dword v[0:1], v3, off offset:128
.LBB0_1629:
	s_or_b64 exec, exec, s[12:13]
	v_mul_f32_e32 v2, v58, v2
	s_nop 1
	v_mov_b32_dpp v3, v2 quad_perm:[1,0,3,2] row_mask:0xf bank_mask:0xf
	s_and_saveexec_b64 s[12:13], vcc
	s_cbranch_execz .LBB0_1631
	s_waitcnt lgkmcnt(0)
	v_cvt_pk_bf16_f32 v2, v2, v3
	global_store_dword v[0:1], v2, off offset:192
.LBB0_1631:
	s_or_b64 exec, exec, s[12:13]
	v_rcp_f32_e32 v2, v71
	s_waitcnt lgkmcnt(0)
	v_mul_f32_e32 v3, v11, v2
	s_nop 1
	v_mov_b32_dpp v4, v3 quad_perm:[1,0,3,2] row_mask:0xf bank_mask:0xf
	v_add_u32_e32 v0, 0x4c00, v144
	v_mov_b32_e32 v1, v145
	v_lshl_add_u64 v[0:1], s[0:1], 0, v[0:1]
	s_and_saveexec_b64 s[12:13], vcc
	s_cbranch_execz .LBB0_1633
	s_waitcnt lgkmcnt(0)
	v_cvt_pk_bf16_f32 v3, v3, v4
	global_store_dword v[0:1], v3, off
.LBB0_1633:
	s_or_b64 exec, exec, s[12:13]
	v_mul_f32_e32 v3, v27, v2
	s_waitcnt lgkmcnt(0)
	s_nop 1
	v_mov_b32_dpp v4, v3 quad_perm:[1,0,3,2] row_mask:0xf bank_mask:0xf
	s_and_saveexec_b64 s[12:13], vcc
	s_cbranch_execz .LBB0_1635
	s_waitcnt lgkmcnt(0)
	v_cvt_pk_bf16_f32 v3, v3, v4
	global_store_dword v[0:1], v3, off offset:64
.LBB0_1635:
	s_or_b64 exec, exec, s[12:13]
	v_mul_f32_e32 v3, v43, v2
	s_waitcnt lgkmcnt(0)
	s_nop 1
	v_mov_b32_dpp v4, v3 quad_perm:[1,0,3,2] row_mask:0xf bank_mask:0xf
	s_and_saveexec_b64 s[12:13], vcc
	s_cbranch_execz .LBB0_1637
	s_waitcnt lgkmcnt(0)
	v_cvt_pk_bf16_f32 v3, v3, v4
	global_store_dword v[0:1], v3, off offset:128
; template <int K> __device__ __forceinline__ float shx(float v) { static_assert(K < 32, "use sum32"); return __int_as_float(__builtin_amdgcn_ds_swizzle(__float_as_int(v), (K << 10) | 0x1f)); }
; __device__ __forceinline__ int crow(int r, int hi) { return (r & 3) + 8 * (r >> 2) + 4 * hi; }
; template <class TIn, class TOut, int ost, bool HAS_SS>
; __device__ __forceinline__ void causal_swa_block(const BlockRef<TIn, TOut>& cur_, const BlockRef<TIn, TOut>& nxt_, int skv, int W, char* lds, Seam<TIn>& S, int cbl  ) {
;     ...
;     if (hi == 0) li_l[r32] = l_reg; asm volatile("s_waitcnt lgkmcnt(0)" ::: "memory");
;     float rli[16];
; #pragma unroll
;     for (int r = 0; r < 16; ++r) rli[r] = __builtin_amdgcn_rcpf(li_l[crow(r, hi)]);
;     int r32e = r32, hie = hi; asm volatile("" : "+v"(r32e), "+v"(hie));
;     char* Ob = (char*)cur.O; const unsigned ob0 = (unsigned)((wid * QBLK + 4 * hie) * ost + r32e) * 2u;
; #pragma unroll
;     for (int r = 0; r < 16; ++r) { const unsigned rowoff = ob0 + (unsigned)(((r & 3) + 8 * (r >> 2)) * ost * 2); float ss_ = 0.f;
; #pragma unroll
;         for (int d0 = 0; d0 < 4; ++d0) { const float v = o[d0][r] * rli[r]; ss_ += v * v;
;             const float vn = shx<1>(v);
;             if ((r32e & 1) == 0) *(unsigned*)(Ob + rowoff + d0 * 64) = cvtpk(v, vn); }
.LBB0_1637:
	s_or_b64 exec, exec, s[12:13]
	v_mul_f32_e32 v2, v59, v2
	s_nop 1
	v_mov_b32_dpp v3, v2 quad_perm:[1,0,3,2] row_mask:0xf bank_mask:0xf
	s_and_saveexec_b64 s[12:13], vcc
	s_cbranch_execz .LBB0_1639
	s_waitcnt lgkmcnt(0)
	v_cvt_pk_bf16_f32 v2, v2, v3
	global_store_dword v[0:1], v2, off offset:192
.LBB0_1639:
	s_or_b64 exec, exec, s[12:13]
	v_rcp_f32_e32 v2, v64
	s_waitcnt lgkmcnt(0)
	v_mul_f32_e32 v3, v12, v2
	s_nop 1
	v_mov_b32_dpp v4, v3 quad_perm:[1,0,3,2] row_mask:0xf bank_mask:0xf
	v_add_u32_e32 v0, 0x6000, v144
	v_mov_b32_e32 v1, v145
	v_lshl_add_u64 v[0:1], s[0:1], 0, v[0:1]
	s_and_saveexec_b64 s[12:13], vcc
	s_cbranch_execz .LBB0_1641
	s_waitcnt lgkmcnt(0)
	v_cvt_pk_bf16_f32 v3, v3, v4
	global_store_dword v[0:1], v3, off
.LBB0_1641:
	s_or_b64 exec, exec, s[12:13]
	v_mul_f32_e32 v3, v28, v2
	s_waitcnt lgkmcnt(0)
	s_nop 1
	v_mov_b32_dpp v4, v3 quad_perm:[1,0,3,2] row_mask:0xf bank_mask:0xf
	s_and_saveexec_b64 s[12:13], vcc
	s_cbranch_execz .LBB0_1643
	s_waitcnt lgkmcnt(0)
	v_cvt_pk_bf16_f32 v3, v3, v4
	global_store_dword v[0:1], v3, off offset:64
.LBB0_1643:
	s_or_b64 exec, exec, s[12:13]
	v_mul_f32_e32 v3, v44, v2
	s_waitcnt lgkmcnt(0)
	s_nop 1
	v_mov_b32_dpp v4, v3 quad_perm:[1,0,3,2] row_mask:0xf bank_mask:0xf
	s_and_saveexec_b64 s[12:13], vcc
	s_cbranch_execz .LBB0_1645
	s_waitcnt lgkmcnt(0)
	v_cvt_pk_bf16_f32 v3, v3, v4
	global_store_dword v[0:1], v3, off offset:128
.LBB0_1645:
	s_or_b64 exec, exec, s[12:13]
	v_mul_f32_e32 v2, v60, v2
	s_nop 1
	v_mov_b32_dpp v3, v2 quad_perm:[1,0,3,2] row_mask:0xf bank_mask:0xf
	s_and_saveexec_b64 s[12:13], vcc
	s_cbranch_execz .LBB0_1647
	s_waitcnt lgkmcnt(0)
	v_cvt_pk_bf16_f32 v2, v2, v3
	global_store_dword v[0:1], v2, off offset:192
.LBB0_1647:
	s_or_b64 exec, exec, s[12:13]
	v_rcp_f32_e32 v2, v65
	s_waitcnt lgkmcnt(0)
	v_mul_f32_e32 v3, v13, v2
	s_nop 1
	v_mov_b32_dpp v4, v3 quad_perm:[1,0,3,2] row_mask:0xf bank_mask:0xf
	v_add_u32_e32 v0, 0x6400, v144
	v_mov_b32_e32 v1, v145
	v_lshl_add_u64 v[0:1], s[0:1], 0, v[0:1]
	s_and_saveexec_b64 s[12:13], vcc
	s_cbranch_execz .LBB0_1649
	s_waitcnt lgkmcnt(0)
	v_cvt_pk_bf16_f32 v3, v3, v4
	global_store_dword v[0:1], v3, off
.LBB0_1649:
	s_or_b64 exec, exec, s[12:13]
	v_mul_f32_e32 v3, v29, v2
	s_waitcnt lgkmcnt(0)
	s_nop 1
	v_mov_b32_dpp v4, v3 quad_perm:[1,0,3,2] row_mask:0xf bank_mask:0xf
	s_and_saveexec_b64 s[12:13], vcc
	s_cbranch_execz .LBB0_1651
	s_waitcnt lgkmcnt(0)
	v_cvt_pk_bf16_f32 v3, v3, v4
	global_store_dword v[0:1], v3, off offset:64
.LBB0_1651:
	s_or_b64 exec, exec, s[12:13]
	v_mul_f32_e32 v3, v45, v2
	s_waitcnt lgkmcnt(0)
	s_nop 1
	v_mov_b32_dpp v4, v3 quad_perm:[1,0,3,2] row_mask:0xf bank_mask:0xf
	s_and_saveexec_b64 s[12:13], vcc
	s_cbranch_execz .LBB0_1653
	s_waitcnt lgkmcnt(0)
	v_cvt_pk_bf16_f32 v3, v3, v4
	global_store_dword v[0:1], v3, off offset:128
.LBB0_1653:
	s_or_b64 exec, exec, s[12:13]
	v_mul_f32_e32 v2, v61, v2
	s_nop 1
	v_mov_b32_dpp v3, v2 quad_perm:[1,0,3,2] row_mask:0xf bank_mask:0xf
	s_and_saveexec_b64 s[12:13], vcc
	s_cbranch_execz .LBB0_1655
	s_waitcnt lgkmcnt(0)
	v_cvt_pk_bf16_f32 v2, v2, v3
	global_store_dword v[0:1], v2, off offset:192
.LBB0_1655:
	s_or_b64 exec, exec, s[12:13]
	v_rcp_f32_e32 v2, v66
	s_waitcnt lgkmcnt(0)
	v_mul_f32_e32 v3, v14, v2
	s_nop 1
	v_mov_b32_dpp v4, v3 quad_perm:[1,0,3,2] row_mask:0xf bank_mask:0xf
	v_add_u32_e32 v0, 0x6800, v144
	v_mov_b32_e32 v1, v145
	v_lshl_add_u64 v[0:1], s[0:1], 0, v[0:1]
	s_and_saveexec_b64 s[12:13], vcc
	s_cbranch_execz .LBB0_1657
	s_waitcnt lgkmcnt(0)
	v_cvt_pk_bf16_f32 v3, v3, v4
	global_store_dword v[0:1], v3, off
.LBB0_1657:
	s_or_b64 exec, exec, s[12:13]
	v_mul_f32_e32 v3, v30, v2
	s_waitcnt lgkmcnt(0)
	s_nop 1
	v_mov_b32_dpp v4, v3 quad_perm:[1,0,3,2] row_mask:0xf bank_mask:0xf
	s_and_saveexec_b64 s[12:13], vcc
	s_cbranch_execz .LBB0_1659
	s_waitcnt lgkmcnt(0)
	v_cvt_pk_bf16_f32 v3, v3, v4
	global_store_dword v[0:1], v3, off offset:64
.LBB0_1659:
	s_or_b64 exec, exec, s[12:13]
	v_mul_f32_e32 v3, v46, v2
	s_waitcnt lgkmcnt(0)
	s_nop 1
	v_mov_b32_dpp v4, v3 quad_perm:[1,0,3,2] row_mask:0xf bank_mask:0xf
	s_and_saveexec_b64 s[12:13], vcc
	s_cbranch_execz .LBB0_1661
	s_waitcnt lgkmcnt(0)
	v_cvt_pk_bf16_f32 v3, v3, v4
	global_store_dword v[0:1], v3, off offset:128
.LBB0_1661:
	s_or_b64 exec, exec, s[12:13]
	v_mul_f32_e32 v2, v62, v2
	s_nop 1
	v_mov_b32_dpp v3, v2 quad_perm:[1,0,3,2] row_mask:0xf bank_mask:0xf
	s_and_saveexec_b64 s[12:13], vcc
	s_cbranch_execz .LBB0_1663
	s_waitcnt lgkmcnt(0)
	v_cvt_pk_bf16_f32 v2, v2, v3
	global_store_dword v[0:1], v2, off offset:192
.LBB0_1663:
	s_or_b64 exec, exec, s[12:13]
	v_rcp_f32_e32 v2, v67
	s_waitcnt lgkmcnt(0)
	v_mul_f32_e32 v3, v15, v2
	s_nop 1
	v_mov_b32_dpp v4, v3 quad_perm:[1,0,3,2] row_mask:0xf bank_mask:0xf
	v_add_u32_e32 v144, 0x6c00, v144
	v_lshl_add_u64 v[0:1], s[0:1], 0, v[144:145]
	s_and_saveexec_b64 s[0:1], vcc
	s_cbranch_execz .LBB0_1665
	s_waitcnt lgkmcnt(0)
	v_cvt_pk_bf16_f32 v3, v3, v4
	global_store_dword v[0:1], v3, off
.LBB0_1665:
	s_or_b64 exec, exec, s[0:1]
	v_mul_f32_e32 v3, v31, v2
	s_waitcnt lgkmcnt(0)
	s_nop 1
	v_mov_b32_dpp v4, v3 quad_perm:[1,0,3,2] row_mask:0xf bank_mask:0xf
	s_and_saveexec_b64 s[0:1], vcc
	s_cbranch_execz .LBB0_1667
	s_waitcnt lgkmcnt(0)
	v_cvt_pk_bf16_f32 v3, v3, v4
	global_store_dword v[0:1], v3, off offset:64
.LBB0_1667:
	s_or_b64 exec, exec, s[0:1]
	v_mul_f32_e32 v3, v47, v2
	s_waitcnt lgkmcnt(0)
	s_nop 1
	v_mov_b32_dpp v4, v3 quad_perm:[1,0,3,2] row_mask:0xf bank_mask:0xf
	s_and_saveexec_b64 s[0:1], vcc
	s_cbranch_execz .LBB0_1669
	s_waitcnt lgkmcnt(0)
	v_cvt_pk_bf16_f32 v3, v3, v4
	global_store_dword v[0:1], v3, off offset:128
.LBB0_1669:
	s_or_b64 exec, exec, s[0:1]
	v_mul_f32_e32 v2, v63, v2
	s_nop 1
	v_mov_b32_dpp v3, v2 quad_perm:[1,0,3,2] row_mask:0xf bank_mask:0xf
	s_and_saveexec_b64 s[0:1], vcc
	s_cbranch_execz .LBB0_1520
	s_waitcnt lgkmcnt(0)
	v_cvt_pk_bf16_f32 v2, v2, v3
	global_store_dword v[0:1], v2, off offset:192
	s_branch .LBB0_1520
